# v3 + first 4 MFMAs of each compute segment issued before the segment barrier
# baseline (speedup 1.0000x reference)
; #define PG8_STAGE(bufoff, gbase, voff) do { _Pragma("unroll") for (int _i = 0; _i < 2; ++_i) \
;         __builtin_amdgcn_global_load_lds((const unsigned*)((const char*)(gbase) + (voff)[_i]), (PG8_LAS unsigned*)(lds + (bufoff) + ldsw + _i * 8192), 16, 0, 0); } while (0)
; #define PG8_LDA(dst, b, h) do { _Pragma("unroll") for (int m = 0; m < 4; ++m) _Pragma("unroll") for (int k = 0; k < 2; ++k) dst[m][k] = *(const PG8_LAS bf16x8*)(lds + PG8_SA(b, h) + aoff + m * 2048 + k * 1024); } while (0)
; #define PG8_LDB(dst, b, h) do { _Pragma("unroll") for (int n = 0; n < 2; ++n) _Pragma("unroll") for (int k = 0; k < 2; ++k) dst[n][k] = *(const PG8_LAS bf16x8*)(lds + PG8_SB(b, h) + boff + n * 2048 + k * 1024); } while (0)
; #define PG8_MMA(ai, bj, At, Bt) do { __builtin_amdgcn_s_setprio(1); _Pragma("unroll") for (int m = 0; m < 4; ++m) _Pragma("unroll") for (int n = 0; n < 2; ++n) _Pragma("unroll") for (int k = 0; k < 2; ++k) \
;         acc[ai][bj][m][n] = __builtin_amdgcn_mfma_f32_16x16x32_f16(Bt[n][k], At[m][k], acc[ai][bj][m][n], 0, 0, 0); __builtin_amdgcn_s_setprio(0); } while (0)
; #define PG8_WAIT_V(n) asm volatile("s_waitcnt vmcnt(" #n ")" ::: "memory")
; #define PG8_WAIT_L(n) asm volatile("s_waitcnt lgkmcnt(" #n ")" ::: "memory")
; #define PG8_BAR __builtin_amdgcn_s_barrier()
; #define PG8_SCHED __builtin_amdgcn_sched_barrier(0)
; template <class Epi, class Sched, bool ALIGN_EPI = false, bool SP2 = false>
; __device__ __forceinline__ void gemm_phase(PG8_LAS unsigned char* lds, const Gemm g, const Sched& S, const Epi& E) {
;     ...
;             PG8_LDB(B0, 0, 0); PG8_LDB(B1, 0, 1); PG8_SCHED; PG8_LDA(At, 0, 0); PG8_STAGE(PG8_SA(1, 1), a1 + hstep, voffA);
;             PG8_WAIT_V(8); PG8_WAIT_L(0); PG8_BAR; PG8_MMA(0, 0, At, B0); PG8_MMA(0, 1, At, B1); PG8_BAR; PG8_SCHED;
;             PG8_LDA(At, 0, 1); PG8_STAGE(PG8_SB(0, 0), b2, voffB); PG8_STAGE(PG8_SB(0, 1), b2 + hstep, voffB); PG8_STAGE(PG8_SA(0, 0), a2, voffA);
;             PG8_WAIT_V(8); PG8_WAIT_L(0); PG8_BAR; PG8_MMA(1, 0, At, B0); PG8_MMA(1, 1, At, B1); PG8_BAR; PG8_SCHED;
.LBB0_146:
	ds_read_b128 v[150:153], v147
	ds_read_b128 v[154:157], v147 offset:1024
	ds_read_b128 v[158:161], v147 offset:2048
	ds_read_b128 v[162:165], v147 offset:3072
	ds_read_b128 v[166:169], v148
	ds_read_b128 v[170:173], v148 offset:1024
	ds_read_b128 v[174:177], v148 offset:2048
	ds_read_b128 v[178:181], v148 offset:3072
	s_add_u32 s24, s22, 0xfff80080
	s_addc_u32 s25, s23, -1
	s_cmp_eq_u32 s62, 28
	s_cselect_b32 s27, s17, s25
	s_cselect_b32 s26, s54, s24
	s_cselect_b32 s25, s15, s61
	s_cselect_b32 s24, s55, s60
	s_add_i32 m0, s13, 0xc000
	ds_read_b128 v[182:185], v149
	ds_read_b128 v[186:189], v149 offset:1024
	ds_read_b128 v[190:193], v149 offset:2048
	ds_read_b128 v[194:197], v149 offset:3072
	ds_read_b128 v[198:201], v149 offset:4096
	ds_read_b128 v[206:209], v149 offset:5120
	ds_read_b128 v[210:213], v149 offset:6144
	ds_read_b128 v[214:217], v149 offset:7168
	global_load_lds_dwordx4 v138, s[22:23]
	s_add_i32 m0, s13, 0xe000
	s_nop 0
	global_load_lds_dwordx4 v136, s[22:23]
	s_waitcnt vmcnt(8)
	s_waitcnt lgkmcnt(0)
	v_mfma_f32_16x16x32_f16 v[120:123], v[158:161], v[182:185], v[120:123]
	v_mfma_f32_16x16x32_f16 v[124:127], v[150:153], v[182:185], v[124:127]
	v_mfma_f32_16x16x32_f16 v[112:115], v[158:161], v[190:193], v[112:115]
	v_mfma_f32_16x16x32_f16 v[116:119], v[150:153], v[190:193], v[116:119]
	s_barrier
	s_waitcnt lgkmcnt(0)
	v_mfma_f32_16x16x32_f16 v[96:99], v[158:161], v[198:201], v[96:99]
	v_mfma_f32_16x16x32_f16 v[100:103], v[150:153], v[198:201], v[100:103]
	v_mfma_f32_16x16x32_f16 v[80:83], v[158:161], v[210:213], v[80:83]
	v_mfma_f32_16x16x32_f16 v[84:87], v[150:153], v[210:213], v[84:87]
	v_mfma_f32_16x16x32_f16 v[120:123], v[162:165], v[186:189], v[120:123]
	v_mfma_f32_16x16x32_f16 v[124:127], v[154:157], v[186:189], v[124:127]
	v_mfma_f32_16x16x32_f16 v[112:115], v[162:165], v[194:197], v[112:115]
	v_mfma_f32_16x16x32_f16 v[116:119], v[154:157], v[194:197], v[116:119]
	v_mfma_f32_16x16x32_f16 v[96:99], v[162:165], v[206:209], v[96:99]
	v_mfma_f32_16x16x32_f16 v[100:103], v[154:157], v[206:209], v[100:103]
	v_mfma_f32_16x16x32_f16 v[80:83], v[162:165], v[214:217], v[80:83]
	v_mfma_f32_16x16x32_f16 v[84:87], v[154:157], v[214:217], v[84:87]
	v_mfma_f32_16x16x32_f16 v[104:107], v[174:177], v[182:185], v[104:107]
	v_mfma_f32_16x16x32_f16 v[108:111], v[166:169], v[182:185], v[108:111]
	v_mfma_f32_16x16x32_f16 v[88:91], v[174:177], v[190:193], v[88:91]
	v_mfma_f32_16x16x32_f16 v[92:95], v[166:169], v[190:193], v[92:95]
	v_mfma_f32_16x16x32_f16 v[72:75], v[174:177], v[198:201], v[72:75]
	v_mfma_f32_16x16x32_f16 v[76:79], v[166:169], v[198:201], v[76:79]
	v_mfma_f32_16x16x32_f16 v[64:67], v[174:177], v[210:213], v[64:67]
	v_mfma_f32_16x16x32_f16 v[68:71], v[166:169], v[210:213], v[68:71]
	v_mfma_f32_16x16x32_f16 v[104:107], v[178:181], v[186:189], v[104:107]
	v_mfma_f32_16x16x32_f16 v[108:111], v[170:173], v[186:189], v[108:111]
	v_mfma_f32_16x16x32_f16 v[88:91], v[178:181], v[194:197], v[88:91]
	v_mfma_f32_16x16x32_f16 v[92:95], v[170:173], v[194:197], v[92:95]
	v_mfma_f32_16x16x32_f16 v[72:75], v[178:181], v[206:209], v[72:75]
	v_mfma_f32_16x16x32_f16 v[76:79], v[170:173], v[206:209], v[76:79]
	v_mfma_f32_16x16x32_f16 v[64:67], v[178:181], v[214:217], v[64:67]
	v_mfma_f32_16x16x32_f16 v[68:71], v[170:173], v[214:217], v[68:71]
	s_barrier
	s_add_i32 s63, s44, s34
	s_add_u32 s98, s24, s8
	s_addc_u32 s99, s25, s9
	s_mov_b32 m0, s63
	ds_read_b128 v[182:185], v149 offset:16384
	ds_read_b128 v[186:189], v149 offset:17408
	ds_read_b128 v[190:193], v149 offset:18432
	ds_read_b128 v[194:197], v149 offset:19456
	ds_read_b128 v[198:201], v149 offset:20480
	ds_read_b128 v[206:209], v149 offset:21504
	ds_read_b128 v[210:213], v149 offset:22528
	ds_read_b128 v[214:217], v149 offset:23552
	global_load_lds_dwordx4 v132, s[24:25]
	s_add_i32 m0, s63, 0x2000
	s_add_u32 s66, s24, 0x80000
	s_addc_u32 s67, s25, 0
	s_add_i32 s63, s45, s34
	global_load_lds_dwordx4 v128, s[24:25]
	s_mov_b32 m0, s63
	s_nop 0
	global_load_lds_dwordx4 v132, s[66:67]
	s_add_i32 m0, s63, 0x2000
	s_nop 0
	global_load_lds_dwordx4 v128, s[66:67]
	s_add_u32 s100, s26, s8
	s_addc_u32 s101, s27, s9
	s_mov_b32 m0, s13
	s_nop 0
	global_load_lds_dwordx4 v134, s[26:27]
	s_mov_b32 m0, s37
	s_nop 0
	global_load_lds_dwordx4 v130, s[26:27]
	s_waitcnt vmcnt(8)
	s_waitcnt lgkmcnt(0)
	v_mfma_f32_16x16x32_f16 v[56:59], v[158:161], v[182:185], v[56:59]
	v_mfma_f32_16x16x32_f16 v[60:63], v[150:153], v[182:185], v[60:63]
	v_mfma_f32_16x16x32_f16 v[48:51], v[158:161], v[190:193], v[48:51]
	v_mfma_f32_16x16x32_f16 v[52:55], v[150:153], v[190:193], v[52:55]
	s_barrier
	s_waitcnt lgkmcnt(0)
	v_mfma_f32_16x16x32_f16 v[32:35], v[158:161], v[198:201], v[32:35]
	v_mfma_f32_16x16x32_f16 v[36:39], v[150:153], v[198:201], v[36:39]
	v_mfma_f32_16x16x32_f16 v[16:19], v[158:161], v[210:213], v[16:19]
	v_mfma_f32_16x16x32_f16 v[20:23], v[150:153], v[210:213], v[20:23]
	v_mfma_f32_16x16x32_f16 v[56:59], v[162:165], v[186:189], v[56:59]
	v_mfma_f32_16x16x32_f16 v[60:63], v[154:157], v[186:189], v[60:63]
	v_mfma_f32_16x16x32_f16 v[48:51], v[162:165], v[194:197], v[48:51]
	v_mfma_f32_16x16x32_f16 v[52:55], v[154:157], v[194:197], v[52:55]
	v_mfma_f32_16x16x32_f16 v[32:35], v[162:165], v[206:209], v[32:35]
	v_mfma_f32_16x16x32_f16 v[36:39], v[154:157], v[206:209], v[36:39]
	v_mfma_f32_16x16x32_f16 v[16:19], v[162:165], v[214:217], v[16:19]
	v_mfma_f32_16x16x32_f16 v[20:23], v[154:157], v[214:217], v[20:23]
	v_mfma_f32_16x16x32_f16 v[40:43], v[174:177], v[182:185], v[40:43]
	v_mfma_f32_16x16x32_f16 v[44:47], v[166:169], v[182:185], v[44:47]
	v_mfma_f32_16x16x32_f16 v[24:27], v[174:177], v[190:193], v[24:27]
	v_mfma_f32_16x16x32_f16 v[28:31], v[166:169], v[190:193], v[28:31]
	v_mfma_f32_16x16x32_f16 v[8:11], v[174:177], v[198:201], v[8:11]
	v_mfma_f32_16x16x32_f16 v[12:15], v[166:169], v[198:201], v[12:15]
	v_mfma_f32_16x16x32_f16 v[0:3], v[174:177], v[210:213], v[0:3]
	v_mfma_f32_16x16x32_f16 v[4:7], v[166:169], v[210:213], v[4:7]
	v_mfma_f32_16x16x32_f16 v[40:43], v[178:181], v[186:189], v[40:43]
	v_mfma_f32_16x16x32_f16 v[44:47], v[170:173], v[186:189], v[44:47]
	v_mfma_f32_16x16x32_f16 v[24:27], v[178:181], v[194:197], v[24:27]
	v_mfma_f32_16x16x32_f16 v[28:31], v[170:173], v[194:197], v[28:31]
	v_mfma_f32_16x16x32_f16 v[8:11], v[178:181], v[206:209], v[8:11]
	v_mfma_f32_16x16x32_f16 v[12:15], v[170:173], v[206:209], v[12:15]
	v_mfma_f32_16x16x32_f16 v[0:3], v[178:181], v[214:217], v[0:3]
	v_mfma_f32_16x16x32_f16 v[4:7], v[170:173], v[214:217], v[4:7]
	s_barrier
; #define PG8_STAGE(bufoff, gbase, voff) do { _Pragma("unroll") for (int _i = 0; _i < 2; ++_i) \
;         __builtin_amdgcn_global_load_lds((const unsigned*)((const char*)(gbase) + (voff)[_i]), (PG8_LAS unsigned*)(lds + (bufoff) + ldsw + _i * 8192), 16, 0, 0); } while (0)
; #define PG8_LDA(dst, b, h) do { _Pragma("unroll") for (int m = 0; m < 4; ++m) _Pragma("unroll") for (int k = 0; k < 2; ++k) dst[m][k] = *(const PG8_LAS bf16x8*)(lds + PG8_SA(b, h) + aoff + m * 2048 + k * 1024); } while (0)
; #define PG8_LDB(dst, b, h) do { _Pragma("unroll") for (int n = 0; n < 2; ++n) _Pragma("unroll") for (int k = 0; k < 2; ++k) dst[n][k] = *(const PG8_LAS bf16x8*)(lds + PG8_SB(b, h) + boff + n * 2048 + k * 1024); } while (0)
; #define PG8_MMA(ai, bj, At, Bt) do { __builtin_amdgcn_s_setprio(1); _Pragma("unroll") for (int m = 0; m < 4; ++m) _Pragma("unroll") for (int n = 0; n < 2; ++n) _Pragma("unroll") for (int k = 0; k < 2; ++k) \
;         acc[ai][bj][m][n] = __builtin_amdgcn_mfma_f32_16x16x32_f16(Bt[n][k], At[m][k], acc[ai][bj][m][n], 0, 0, 0); __builtin_amdgcn_s_setprio(0); } while (0)
; #define PG8_WAIT_V(n) asm volatile("s_waitcnt vmcnt(" #n ")" ::: "memory")
; #define PG8_WAIT_L(n) asm volatile("s_waitcnt lgkmcnt(" #n ")" ::: "memory")
; #define PG8_BAR __builtin_amdgcn_s_barrier()
; #define PG8_SCHED __builtin_amdgcn_sched_barrier(0)
; template <class Epi, class Sched, bool ALIGN_EPI = false, bool SP2 = false>
; __device__ __forceinline__ void gemm_phase(PG8_LAS unsigned char* lds, const Gemm g, const Sched& S, const Epi& E) {
;     ...
;             PG8_LDB(B0, 1, 0); PG8_LDB(B1, 1, 1); PG8_SCHED; PG8_LDA(At, 1, 0); PG8_STAGE(PG8_SA(0, 1), a2 + hstep, voffA);
;             PG8_WAIT_V(8); PG8_WAIT_L(0); PG8_BAR; PG8_MMA(0, 0, At, B0); PG8_MMA(0, 1, At, B1); PG8_BAR; PG8_SCHED;
;             PG8_LDA(At, 1, 1); PG8_STAGE(PG8_SB(1, 0), b3, voffB); PG8_STAGE(PG8_SB(1, 1), b3 + hstep, voffB); PG8_STAGE(PG8_SA(1, 0), a3, voffA);
;             PG8_WAIT_V(8); PG8_WAIT_L(0); PG8_BAR; PG8_MMA(1, 0, At, B0); PG8_MMA(1, 1, At, B1); PG8_BAR; PG8_SCHED;
	s_add_i32 s63, 0, 0x18000
	s_add_i32 s66, 0, 0x1c000
	v_add_u32_e32 v162, s63, v145
	v_add_u32_e32 v178, s66, v145
	ds_read_b128 v[150:153], v162
	ds_read_b128 v[154:157], v162 offset:1024
	ds_read_b128 v[158:161], v162 offset:2048
	ds_read_b128 v[162:165], v162 offset:3072
	ds_read_b128 v[166:169], v178
	ds_read_b128 v[170:173], v178 offset:1024
	ds_read_b128 v[174:177], v178 offset:2048
	ds_read_b128 v[178:181], v178 offset:3072
	s_add_u32 s26, s26, 0x80000
	s_addc_u32 s27, s27, 0
	s_mov_b32 m0, s38
	ds_read_b128 v[182:185], v149 offset:32768
	ds_read_b128 v[186:189], v149 offset:33792
	ds_read_b128 v[190:193], v149 offset:34816
	ds_read_b128 v[194:197], v149 offset:35840
	ds_read_b128 v[198:201], v149 offset:36864
	ds_read_b128 v[206:209], v149 offset:37888
	ds_read_b128 v[210:213], v149 offset:38912
	ds_read_b128 v[214:217], v149 offset:39936
	global_load_lds_dwordx4 v134, s[26:27]
	s_mov_b32 m0, s39
	s_nop 0
	global_load_lds_dwordx4 v130, s[26:27]
	s_waitcnt vmcnt(8)
	s_waitcnt lgkmcnt(0)
	v_mfma_f32_16x16x32_f16 v[120:123], v[158:161], v[182:185], v[120:123]
	v_mfma_f32_16x16x32_f16 v[124:127], v[150:153], v[182:185], v[124:127]
	v_mfma_f32_16x16x32_f16 v[112:115], v[158:161], v[190:193], v[112:115]
	v_mfma_f32_16x16x32_f16 v[116:119], v[150:153], v[190:193], v[116:119]
	s_barrier
	s_waitcnt lgkmcnt(0)
	v_mfma_f32_16x16x32_f16 v[96:99], v[158:161], v[198:201], v[96:99]
	v_mfma_f32_16x16x32_f16 v[100:103], v[150:153], v[198:201], v[100:103]
	v_mfma_f32_16x16x32_f16 v[80:83], v[158:161], v[210:213], v[80:83]
	v_mfma_f32_16x16x32_f16 v[84:87], v[150:153], v[210:213], v[84:87]
	v_mfma_f32_16x16x32_f16 v[120:123], v[162:165], v[186:189], v[120:123]
	v_mfma_f32_16x16x32_f16 v[124:127], v[154:157], v[186:189], v[124:127]
	v_mfma_f32_16x16x32_f16 v[112:115], v[162:165], v[194:197], v[112:115]
	v_mfma_f32_16x16x32_f16 v[116:119], v[154:157], v[194:197], v[116:119]
	v_mfma_f32_16x16x32_f16 v[96:99], v[162:165], v[206:209], v[96:99]
	v_mfma_f32_16x16x32_f16 v[100:103], v[154:157], v[206:209], v[100:103]
	v_mfma_f32_16x16x32_f16 v[80:83], v[162:165], v[214:217], v[80:83]
	v_mfma_f32_16x16x32_f16 v[84:87], v[154:157], v[214:217], v[84:87]
	v_mfma_f32_16x16x32_f16 v[104:107], v[174:177], v[182:185], v[104:107]
	v_mfma_f32_16x16x32_f16 v[108:111], v[166:169], v[182:185], v[108:111]
	v_mfma_f32_16x16x32_f16 v[88:91], v[174:177], v[190:193], v[88:91]
	v_mfma_f32_16x16x32_f16 v[92:95], v[166:169], v[190:193], v[92:95]
	v_mfma_f32_16x16x32_f16 v[72:75], v[174:177], v[198:201], v[72:75]
	v_mfma_f32_16x16x32_f16 v[76:79], v[166:169], v[198:201], v[76:79]
	v_mfma_f32_16x16x32_f16 v[64:67], v[174:177], v[210:213], v[64:67]
	v_mfma_f32_16x16x32_f16 v[68:71], v[166:169], v[210:213], v[68:71]
	v_mfma_f32_16x16x32_f16 v[104:107], v[178:181], v[186:189], v[104:107]
	v_mfma_f32_16x16x32_f16 v[108:111], v[170:173], v[186:189], v[108:111]
	v_mfma_f32_16x16x32_f16 v[88:91], v[178:181], v[194:197], v[88:91]
	v_mfma_f32_16x16x32_f16 v[92:95], v[170:173], v[194:197], v[92:95]
	v_mfma_f32_16x16x32_f16 v[72:75], v[178:181], v[206:209], v[72:75]
	v_mfma_f32_16x16x32_f16 v[76:79], v[170:173], v[206:209], v[76:79]
	v_mfma_f32_16x16x32_f16 v[64:67], v[178:181], v[214:217], v[64:67]
	v_mfma_f32_16x16x32_f16 v[68:71], v[170:173], v[214:217], v[68:71]
	s_barrier
	s_add_i32 s26, s63, s34
	s_mov_b32 m0, s26
	ds_read_b128 v[182:185], v149 offset:49152
	ds_read_b128 v[186:189], v149 offset:50176
	ds_read_b128 v[190:193], v149 offset:51200
	ds_read_b128 v[194:197], v149 offset:52224
	ds_read_b128 v[198:201], v149 offset:53248
	ds_read_b128 v[206:209], v149 offset:54272
	ds_read_b128 v[210:213], v149 offset:55296
	ds_read_b128 v[214:217], v149 offset:56320
	global_load_lds_dwordx4 v132, s[98:99]
	s_add_i32 m0, s26, 0x2000
	s_add_u32 s24, s24, 0x80080
	s_addc_u32 s25, s25, 0
	s_add_i32 s26, s66, s34
	global_load_lds_dwordx4 v128, s[98:99]
	s_mov_b32 m0, s26
	s_nop 0
	global_load_lds_dwordx4 v132, s[24:25]
	s_add_i32 m0, s26, 0x2000
	s_nop 0
	global_load_lds_dwordx4 v128, s[24:25]
	s_mov_b32 m0, s41
	s_nop 0
	global_load_lds_dwordx4 v134, s[100:101]
	s_mov_b32 m0, s42
	s_nop 0
	global_load_lds_dwordx4 v130, s[100:101]
	s_waitcnt vmcnt(8)
	s_waitcnt lgkmcnt(0)
	v_mfma_f32_16x16x32_f16 v[56:59], v[158:161], v[182:185], v[56:59]
	v_mfma_f32_16x16x32_f16 v[60:63], v[150:153], v[182:185], v[60:63]
	v_mfma_f32_16x16x32_f16 v[48:51], v[158:161], v[190:193], v[48:51]
	v_mfma_f32_16x16x32_f16 v[52:55], v[150:153], v[190:193], v[52:55]
	s_barrier
	s_waitcnt lgkmcnt(0)
	v_mfma_f32_16x16x32_f16 v[32:35], v[158:161], v[198:201], v[32:35]
	v_mfma_f32_16x16x32_f16 v[36:39], v[150:153], v[198:201], v[36:39]
	v_mfma_f32_16x16x32_f16 v[16:19], v[158:161], v[210:213], v[16:19]
	v_mfma_f32_16x16x32_f16 v[20:23], v[150:153], v[210:213], v[20:23]
	v_mfma_f32_16x16x32_f16 v[56:59], v[162:165], v[186:189], v[56:59]
	v_mfma_f32_16x16x32_f16 v[60:63], v[154:157], v[186:189], v[60:63]
	v_mfma_f32_16x16x32_f16 v[48:51], v[162:165], v[194:197], v[48:51]
	v_mfma_f32_16x16x32_f16 v[52:55], v[154:157], v[194:197], v[52:55]
	v_mfma_f32_16x16x32_f16 v[32:35], v[162:165], v[206:209], v[32:35]
	v_mfma_f32_16x16x32_f16 v[36:39], v[154:157], v[206:209], v[36:39]
	v_mfma_f32_16x16x32_f16 v[16:19], v[162:165], v[214:217], v[16:19]
	v_mfma_f32_16x16x32_f16 v[20:23], v[154:157], v[214:217], v[20:23]
	v_mfma_f32_16x16x32_f16 v[40:43], v[174:177], v[182:185], v[40:43]
	v_mfma_f32_16x16x32_f16 v[44:47], v[166:169], v[182:185], v[44:47]
	v_mfma_f32_16x16x32_f16 v[24:27], v[174:177], v[190:193], v[24:27]
	v_mfma_f32_16x16x32_f16 v[28:31], v[166:169], v[190:193], v[28:31]
	v_mfma_f32_16x16x32_f16 v[8:11], v[174:177], v[198:201], v[8:11]
	v_mfma_f32_16x16x32_f16 v[12:15], v[166:169], v[198:201], v[12:15]
	v_mfma_f32_16x16x32_f16 v[0:3], v[174:177], v[210:213], v[0:3]
	v_mfma_f32_16x16x32_f16 v[4:7], v[166:169], v[210:213], v[4:7]
	v_mfma_f32_16x16x32_f16 v[40:43], v[178:181], v[186:189], v[40:43]
	v_mfma_f32_16x16x32_f16 v[44:47], v[170:173], v[186:189], v[44:47]
	v_mfma_f32_16x16x32_f16 v[24:27], v[178:181], v[194:197], v[24:27]
	v_mfma_f32_16x16x32_f16 v[28:31], v[170:173], v[194:197], v[28:31]
	v_mfma_f32_16x16x32_f16 v[8:11], v[178:181], v[206:209], v[8:11]
	v_mfma_f32_16x16x32_f16 v[12:15], v[170:173], v[206:209], v[12:15]
	v_mfma_f32_16x16x32_f16 v[0:3], v[178:181], v[214:217], v[0:3]
	v_mfma_f32_16x16x32_f16 v[4:7], v[170:173], v[214:217], v[4:7]
	s_barrier
	s_add_i32 s62, s62, 2
	s_add_u32 s60, s60, 0x100
	s_addc_u32 s61, s61, 0
	s_add_u32 s22, s22, 0x100
	s_addc_u32 s23, s23, 0
	s_cmp_gt_u32 s62, 29
	s_cbranch_scc0 .LBB0_146
	s_and_b64 vcc, exec, s[10:11]
	s_cbranch_vccz .LBB0_149
	s_barrier

; #define PG8_STAGE(bufoff, gbase, voff) do { _Pragma("unroll") for (int _i = 0; _i < 2; ++_i) \
;         __builtin_amdgcn_global_load_lds((const unsigned*)((const char*)(gbase) + (voff)[_i]), (PG8_LAS unsigned*)(lds + (bufoff) + ldsw + _i * 8192), 16, 0, 0); } while (0)
; #define PG8_LDA(dst, b, h) do { _Pragma("unroll") for (int m = 0; m < 4; ++m) _Pragma("unroll") for (int k = 0; k < 2; ++k) dst[m][k] = *(const PG8_LAS bf16x8*)(lds + PG8_SA(b, h) + aoff + m * 2048 + k * 1024); } while (0)
; #define PG8_LDB(dst, b, h) do { _Pragma("unroll") for (int n = 0; n < 2; ++n) _Pragma("unroll") for (int k = 0; k < 2; ++k) dst[n][k] = *(const PG8_LAS bf16x8*)(lds + PG8_SB(b, h) + boff + n * 2048 + k * 1024); } while (0)
; #define PG8_MMA(ai, bj, At, Bt) do { __builtin_amdgcn_s_setprio(1); _Pragma("unroll") for (int m = 0; m < 4; ++m) _Pragma("unroll") for (int n = 0; n < 2; ++n) _Pragma("unroll") for (int k = 0; k < 2; ++k) \
;         acc[ai][bj][m][n] = __builtin_amdgcn_mfma_f32_16x16x32_f16(Bt[n][k], At[m][k], acc[ai][bj][m][n], 0, 0, 0); __builtin_amdgcn_s_setprio(0); } while (0)
; #define PG8_WAIT_V(n) asm volatile("s_waitcnt vmcnt(" #n ")" ::: "memory")
; #define PG8_WAIT_L(n) asm volatile("s_waitcnt lgkmcnt(" #n ")" ::: "memory")
; #define PG8_BAR __builtin_amdgcn_s_barrier()
; #define PG8_SCHED __builtin_amdgcn_sched_barrier(0)
; template <class Epi, class Sched, bool ALIGN_EPI = false, bool SP2 = false>
; __device__ __forceinline__ void gemm_phase(PG8_LAS unsigned char* lds, const Gemm g, const Sched& S, const Epi& E) {
;     ...
;             PG8_LDB(B0, 0, 0); PG8_LDB(B1, 0, 1); PG8_SCHED; PG8_LDA(At, 0, 0); PG8_STAGE(PG8_SA(1, 1), a1 + hstep, voffA);
;             PG8_WAIT_V(8); PG8_WAIT_L(0); PG8_BAR; PG8_MMA(0, 0, At, B0); PG8_MMA(0, 1, At, B1); PG8_BAR; PG8_SCHED;
;             PG8_LDA(At, 0, 1); PG8_STAGE(PG8_SB(0, 0), b2, voffB); PG8_STAGE(PG8_SB(0, 1), b2 + hstep, voffB); PG8_STAGE(PG8_SA(0, 0), a2, voffA);
;             PG8_WAIT_V(8); PG8_WAIT_L(0); PG8_BAR; PG8_MMA(1, 0, At, B0); PG8_MMA(1, 1, At, B1); PG8_BAR; PG8_SCHED;
.LBB0_485:
	ds_read_b128 v[128:131], v163
	ds_read_b128 v[132:135], v163 offset:1024
	ds_read_b128 v[152:155], v163 offset:2048
	ds_read_b128 v[156:159], v163 offset:3072
	ds_read_b128 v[166:169], v164
	ds_read_b128 v[170:173], v164 offset:1024
	ds_read_b128 v[174:177], v164 offset:2048
	ds_read_b128 v[178:181], v164 offset:3072
	s_add_u32 s26, s24, 0x100
	s_addc_u32 s27, s25, 0
	s_cmp_eq_u32 s65, 20
	s_cselect_b32 s31, s1, s27
	s_cselect_b32 s30, s0, s26
	s_cselect_b32 s29, s23, s64
	s_cselect_b32 s28, s22, s63
	s_add_i32 m0, s37, 0xc000
	ds_read_b128 v[182:185], v165
	ds_read_b128 v[186:189], v165 offset:1024
	ds_read_b128 v[190:193], v165 offset:2048
	ds_read_b128 v[194:197], v165 offset:3072
	ds_read_b128 v[198:201], v165 offset:4096
	ds_read_b128 v[208:211], v165 offset:5120
	ds_read_b128 v[212:215], v165 offset:6144
	ds_read_b128 v[216:219], v165 offset:7168
	global_load_lds_dwordx4 v146, s[24:25]
	s_add_i32 m0, s37, 0xe000
	s_nop 0
	global_load_lds_dwordx4 v144, s[24:25]
	s_waitcnt vmcnt(8)
	s_waitcnt lgkmcnt(0)
	v_mfma_f32_16x16x32_f16 v[120:123], v[152:155], v[182:185], v[120:123]
	v_mfma_f32_16x16x32_f16 v[124:127], v[128:131], v[182:185], v[124:127]
	v_mfma_f32_16x16x32_f16 v[104:107], v[152:155], v[190:193], v[104:107]
	v_mfma_f32_16x16x32_f16 v[108:111], v[128:131], v[190:193], v[108:111]
	s_barrier
	s_waitcnt lgkmcnt(0)
	v_mfma_f32_16x16x32_f16 v[88:91], v[152:155], v[198:201], v[88:91]
	v_mfma_f32_16x16x32_f16 v[92:95], v[128:131], v[198:201], v[92:95]
	v_mfma_f32_16x16x32_f16 v[72:75], v[152:155], v[212:215], v[72:75]
	v_mfma_f32_16x16x32_f16 v[76:79], v[128:131], v[212:215], v[76:79]
	v_mfma_f32_16x16x32_f16 v[120:123], v[156:159], v[186:189], v[120:123]
	v_mfma_f32_16x16x32_f16 v[124:127], v[132:135], v[186:189], v[124:127]
	v_mfma_f32_16x16x32_f16 v[104:107], v[156:159], v[194:197], v[104:107]
	v_mfma_f32_16x16x32_f16 v[108:111], v[132:135], v[194:197], v[108:111]
	v_mfma_f32_16x16x32_f16 v[88:91], v[156:159], v[208:211], v[88:91]
	v_mfma_f32_16x16x32_f16 v[92:95], v[132:135], v[208:211], v[92:95]
	v_mfma_f32_16x16x32_f16 v[72:75], v[156:159], v[216:219], v[72:75]
	v_mfma_f32_16x16x32_f16 v[76:79], v[132:135], v[216:219], v[76:79]
	v_mfma_f32_16x16x32_f16 v[112:115], v[174:177], v[182:185], v[112:115]
	v_mfma_f32_16x16x32_f16 v[116:119], v[166:169], v[182:185], v[116:119]
	v_mfma_f32_16x16x32_f16 v[96:99], v[174:177], v[190:193], v[96:99]
	v_mfma_f32_16x16x32_f16 v[100:103], v[166:169], v[190:193], v[100:103]
	v_mfma_f32_16x16x32_f16 v[80:83], v[174:177], v[198:201], v[80:83]
	v_mfma_f32_16x16x32_f16 v[84:87], v[166:169], v[198:201], v[84:87]
	v_mfma_f32_16x16x32_f16 v[64:67], v[174:177], v[212:215], v[64:67]
	v_mfma_f32_16x16x32_f16 v[68:71], v[166:169], v[212:215], v[68:71]
	v_mfma_f32_16x16x32_f16 v[112:115], v[178:181], v[186:189], v[112:115]
	v_mfma_f32_16x16x32_f16 v[116:119], v[170:173], v[186:189], v[116:119]
	v_mfma_f32_16x16x32_f16 v[96:99], v[178:181], v[194:197], v[96:99]
	v_mfma_f32_16x16x32_f16 v[100:103], v[170:173], v[194:197], v[100:103]
	v_mfma_f32_16x16x32_f16 v[80:83], v[178:181], v[208:211], v[80:83]
	v_mfma_f32_16x16x32_f16 v[84:87], v[170:173], v[208:211], v[84:87]
	v_mfma_f32_16x16x32_f16 v[64:67], v[178:181], v[216:219], v[64:67]
	v_mfma_f32_16x16x32_f16 v[68:71], v[170:173], v[216:219], v[68:71]
	s_barrier
	s_add_i32 s24, s45, s36
	s_add_u32 s98, s28, s16
	s_addc_u32 s99, s29, s17
	s_mov_b32 m0, s24
	ds_read_b128 v[182:185], v165 offset:16384
	ds_read_b128 v[186:189], v165 offset:17408
	ds_read_b128 v[190:193], v165 offset:18432
	ds_read_b128 v[194:197], v165 offset:19456
	ds_read_b128 v[198:201], v165 offset:20480
	ds_read_b128 v[208:211], v165 offset:21504
	ds_read_b128 v[212:215], v165 offset:22528
	ds_read_b128 v[216:219], v165 offset:23552
	global_load_lds_dwordx4 v138, s[28:29]
	s_add_i32 m0, s24, 0x2000
	s_add_u32 s24, s28, 0x60000
	s_addc_u32 s25, s29, 0
	s_add_i32 s66, s52, s36
	global_load_lds_dwordx4 v142, s[28:29]
	s_mov_b32 m0, s66
	s_nop 0
	global_load_lds_dwordx4 v138, s[24:25]
	s_add_i32 m0, s66, 0x2000
	s_nop 0
	global_load_lds_dwordx4 v142, s[24:25]
	s_add_u32 s100, s30, s16
	s_addc_u32 s101, s31, s17
	s_mov_b32 m0, s37
	s_nop 0
	global_load_lds_dwordx4 v136, s[30:31]
	s_mov_b32 m0, s38
	s_nop 0
	global_load_lds_dwordx4 v140, s[30:31]
	s_waitcnt vmcnt(8)
	s_waitcnt lgkmcnt(0)
	v_mfma_f32_16x16x32_f16 v[56:59], v[152:155], v[182:185], v[56:59]
	v_mfma_f32_16x16x32_f16 v[60:63], v[128:131], v[182:185], v[60:63]
	v_mfma_f32_16x16x32_f16 v[40:43], v[152:155], v[190:193], v[40:43]
	v_mfma_f32_16x16x32_f16 v[44:47], v[128:131], v[190:193], v[44:47]
	s_barrier
	s_waitcnt lgkmcnt(0)
	v_mfma_f32_16x16x32_f16 v[24:27], v[152:155], v[198:201], v[24:27]
	v_mfma_f32_16x16x32_f16 v[28:31], v[128:131], v[198:201], v[28:31]
	v_mfma_f32_16x16x32_f16 v[8:11], v[152:155], v[212:215], v[8:11]
	v_mfma_f32_16x16x32_f16 v[12:15], v[128:131], v[212:215], v[12:15]
	v_mfma_f32_16x16x32_f16 v[56:59], v[156:159], v[186:189], v[56:59]
	v_mfma_f32_16x16x32_f16 v[60:63], v[132:135], v[186:189], v[60:63]
	v_mfma_f32_16x16x32_f16 v[40:43], v[156:159], v[194:197], v[40:43]
	v_mfma_f32_16x16x32_f16 v[44:47], v[132:135], v[194:197], v[44:47]
	v_mfma_f32_16x16x32_f16 v[24:27], v[156:159], v[208:211], v[24:27]
	v_mfma_f32_16x16x32_f16 v[28:31], v[132:135], v[208:211], v[28:31]
	v_mfma_f32_16x16x32_f16 v[8:11], v[156:159], v[216:219], v[8:11]
	v_mfma_f32_16x16x32_f16 v[12:15], v[132:135], v[216:219], v[12:15]
	v_mfma_f32_16x16x32_f16 v[48:51], v[174:177], v[182:185], v[48:51]
	v_mfma_f32_16x16x32_f16 v[52:55], v[166:169], v[182:185], v[52:55]
	v_mfma_f32_16x16x32_f16 v[32:35], v[174:177], v[190:193], v[32:35]
	v_mfma_f32_16x16x32_f16 v[36:39], v[166:169], v[190:193], v[36:39]
	v_mfma_f32_16x16x32_f16 v[16:19], v[174:177], v[198:201], v[16:19]
	v_mfma_f32_16x16x32_f16 v[20:23], v[166:169], v[198:201], v[20:23]
	v_mfma_f32_16x16x32_f16 v[0:3], v[174:177], v[212:215], v[0:3]
	v_mfma_f32_16x16x32_f16 v[4:7], v[166:169], v[212:215], v[4:7]
	v_mfma_f32_16x16x32_f16 v[48:51], v[178:181], v[186:189], v[48:51]
	v_mfma_f32_16x16x32_f16 v[52:55], v[170:173], v[186:189], v[52:55]
	v_mfma_f32_16x16x32_f16 v[32:35], v[178:181], v[194:197], v[32:35]
	v_mfma_f32_16x16x32_f16 v[36:39], v[170:173], v[194:197], v[36:39]
	v_mfma_f32_16x16x32_f16 v[16:19], v[178:181], v[208:211], v[16:19]
	v_mfma_f32_16x16x32_f16 v[20:23], v[170:173], v[208:211], v[20:23]
	v_mfma_f32_16x16x32_f16 v[0:3], v[178:181], v[216:219], v[0:3]
	v_mfma_f32_16x16x32_f16 v[4:7], v[170:173], v[216:219], v[4:7]
	s_barrier
; #define PG8_STAGE(bufoff, gbase, voff) do { _Pragma("unroll") for (int _i = 0; _i < 2; ++_i) \
;         __builtin_amdgcn_global_load_lds((const unsigned*)((const char*)(gbase) + (voff)[_i]), (PG8_LAS unsigned*)(lds + (bufoff) + ldsw + _i * 8192), 16, 0, 0); } while (0)
; #define PG8_LDA(dst, b, h) do { _Pragma("unroll") for (int m = 0; m < 4; ++m) _Pragma("unroll") for (int k = 0; k < 2; ++k) dst[m][k] = *(const PG8_LAS bf16x8*)(lds + PG8_SA(b, h) + aoff + m * 2048 + k * 1024); } while (0)
; #define PG8_LDB(dst, b, h) do { _Pragma("unroll") for (int n = 0; n < 2; ++n) _Pragma("unroll") for (int k = 0; k < 2; ++k) dst[n][k] = *(const PG8_LAS bf16x8*)(lds + PG8_SB(b, h) + boff + n * 2048 + k * 1024); } while (0)
; #define PG8_MMA(ai, bj, At, Bt) do { __builtin_amdgcn_s_setprio(1); _Pragma("unroll") for (int m = 0; m < 4; ++m) _Pragma("unroll") for (int n = 0; n < 2; ++n) _Pragma("unroll") for (int k = 0; k < 2; ++k) \
;         acc[ai][bj][m][n] = __builtin_amdgcn_mfma_f32_16x16x32_f16(Bt[n][k], At[m][k], acc[ai][bj][m][n], 0, 0, 0); __builtin_amdgcn_s_setprio(0); } while (0)
; #define PG8_WAIT_V(n) asm volatile("s_waitcnt vmcnt(" #n ")" ::: "memory")
; #define PG8_WAIT_L(n) asm volatile("s_waitcnt lgkmcnt(" #n ")" ::: "memory")
; #define PG8_BAR __builtin_amdgcn_s_barrier()
; #define PG8_SCHED __builtin_amdgcn_sched_barrier(0)
; template <class Epi, class Sched, bool ALIGN_EPI = false, bool SP2 = false>
; __device__ __forceinline__ void gemm_phase(PG8_LAS unsigned char* lds, const Gemm g, const Sched& S, const Epi& E) {
;     ...
;             PG8_LDB(B0, 1, 0); PG8_LDB(B1, 1, 1); PG8_SCHED; PG8_LDA(At, 1, 0); PG8_STAGE(PG8_SA(0, 1), a2 + hstep, voffA);
;             PG8_WAIT_V(8); PG8_WAIT_L(0); PG8_BAR; PG8_MMA(0, 0, At, B0); PG8_MMA(0, 1, At, B1); PG8_BAR; PG8_SCHED;
;             PG8_LDA(At, 1, 1); PG8_STAGE(PG8_SB(1, 0), b3, voffB); PG8_STAGE(PG8_SB(1, 1), b3 + hstep, voffB); PG8_STAGE(PG8_SA(1, 0), a3, voffA);
;             PG8_WAIT_V(8); PG8_WAIT_L(0); PG8_BAR; PG8_MMA(1, 0, At, B0); PG8_MMA(1, 1, At, B1); PG8_BAR; PG8_SCHED;
	s_add_i32 s66, 0, 0x18000
	s_add_i32 s67, 0, 0x1c000
	v_add_u32_e32 v156, s66, v161
	v_add_u32_e32 v178, s67, v161
	ds_read_b128 v[128:131], v156
	ds_read_b128 v[132:135], v156 offset:1024
	ds_read_b128 v[152:155], v156 offset:2048
	ds_read_b128 v[156:159], v156 offset:3072
	ds_read_b128 v[166:169], v178
	ds_read_b128 v[170:173], v178 offset:1024
	ds_read_b128 v[174:177], v178 offset:2048
	ds_read_b128 v[178:181], v178 offset:3072
	s_add_u32 s24, s30, 0x60000
	s_addc_u32 s25, s31, 0
	s_mov_b32 m0, s39
	ds_read_b128 v[182:185], v165 offset:32768
	ds_read_b128 v[186:189], v165 offset:33792
	ds_read_b128 v[190:193], v165 offset:34816
	ds_read_b128 v[194:197], v165 offset:35840
	ds_read_b128 v[198:201], v165 offset:36864
	ds_read_b128 v[208:211], v165 offset:37888
	ds_read_b128 v[212:215], v165 offset:38912
	ds_read_b128 v[216:219], v165 offset:39936
	global_load_lds_dwordx4 v136, s[24:25]
	s_mov_b32 m0, s40
	s_nop 0
	global_load_lds_dwordx4 v140, s[24:25]
	s_waitcnt vmcnt(8)
	s_waitcnt lgkmcnt(0)
	v_mfma_f32_16x16x32_f16 v[120:123], v[152:155], v[182:185], v[120:123]
	v_mfma_f32_16x16x32_f16 v[124:127], v[128:131], v[182:185], v[124:127]
	v_mfma_f32_16x16x32_f16 v[104:107], v[152:155], v[190:193], v[104:107]
	v_mfma_f32_16x16x32_f16 v[108:111], v[128:131], v[190:193], v[108:111]
	s_barrier
	s_waitcnt lgkmcnt(0)
	v_mfma_f32_16x16x32_f16 v[88:91], v[152:155], v[198:201], v[88:91]
	v_mfma_f32_16x16x32_f16 v[92:95], v[128:131], v[198:201], v[92:95]
	v_mfma_f32_16x16x32_f16 v[72:75], v[152:155], v[212:215], v[72:75]
	v_mfma_f32_16x16x32_f16 v[76:79], v[128:131], v[212:215], v[76:79]
	v_mfma_f32_16x16x32_f16 v[120:123], v[156:159], v[186:189], v[120:123]
	v_mfma_f32_16x16x32_f16 v[124:127], v[132:135], v[186:189], v[124:127]
	v_mfma_f32_16x16x32_f16 v[104:107], v[156:159], v[194:197], v[104:107]
	v_mfma_f32_16x16x32_f16 v[108:111], v[132:135], v[194:197], v[108:111]
	v_mfma_f32_16x16x32_f16 v[88:91], v[156:159], v[208:211], v[88:91]
	v_mfma_f32_16x16x32_f16 v[92:95], v[132:135], v[208:211], v[92:95]
	v_mfma_f32_16x16x32_f16 v[72:75], v[156:159], v[216:219], v[72:75]
	v_mfma_f32_16x16x32_f16 v[76:79], v[132:135], v[216:219], v[76:79]
	v_mfma_f32_16x16x32_f16 v[112:115], v[174:177], v[182:185], v[112:115]
	v_mfma_f32_16x16x32_f16 v[116:119], v[166:169], v[182:185], v[116:119]
	v_mfma_f32_16x16x32_f16 v[96:99], v[174:177], v[190:193], v[96:99]
	v_mfma_f32_16x16x32_f16 v[100:103], v[166:169], v[190:193], v[100:103]
	v_mfma_f32_16x16x32_f16 v[80:83], v[174:177], v[198:201], v[80:83]
	v_mfma_f32_16x16x32_f16 v[84:87], v[166:169], v[198:201], v[84:87]
	v_mfma_f32_16x16x32_f16 v[64:67], v[174:177], v[212:215], v[64:67]
	v_mfma_f32_16x16x32_f16 v[68:71], v[166:169], v[212:215], v[68:71]
	v_mfma_f32_16x16x32_f16 v[112:115], v[178:181], v[186:189], v[112:115]
	v_mfma_f32_16x16x32_f16 v[116:119], v[170:173], v[186:189], v[116:119]
	v_mfma_f32_16x16x32_f16 v[96:99], v[178:181], v[194:197], v[96:99]
	v_mfma_f32_16x16x32_f16 v[100:103], v[170:173], v[194:197], v[100:103]
	v_mfma_f32_16x16x32_f16 v[80:83], v[178:181], v[208:211], v[80:83]
	v_mfma_f32_16x16x32_f16 v[84:87], v[170:173], v[208:211], v[84:87]
	v_mfma_f32_16x16x32_f16 v[64:67], v[178:181], v[216:219], v[64:67]
	v_mfma_f32_16x16x32_f16 v[68:71], v[170:173], v[216:219], v[68:71]
	s_barrier
	s_add_i32 s24, s66, s36
	s_mov_b32 m0, s24
	ds_read_b128 v[182:185], v165 offset:49152
	ds_read_b128 v[186:189], v165 offset:50176
	ds_read_b128 v[190:193], v165 offset:51200
	ds_read_b128 v[194:197], v165 offset:52224
	ds_read_b128 v[198:201], v165 offset:53248
	ds_read_b128 v[208:211], v165 offset:54272
	ds_read_b128 v[212:215], v165 offset:55296
	ds_read_b128 v[216:219], v165 offset:56320
	global_load_lds_dwordx4 v138, s[98:99]
	s_add_i32 m0, s24, 0x2000
	s_add_u32 s24, s28, 0x60080
	s_addc_u32 s25, s29, 0
	s_add_i32 s28, s67, s36
	global_load_lds_dwordx4 v142, s[98:99]
	s_mov_b32 m0, s28
	s_nop 0
	global_load_lds_dwordx4 v138, s[24:25]
	s_add_i32 m0, s28, 0x2000
	s_nop 0
	global_load_lds_dwordx4 v142, s[24:25]
	s_mov_b32 m0, s42
	s_nop 0
	global_load_lds_dwordx4 v136, s[100:101]
	s_mov_b32 m0, s43
	s_nop 0
	global_load_lds_dwordx4 v140, s[100:101]
	s_waitcnt vmcnt(8)
	s_waitcnt lgkmcnt(0)
	v_mfma_f32_16x16x32_f16 v[56:59], v[152:155], v[182:185], v[56:59]
	v_mfma_f32_16x16x32_f16 v[60:63], v[128:131], v[182:185], v[60:63]
	v_mfma_f32_16x16x32_f16 v[40:43], v[152:155], v[190:193], v[40:43]
	v_mfma_f32_16x16x32_f16 v[44:47], v[128:131], v[190:193], v[44:47]
	s_barrier
	s_waitcnt lgkmcnt(0)
	v_mfma_f32_16x16x32_f16 v[24:27], v[152:155], v[198:201], v[24:27]
	v_mfma_f32_16x16x32_f16 v[28:31], v[128:131], v[198:201], v[28:31]
	v_mfma_f32_16x16x32_f16 v[8:11], v[152:155], v[212:215], v[8:11]
	v_mfma_f32_16x16x32_f16 v[12:15], v[128:131], v[212:215], v[12:15]
	v_mfma_f32_16x16x32_f16 v[56:59], v[156:159], v[186:189], v[56:59]
	v_mfma_f32_16x16x32_f16 v[60:63], v[132:135], v[186:189], v[60:63]
	v_mfma_f32_16x16x32_f16 v[40:43], v[156:159], v[194:197], v[40:43]
	v_mfma_f32_16x16x32_f16 v[44:47], v[132:135], v[194:197], v[44:47]
	v_mfma_f32_16x16x32_f16 v[24:27], v[156:159], v[208:211], v[24:27]
	v_mfma_f32_16x16x32_f16 v[28:31], v[132:135], v[208:211], v[28:31]
	v_mfma_f32_16x16x32_f16 v[8:11], v[156:159], v[216:219], v[8:11]
	v_mfma_f32_16x16x32_f16 v[12:15], v[132:135], v[216:219], v[12:15]
	v_mfma_f32_16x16x32_f16 v[48:51], v[174:177], v[182:185], v[48:51]
	v_mfma_f32_16x16x32_f16 v[52:55], v[166:169], v[182:185], v[52:55]
	v_mfma_f32_16x16x32_f16 v[32:35], v[174:177], v[190:193], v[32:35]
	v_mfma_f32_16x16x32_f16 v[36:39], v[166:169], v[190:193], v[36:39]
	v_mfma_f32_16x16x32_f16 v[16:19], v[174:177], v[198:201], v[16:19]
	v_mfma_f32_16x16x32_f16 v[20:23], v[166:169], v[198:201], v[20:23]
	v_mfma_f32_16x16x32_f16 v[0:3], v[174:177], v[212:215], v[0:3]
	v_mfma_f32_16x16x32_f16 v[4:7], v[166:169], v[212:215], v[4:7]
	v_mfma_f32_16x16x32_f16 v[48:51], v[178:181], v[186:189], v[48:51]
	v_mfma_f32_16x16x32_f16 v[52:55], v[170:173], v[186:189], v[52:55]
	v_mfma_f32_16x16x32_f16 v[32:35], v[178:181], v[194:197], v[32:35]
	v_mfma_f32_16x16x32_f16 v[36:39], v[170:173], v[194:197], v[36:39]
	v_mfma_f32_16x16x32_f16 v[16:19], v[178:181], v[208:211], v[16:19]
	v_mfma_f32_16x16x32_f16 v[20:23], v[170:173], v[208:211], v[20:23]
	v_mfma_f32_16x16x32_f16 v[0:3], v[178:181], v[216:219], v[0:3]
	v_mfma_f32_16x16x32_f16 v[4:7], v[170:173], v[216:219], v[4:7]
	s_barrier
	s_add_i32 s65, s65, 2
	s_add_u32 s63, s63, 0x100
	s_addc_u32 s64, s64, 0
	s_cmp_gt_u32 s65, 21
	s_mov_b64 s[24:25], s[26:27]
	s_cbranch_scc0 .LBB0_485
	s_and_b64 vcc, exec, s[18:19]
	s_cbranch_vccz .LBB0_488
	s_barrier

; #define PG8_STAGE(bufoff, gbase, voff) do { _Pragma("unroll") for (int _i = 0; _i < 2; ++_i) \
;         __builtin_amdgcn_global_load_lds((const unsigned*)((const char*)(gbase) + (voff)[_i]), (PG8_LAS unsigned*)(lds + (bufoff) + ldsw + _i * 8192), 16, 0, 0); } while (0)
; #define PG8_LDA(dst, b, h) do { _Pragma("unroll") for (int m = 0; m < 4; ++m) _Pragma("unroll") for (int k = 0; k < 2; ++k) dst[m][k] = *(const PG8_LAS bf16x8*)(lds + PG8_SA(b, h) + aoff + m * 2048 + k * 1024); } while (0)
; #define PG8_LDB(dst, b, h) do { _Pragma("unroll") for (int n = 0; n < 2; ++n) _Pragma("unroll") for (int k = 0; k < 2; ++k) dst[n][k] = *(const PG8_LAS bf16x8*)(lds + PG8_SB(b, h) + boff + n * 2048 + k * 1024); } while (0)
; #define PG8_MMA(ai, bj, At, Bt) do { __builtin_amdgcn_s_setprio(1); _Pragma("unroll") for (int m = 0; m < 4; ++m) _Pragma("unroll") for (int n = 0; n < 2; ++n) _Pragma("unroll") for (int k = 0; k < 2; ++k) \
;         acc[ai][bj][m][n] = __builtin_amdgcn_mfma_f32_16x16x32_f16(Bt[n][k], At[m][k], acc[ai][bj][m][n], 0, 0, 0); __builtin_amdgcn_s_setprio(0); } while (0)
; #define PG8_WAIT_V(n) asm volatile("s_waitcnt vmcnt(" #n ")" ::: "memory")
; #define PG8_WAIT_L(n) asm volatile("s_waitcnt lgkmcnt(" #n ")" ::: "memory")
; #define PG8_BAR __builtin_amdgcn_s_barrier()
; #define PG8_SCHED __builtin_amdgcn_sched_barrier(0)
; template <class Epi, class Sched, bool ALIGN_EPI = false, bool SP2 = false>
; __device__ __forceinline__ void gemm_phase(PG8_LAS unsigned char* lds, const Gemm g, const Sched& S, const Epi& E) {
;     ...
;             PG8_LDB(B0, 0, 0); PG8_LDB(B1, 0, 1); PG8_SCHED; PG8_LDA(At, 0, 0); PG8_STAGE(PG8_SA(1, 1), a1 + hstep, voffA);
;             PG8_WAIT_V(8); PG8_WAIT_L(0); PG8_BAR; PG8_MMA(0, 0, At, B0); PG8_MMA(0, 1, At, B1); PG8_BAR; PG8_SCHED;
;             PG8_LDA(At, 0, 1); PG8_STAGE(PG8_SB(0, 0), b2, voffB); PG8_STAGE(PG8_SB(0, 1), b2 + hstep, voffB); PG8_STAGE(PG8_SA(0, 0), a2, voffA);
;             PG8_WAIT_V(8); PG8_WAIT_L(0); PG8_BAR; PG8_MMA(1, 0, At, B0); PG8_MMA(1, 1, At, B1); PG8_BAR; PG8_SCHED;
.LBB0_577:
	ds_read_b128 v[128:131], v198
	ds_read_b128 v[132:135], v198 offset:1024
	ds_read_b128 v[136:139], v198 offset:2048
	ds_read_b128 v[140:143], v198 offset:3072
	ds_read_b128 v[144:147], v199
	ds_read_b128 v[148:151], v199 offset:1024
	ds_read_b128 v[152:155], v199 offset:2048
	ds_read_b128 v[156:159], v199 offset:3072
	s_add_u32 s42, s40, 0xfff80080
	s_addc_u32 s43, s41, -1
	s_cmp_eq_u32 s91, 28
	s_cselect_b32 s45, s31, s43
	s_cselect_b32 s44, s87, s42
	s_cselect_b32 s43, s29, s90
	s_cselect_b32 s42, s88, s89
	s_add_i32 m0, s39, 0xc000
	ds_read_b128 v[176:179], v200
	ds_read_b128 v[180:183], v200 offset:1024
	ds_read_b128 v[184:187], v200 offset:2048
	ds_read_b128 v[188:191], v200 offset:3072
	ds_read_b128 v[208:211], v200 offset:4096
	ds_read_b128 v[212:215], v200 offset:5120
	ds_read_b128 v[216:219], v200 offset:6144
	ds_read_b128 v[220:223], v200 offset:7168
	global_load_lds_dwordx4 v170, s[40:41]
	s_add_i32 m0, s39, 0xe000
	s_nop 0
	global_load_lds_dwordx4 v168, s[40:41]
	s_waitcnt vmcnt(8)
	s_waitcnt lgkmcnt(0)
	v_mfma_f32_16x16x32_f16 v[120:123], v[136:139], v[176:179], v[120:123]
	v_mfma_f32_16x16x32_f16 v[124:127], v[128:131], v[176:179], v[124:127]
	v_mfma_f32_16x16x32_f16 v[104:107], v[136:139], v[184:187], v[104:107]
	v_mfma_f32_16x16x32_f16 v[108:111], v[128:131], v[184:187], v[108:111]
	s_barrier
	s_waitcnt lgkmcnt(0)
	v_mfma_f32_16x16x32_f16 v[88:91], v[136:139], v[208:211], v[88:91]
	v_mfma_f32_16x16x32_f16 v[92:95], v[128:131], v[208:211], v[92:95]
	v_mfma_f32_16x16x32_f16 v[72:75], v[136:139], v[216:219], v[72:75]
	v_mfma_f32_16x16x32_f16 v[76:79], v[128:131], v[216:219], v[76:79]
	v_mfma_f32_16x16x32_f16 v[120:123], v[140:143], v[180:183], v[120:123]
	v_mfma_f32_16x16x32_f16 v[124:127], v[132:135], v[180:183], v[124:127]
	v_mfma_f32_16x16x32_f16 v[104:107], v[140:143], v[188:191], v[104:107]
	v_mfma_f32_16x16x32_f16 v[108:111], v[132:135], v[188:191], v[108:111]
	v_mfma_f32_16x16x32_f16 v[88:91], v[140:143], v[212:215], v[88:91]
	v_mfma_f32_16x16x32_f16 v[92:95], v[132:135], v[212:215], v[92:95]
	v_mfma_f32_16x16x32_f16 v[72:75], v[140:143], v[220:223], v[72:75]
	v_mfma_f32_16x16x32_f16 v[76:79], v[132:135], v[220:223], v[76:79]
	v_mfma_f32_16x16x32_f16 v[112:115], v[152:155], v[176:179], v[112:115]
	v_mfma_f32_16x16x32_f16 v[116:119], v[144:147], v[176:179], v[116:119]
	v_mfma_f32_16x16x32_f16 v[96:99], v[152:155], v[184:187], v[96:99]
	v_mfma_f32_16x16x32_f16 v[100:103], v[144:147], v[184:187], v[100:103]
	v_mfma_f32_16x16x32_f16 v[80:83], v[152:155], v[208:211], v[80:83]
	v_mfma_f32_16x16x32_f16 v[84:87], v[144:147], v[208:211], v[84:87]
	v_mfma_f32_16x16x32_f16 v[64:67], v[152:155], v[216:219], v[64:67]
	v_mfma_f32_16x16x32_f16 v[68:71], v[144:147], v[216:219], v[68:71]
	v_mfma_f32_16x16x32_f16 v[112:115], v[156:159], v[180:183], v[112:115]
	v_mfma_f32_16x16x32_f16 v[116:119], v[148:151], v[180:183], v[116:119]
	v_mfma_f32_16x16x32_f16 v[96:99], v[156:159], v[188:191], v[96:99]
	v_mfma_f32_16x16x32_f16 v[100:103], v[148:151], v[188:191], v[100:103]
	v_mfma_f32_16x16x32_f16 v[80:83], v[156:159], v[212:215], v[80:83]
	v_mfma_f32_16x16x32_f16 v[84:87], v[148:151], v[212:215], v[84:87]
	v_mfma_f32_16x16x32_f16 v[64:67], v[156:159], v[220:223], v[64:67]
	v_mfma_f32_16x16x32_f16 v[68:71], v[148:151], v[220:223], v[68:71]
	s_barrier
	s_add_i32 s92, s74, s63
	s_add_u32 s98, s42, s16
	s_addc_u32 s99, s43, s17
	s_mov_b32 m0, s92
	ds_read_b128 v[176:179], v200 offset:16384
	ds_read_b128 v[180:183], v200 offset:17408
	ds_read_b128 v[184:187], v200 offset:18432
	ds_read_b128 v[188:191], v200 offset:19456
	ds_read_b128 v[208:211], v200 offset:20480
	ds_read_b128 v[212:215], v200 offset:21504
	ds_read_b128 v[216:219], v200 offset:22528
	ds_read_b128 v[220:223], v200 offset:23552
	global_load_lds_dwordx4 v162, s[42:43]
	s_add_i32 m0, s92, 0x2000
	s_add_u32 s92, s42, 0x80000
	s_addc_u32 s93, s43, 0
	s_add_i32 s94, s75, s63
	global_load_lds_dwordx4 v166, s[42:43]
	s_mov_b32 m0, s94
	s_nop 0
	global_load_lds_dwordx4 v162, s[92:93]
	s_add_i32 m0, s94, 0x2000
	s_nop 0
	global_load_lds_dwordx4 v166, s[92:93]
	s_add_u32 s100, s44, s16
	s_addc_u32 s101, s45, s17
	s_mov_b32 m0, s39
	s_nop 0
	global_load_lds_dwordx4 v160, s[44:45]
	s_mov_b32 m0, s64
	s_nop 0
	global_load_lds_dwordx4 v164, s[44:45]
	s_waitcnt vmcnt(8)
	s_waitcnt lgkmcnt(0)
	v_mfma_f32_16x16x32_f16 v[56:59], v[136:139], v[176:179], v[56:59]
	v_mfma_f32_16x16x32_f16 v[60:63], v[128:131], v[176:179], v[60:63]
	v_mfma_f32_16x16x32_f16 v[40:43], v[136:139], v[184:187], v[40:43]
	v_mfma_f32_16x16x32_f16 v[44:47], v[128:131], v[184:187], v[44:47]
	s_barrier
	s_waitcnt lgkmcnt(0)
	v_mfma_f32_16x16x32_f16 v[24:27], v[136:139], v[208:211], v[24:27]
	v_mfma_f32_16x16x32_f16 v[28:31], v[128:131], v[208:211], v[28:31]
	v_mfma_f32_16x16x32_f16 v[8:11], v[136:139], v[216:219], v[8:11]
	v_mfma_f32_16x16x32_f16 v[12:15], v[128:131], v[216:219], v[12:15]
	v_mfma_f32_16x16x32_f16 v[56:59], v[140:143], v[180:183], v[56:59]
	v_mfma_f32_16x16x32_f16 v[60:63], v[132:135], v[180:183], v[60:63]
	v_mfma_f32_16x16x32_f16 v[40:43], v[140:143], v[188:191], v[40:43]
	v_mfma_f32_16x16x32_f16 v[44:47], v[132:135], v[188:191], v[44:47]
	v_mfma_f32_16x16x32_f16 v[24:27], v[140:143], v[212:215], v[24:27]
	v_mfma_f32_16x16x32_f16 v[28:31], v[132:135], v[212:215], v[28:31]
	v_mfma_f32_16x16x32_f16 v[8:11], v[140:143], v[220:223], v[8:11]
	v_mfma_f32_16x16x32_f16 v[12:15], v[132:135], v[220:223], v[12:15]
	v_mfma_f32_16x16x32_f16 v[48:51], v[152:155], v[176:179], v[48:51]
	v_mfma_f32_16x16x32_f16 v[52:55], v[144:147], v[176:179], v[52:55]
	v_mfma_f32_16x16x32_f16 v[32:35], v[152:155], v[184:187], v[32:35]
	v_mfma_f32_16x16x32_f16 v[36:39], v[144:147], v[184:187], v[36:39]
	v_mfma_f32_16x16x32_f16 v[16:19], v[152:155], v[208:211], v[16:19]
	v_mfma_f32_16x16x32_f16 v[20:23], v[144:147], v[208:211], v[20:23]
	v_mfma_f32_16x16x32_f16 v[0:3], v[152:155], v[216:219], v[0:3]
	v_mfma_f32_16x16x32_f16 v[4:7], v[144:147], v[216:219], v[4:7]
	v_mfma_f32_16x16x32_f16 v[48:51], v[156:159], v[180:183], v[48:51]
	v_mfma_f32_16x16x32_f16 v[52:55], v[148:151], v[180:183], v[52:55]
	v_mfma_f32_16x16x32_f16 v[32:35], v[156:159], v[188:191], v[32:35]
	v_mfma_f32_16x16x32_f16 v[36:39], v[148:151], v[188:191], v[36:39]
	v_mfma_f32_16x16x32_f16 v[16:19], v[156:159], v[212:215], v[16:19]
	v_mfma_f32_16x16x32_f16 v[20:23], v[148:151], v[212:215], v[20:23]
	v_mfma_f32_16x16x32_f16 v[0:3], v[156:159], v[220:223], v[0:3]
	v_mfma_f32_16x16x32_f16 v[4:7], v[148:151], v[220:223], v[4:7]
	s_barrier
; #define PG8_STAGE(bufoff, gbase, voff) do { _Pragma("unroll") for (int _i = 0; _i < 2; ++_i) \
;         __builtin_amdgcn_global_load_lds((const unsigned*)((const char*)(gbase) + (voff)[_i]), (PG8_LAS unsigned*)(lds + (bufoff) + ldsw + _i * 8192), 16, 0, 0); } while (0)
; #define PG8_LDA(dst, b, h) do { _Pragma("unroll") for (int m = 0; m < 4; ++m) _Pragma("unroll") for (int k = 0; k < 2; ++k) dst[m][k] = *(const PG8_LAS bf16x8*)(lds + PG8_SA(b, h) + aoff + m * 2048 + k * 1024); } while (0)
; #define PG8_LDB(dst, b, h) do { _Pragma("unroll") for (int n = 0; n < 2; ++n) _Pragma("unroll") for (int k = 0; k < 2; ++k) dst[n][k] = *(const PG8_LAS bf16x8*)(lds + PG8_SB(b, h) + boff + n * 2048 + k * 1024); } while (0)
; #define PG8_MMA(ai, bj, At, Bt) do { __builtin_amdgcn_s_setprio(1); _Pragma("unroll") for (int m = 0; m < 4; ++m) _Pragma("unroll") for (int n = 0; n < 2; ++n) _Pragma("unroll") for (int k = 0; k < 2; ++k) \
;         acc[ai][bj][m][n] = __builtin_amdgcn_mfma_f32_16x16x32_f16(Bt[n][k], At[m][k], acc[ai][bj][m][n], 0, 0, 0); __builtin_amdgcn_s_setprio(0); } while (0)
; #define PG8_WAIT_V(n) asm volatile("s_waitcnt vmcnt(" #n ")" ::: "memory")
; #define PG8_WAIT_L(n) asm volatile("s_waitcnt lgkmcnt(" #n ")" ::: "memory")
; #define PG8_BAR __builtin_amdgcn_s_barrier()
; #define PG8_SCHED __builtin_amdgcn_sched_barrier(0)
; template <class Epi, class Sched, bool ALIGN_EPI = false, bool SP2 = false>
; __device__ __forceinline__ void gemm_phase(PG8_LAS unsigned char* lds, const Gemm g, const Sched& S, const Epi& E) {
;     ...
;             PG8_LDB(B0, 1, 0); PG8_LDB(B1, 1, 1); PG8_SCHED; PG8_LDA(At, 1, 0); PG8_STAGE(PG8_SA(0, 1), a2 + hstep, voffA);
;             PG8_WAIT_V(8); PG8_WAIT_L(0); PG8_BAR; PG8_MMA(0, 0, At, B0); PG8_MMA(0, 1, At, B1); PG8_BAR; PG8_SCHED;
;             PG8_LDA(At, 1, 1); PG8_STAGE(PG8_SB(1, 0), b3, voffB); PG8_STAGE(PG8_SB(1, 1), b3 + hstep, voffB); PG8_STAGE(PG8_SA(1, 0), a3, voffA);
;             PG8_WAIT_V(8); PG8_WAIT_L(0); PG8_BAR; PG8_MMA(1, 0, At, B0); PG8_MMA(1, 1, At, B1); PG8_BAR; PG8_SCHED;
	s_add_i32 s92, 0, 0x18000
	s_add_i32 s93, 0, 0x1c000
	v_add_u32_e32 v140, s92, v196
	v_add_u32_e32 v156, s93, v196
	ds_read_b128 v[128:131], v140
	ds_read_b128 v[132:135], v140 offset:1024
	ds_read_b128 v[136:139], v140 offset:2048
	ds_read_b128 v[140:143], v140 offset:3072
	ds_read_b128 v[144:147], v156
	ds_read_b128 v[148:151], v156 offset:1024
	ds_read_b128 v[152:155], v156 offset:2048
	ds_read_b128 v[156:159], v156 offset:3072
	s_add_u32 s44, s44, 0x80000
	s_addc_u32 s45, s45, 0
	s_mov_b32 m0, s65
	ds_read_b128 v[176:179], v200 offset:32768
	ds_read_b128 v[180:183], v200 offset:33792
	ds_read_b128 v[184:187], v200 offset:34816
	ds_read_b128 v[188:191], v200 offset:35840
	ds_read_b128 v[208:211], v200 offset:36864
	ds_read_b128 v[212:215], v200 offset:37888
	ds_read_b128 v[216:219], v200 offset:38912
	ds_read_b128 v[220:223], v200 offset:39936
	global_load_lds_dwordx4 v160, s[44:45]
	s_mov_b32 m0, s66
	s_nop 0
	global_load_lds_dwordx4 v164, s[44:45]
	s_waitcnt vmcnt(8)
	s_waitcnt lgkmcnt(0)
	v_mfma_f32_16x16x32_f16 v[120:123], v[136:139], v[176:179], v[120:123]
	v_mfma_f32_16x16x32_f16 v[124:127], v[128:131], v[176:179], v[124:127]
	v_mfma_f32_16x16x32_f16 v[104:107], v[136:139], v[184:187], v[104:107]
	v_mfma_f32_16x16x32_f16 v[108:111], v[128:131], v[184:187], v[108:111]
	s_barrier
	s_waitcnt lgkmcnt(0)
	v_mfma_f32_16x16x32_f16 v[88:91], v[136:139], v[208:211], v[88:91]
	v_mfma_f32_16x16x32_f16 v[92:95], v[128:131], v[208:211], v[92:95]
	v_mfma_f32_16x16x32_f16 v[72:75], v[136:139], v[216:219], v[72:75]
	v_mfma_f32_16x16x32_f16 v[76:79], v[128:131], v[216:219], v[76:79]
	v_mfma_f32_16x16x32_f16 v[120:123], v[140:143], v[180:183], v[120:123]
	v_mfma_f32_16x16x32_f16 v[124:127], v[132:135], v[180:183], v[124:127]
	v_mfma_f32_16x16x32_f16 v[104:107], v[140:143], v[188:191], v[104:107]
	v_mfma_f32_16x16x32_f16 v[108:111], v[132:135], v[188:191], v[108:111]
	v_mfma_f32_16x16x32_f16 v[88:91], v[140:143], v[212:215], v[88:91]
	v_mfma_f32_16x16x32_f16 v[92:95], v[132:135], v[212:215], v[92:95]
	v_mfma_f32_16x16x32_f16 v[72:75], v[140:143], v[220:223], v[72:75]
	v_mfma_f32_16x16x32_f16 v[76:79], v[132:135], v[220:223], v[76:79]
	v_mfma_f32_16x16x32_f16 v[112:115], v[152:155], v[176:179], v[112:115]
	v_mfma_f32_16x16x32_f16 v[116:119], v[144:147], v[176:179], v[116:119]
	v_mfma_f32_16x16x32_f16 v[96:99], v[152:155], v[184:187], v[96:99]
	v_mfma_f32_16x16x32_f16 v[100:103], v[144:147], v[184:187], v[100:103]
	v_mfma_f32_16x16x32_f16 v[80:83], v[152:155], v[208:211], v[80:83]
	v_mfma_f32_16x16x32_f16 v[84:87], v[144:147], v[208:211], v[84:87]
	v_mfma_f32_16x16x32_f16 v[64:67], v[152:155], v[216:219], v[64:67]
	v_mfma_f32_16x16x32_f16 v[68:71], v[144:147], v[216:219], v[68:71]
	v_mfma_f32_16x16x32_f16 v[112:115], v[156:159], v[180:183], v[112:115]
	v_mfma_f32_16x16x32_f16 v[116:119], v[148:151], v[180:183], v[116:119]
	v_mfma_f32_16x16x32_f16 v[96:99], v[156:159], v[188:191], v[96:99]
	v_mfma_f32_16x16x32_f16 v[100:103], v[148:151], v[188:191], v[100:103]
	v_mfma_f32_16x16x32_f16 v[80:83], v[156:159], v[212:215], v[80:83]
	v_mfma_f32_16x16x32_f16 v[84:87], v[148:151], v[212:215], v[84:87]
	v_mfma_f32_16x16x32_f16 v[64:67], v[156:159], v[220:223], v[64:67]
	v_mfma_f32_16x16x32_f16 v[68:71], v[148:151], v[220:223], v[68:71]
	s_barrier
	s_add_i32 s44, s92, s63
	s_mov_b32 m0, s44
	ds_read_b128 v[176:179], v200 offset:49152
	ds_read_b128 v[180:183], v200 offset:50176
	ds_read_b128 v[184:187], v200 offset:51200
	ds_read_b128 v[188:191], v200 offset:52224
	ds_read_b128 v[208:211], v200 offset:53248
	ds_read_b128 v[212:215], v200 offset:54272
	ds_read_b128 v[216:219], v200 offset:55296
	ds_read_b128 v[220:223], v200 offset:56320
	global_load_lds_dwordx4 v162, s[98:99]
	s_add_i32 m0, s44, 0x2000
	s_add_u32 s42, s42, 0x80080
	s_addc_u32 s43, s43, 0
	s_add_i32 s44, s93, s63
	global_load_lds_dwordx4 v166, s[98:99]
	s_mov_b32 m0, s44
	s_nop 0
	global_load_lds_dwordx4 v162, s[42:43]
	s_add_i32 m0, s44, 0x2000
	s_nop 0
	global_load_lds_dwordx4 v166, s[42:43]
	s_mov_b32 m0, s68
	s_nop 0
	global_load_lds_dwordx4 v160, s[100:101]
	s_mov_b32 m0, s69
	s_nop 0
	global_load_lds_dwordx4 v164, s[100:101]
	s_waitcnt vmcnt(8)
	s_waitcnt lgkmcnt(0)
	v_mfma_f32_16x16x32_f16 v[56:59], v[136:139], v[176:179], v[56:59]
	v_mfma_f32_16x16x32_f16 v[60:63], v[128:131], v[176:179], v[60:63]
	v_mfma_f32_16x16x32_f16 v[40:43], v[136:139], v[184:187], v[40:43]
	v_mfma_f32_16x16x32_f16 v[44:47], v[128:131], v[184:187], v[44:47]
	s_barrier
	s_waitcnt lgkmcnt(0)
	v_mfma_f32_16x16x32_f16 v[24:27], v[136:139], v[208:211], v[24:27]
	v_mfma_f32_16x16x32_f16 v[28:31], v[128:131], v[208:211], v[28:31]
	v_mfma_f32_16x16x32_f16 v[8:11], v[136:139], v[216:219], v[8:11]
	v_mfma_f32_16x16x32_f16 v[12:15], v[128:131], v[216:219], v[12:15]
	v_mfma_f32_16x16x32_f16 v[56:59], v[140:143], v[180:183], v[56:59]
	v_mfma_f32_16x16x32_f16 v[60:63], v[132:135], v[180:183], v[60:63]
	v_mfma_f32_16x16x32_f16 v[40:43], v[140:143], v[188:191], v[40:43]
	v_mfma_f32_16x16x32_f16 v[44:47], v[132:135], v[188:191], v[44:47]
	v_mfma_f32_16x16x32_f16 v[24:27], v[140:143], v[212:215], v[24:27]
	v_mfma_f32_16x16x32_f16 v[28:31], v[132:135], v[212:215], v[28:31]
	v_mfma_f32_16x16x32_f16 v[8:11], v[140:143], v[220:223], v[8:11]
	v_mfma_f32_16x16x32_f16 v[12:15], v[132:135], v[220:223], v[12:15]
	v_mfma_f32_16x16x32_f16 v[48:51], v[152:155], v[176:179], v[48:51]
	v_mfma_f32_16x16x32_f16 v[52:55], v[144:147], v[176:179], v[52:55]
	v_mfma_f32_16x16x32_f16 v[32:35], v[152:155], v[184:187], v[32:35]
	v_mfma_f32_16x16x32_f16 v[36:39], v[144:147], v[184:187], v[36:39]
	v_mfma_f32_16x16x32_f16 v[16:19], v[152:155], v[208:211], v[16:19]
	v_mfma_f32_16x16x32_f16 v[20:23], v[144:147], v[208:211], v[20:23]
	v_mfma_f32_16x16x32_f16 v[0:3], v[152:155], v[216:219], v[0:3]
	v_mfma_f32_16x16x32_f16 v[4:7], v[144:147], v[216:219], v[4:7]
	v_mfma_f32_16x16x32_f16 v[48:51], v[156:159], v[180:183], v[48:51]
	v_mfma_f32_16x16x32_f16 v[52:55], v[148:151], v[180:183], v[52:55]
	v_mfma_f32_16x16x32_f16 v[32:35], v[156:159], v[188:191], v[32:35]
	v_mfma_f32_16x16x32_f16 v[36:39], v[148:151], v[188:191], v[36:39]
	v_mfma_f32_16x16x32_f16 v[16:19], v[156:159], v[212:215], v[16:19]
	v_mfma_f32_16x16x32_f16 v[20:23], v[148:151], v[212:215], v[20:23]
	v_mfma_f32_16x16x32_f16 v[0:3], v[156:159], v[220:223], v[0:3]
	v_mfma_f32_16x16x32_f16 v[4:7], v[148:151], v[220:223], v[4:7]
	s_barrier
	s_add_i32 s91, s91, 2
	s_add_u32 s89, s89, 0x100
	s_addc_u32 s90, s90, 0
	s_add_u32 s40, s40, 0x100
	s_addc_u32 s41, s41, 0
	s_cmp_gt_u32 s91, 29
	s_cbranch_scc0 .LBB0_577
	s_and_b64 vcc, exec, s[18:19]
	s_cbranch_vccz .LBB0_580
	s_barrier

; #define PG8_STAGE(bufoff, gbase, voff) do { _Pragma("unroll") for (int _i = 0; _i < 2; ++_i) \
;         __builtin_amdgcn_global_load_lds((const unsigned*)((const char*)(gbase) + (voff)[_i]), (PG8_LAS unsigned*)(lds + (bufoff) + ldsw + _i * 8192), 16, 0, 0); } while (0)
; #define PG8_LDA(dst, b, h) do { _Pragma("unroll") for (int m = 0; m < 4; ++m) _Pragma("unroll") for (int k = 0; k < 2; ++k) dst[m][k] = *(const PG8_LAS bf16x8*)(lds + PG8_SA(b, h) + aoff + m * 2048 + k * 1024); } while (0)
; #define PG8_LDB(dst, b, h) do { _Pragma("unroll") for (int n = 0; n < 2; ++n) _Pragma("unroll") for (int k = 0; k < 2; ++k) dst[n][k] = *(const PG8_LAS bf16x8*)(lds + PG8_SB(b, h) + boff + n * 2048 + k * 1024); } while (0)
; #define PG8_MMA(ai, bj, At, Bt) do { __builtin_amdgcn_s_setprio(1); _Pragma("unroll") for (int m = 0; m < 4; ++m) _Pragma("unroll") for (int n = 0; n < 2; ++n) _Pragma("unroll") for (int k = 0; k < 2; ++k) \
;         acc[ai][bj][m][n] = __builtin_amdgcn_mfma_f32_16x16x32_f16(Bt[n][k], At[m][k], acc[ai][bj][m][n], 0, 0, 0); __builtin_amdgcn_s_setprio(0); } while (0)
; #define PG8_WAIT_V(n) asm volatile("s_waitcnt vmcnt(" #n ")" ::: "memory")
; #define PG8_WAIT_L(n) asm volatile("s_waitcnt lgkmcnt(" #n ")" ::: "memory")
; #define PG8_BAR __builtin_amdgcn_s_barrier()
; #define PG8_SCHED __builtin_amdgcn_sched_barrier(0)
; template <class Epi, class Sched, bool ALIGN_EPI = false, bool SP2 = false>
; __device__ __forceinline__ void gemm_phase(PG8_LAS unsigned char* lds, const Gemm g, const Sched& S, const Epi& E) {
;     ...
;             PG8_LDB(B0, 0, 0); PG8_LDB(B1, 0, 1); PG8_SCHED; PG8_LDA(At, 0, 0); PG8_STAGE(PG8_SA(1, 1), a1 + hstep, voffA);
;             PG8_WAIT_V(8); PG8_WAIT_L(0); PG8_BAR; PG8_MMA(0, 0, At, B0); PG8_MMA(0, 1, At, B1); PG8_BAR; PG8_SCHED;
;             PG8_LDA(At, 0, 1); PG8_STAGE(PG8_SB(0, 0), b2, voffB); PG8_STAGE(PG8_SB(0, 1), b2 + hstep, voffB); PG8_STAGE(PG8_SA(0, 0), a2, voffA);
;             PG8_WAIT_V(8); PG8_WAIT_L(0); PG8_BAR; PG8_MMA(1, 0, At, B0); PG8_MMA(1, 1, At, B1); PG8_BAR; PG8_SCHED;
.LBB0_655:
	ds_read_b128 v[128:131], v211
	ds_read_b128 v[132:135], v211 offset:1024
	ds_read_b128 v[136:139], v211 offset:2048
	ds_read_b128 v[140:143], v211 offset:3072
	ds_read_b128 v[144:147], v212
	ds_read_b128 v[148:151], v212 offset:1024
	ds_read_b128 v[152:155], v212 offset:2048
	ds_read_b128 v[156:159], v212 offset:3072
	s_add_u32 s42, s40, 0xffe00080
	s_addc_u32 s43, s41, -1
	s_cmpk_eq_i32 s86, 0x7c
	s_cselect_b32 s45, s29, s43
	s_cselect_b32 s44, s37, s42
	s_cselect_b32 s43, s27, s83
	s_cselect_b32 s42, s81, s82
	s_add_i32 m0, s39, 0xc000
	ds_read_b128 v[160:163], v213
	ds_read_b128 v[164:167], v213 offset:1024
	ds_read_b128 v[184:187], v213 offset:2048
	ds_read_b128 v[188:191], v213 offset:3072
	ds_read_b128 v[192:195], v213 offset:4096
	ds_read_b128 v[196:199], v213 offset:5120
	ds_read_b128 v[200:203], v213 offset:6144
	ds_read_b128 v[214:217], v213 offset:7168
	global_load_lds_dwordx4 v178, s[40:41]
	s_add_i32 m0, s39, 0xe000
	s_nop 0
	global_load_lds_dwordx4 v176, s[40:41]
	s_waitcnt vmcnt(8)
	s_waitcnt lgkmcnt(0)
	v_mfma_f32_16x16x32_f16 v[120:123], v[136:139], v[160:163], v[120:123]
	v_mfma_f32_16x16x32_f16 v[124:127], v[128:131], v[160:163], v[124:127]
	v_mfma_f32_16x16x32_f16 v[104:107], v[136:139], v[184:187], v[104:107]
	v_mfma_f32_16x16x32_f16 v[108:111], v[128:131], v[184:187], v[108:111]
	s_barrier
	s_waitcnt lgkmcnt(0)
	v_mfma_f32_16x16x32_f16 v[88:91], v[136:139], v[192:195], v[88:91]
	v_mfma_f32_16x16x32_f16 v[92:95], v[128:131], v[192:195], v[92:95]
	v_mfma_f32_16x16x32_f16 v[72:75], v[136:139], v[200:203], v[72:75]
	v_mfma_f32_16x16x32_f16 v[76:79], v[128:131], v[200:203], v[76:79]
	v_mfma_f32_16x16x32_f16 v[120:123], v[140:143], v[164:167], v[120:123]
	v_mfma_f32_16x16x32_f16 v[124:127], v[132:135], v[164:167], v[124:127]
	v_mfma_f32_16x16x32_f16 v[104:107], v[140:143], v[188:191], v[104:107]
	v_mfma_f32_16x16x32_f16 v[108:111], v[132:135], v[188:191], v[108:111]
	v_mfma_f32_16x16x32_f16 v[88:91], v[140:143], v[196:199], v[88:91]
	v_mfma_f32_16x16x32_f16 v[92:95], v[132:135], v[196:199], v[92:95]
	v_mfma_f32_16x16x32_f16 v[72:75], v[140:143], v[214:217], v[72:75]
	v_mfma_f32_16x16x32_f16 v[76:79], v[132:135], v[214:217], v[76:79]
	v_mfma_f32_16x16x32_f16 v[112:115], v[152:155], v[160:163], v[112:115]
	v_mfma_f32_16x16x32_f16 v[116:119], v[144:147], v[160:163], v[116:119]
	v_mfma_f32_16x16x32_f16 v[96:99], v[152:155], v[184:187], v[96:99]
	v_mfma_f32_16x16x32_f16 v[100:103], v[144:147], v[184:187], v[100:103]
	v_mfma_f32_16x16x32_f16 v[80:83], v[152:155], v[192:195], v[80:83]
	v_mfma_f32_16x16x32_f16 v[84:87], v[144:147], v[192:195], v[84:87]
	v_mfma_f32_16x16x32_f16 v[64:67], v[152:155], v[200:203], v[64:67]
	v_mfma_f32_16x16x32_f16 v[68:71], v[144:147], v[200:203], v[68:71]
	v_mfma_f32_16x16x32_f16 v[112:115], v[156:159], v[164:167], v[112:115]
	v_mfma_f32_16x16x32_f16 v[116:119], v[148:151], v[164:167], v[116:119]
	v_mfma_f32_16x16x32_f16 v[96:99], v[156:159], v[188:191], v[96:99]
	v_mfma_f32_16x16x32_f16 v[100:103], v[148:151], v[188:191], v[100:103]
	v_mfma_f32_16x16x32_f16 v[80:83], v[156:159], v[196:199], v[80:83]
	v_mfma_f32_16x16x32_f16 v[84:87], v[148:151], v[196:199], v[84:87]
	v_mfma_f32_16x16x32_f16 v[64:67], v[156:159], v[214:217], v[64:67]
	v_mfma_f32_16x16x32_f16 v[68:71], v[148:151], v[214:217], v[68:71]
	s_barrier
	s_add_i32 s87, s69, s61
	s_add_u32 s98, s42, s18
	s_addc_u32 s99, s43, s19
	s_mov_b32 m0, s87
	ds_read_b128 v[160:163], v213 offset:16384
	ds_read_b128 v[164:167], v213 offset:17408
	ds_read_b128 v[184:187], v213 offset:18432
	ds_read_b128 v[188:191], v213 offset:19456
	ds_read_b128 v[192:195], v213 offset:20480
	ds_read_b128 v[196:199], v213 offset:21504
	ds_read_b128 v[200:203], v213 offset:22528
	ds_read_b128 v[214:217], v213 offset:23552
	global_load_lds_dwordx4 v170, s[42:43]
	s_add_i32 m0, s87, 0x2000
	s_add_u32 s88, s42, 0x200000
	s_addc_u32 s89, s43, 0
	s_add_i32 s87, s74, s61
	global_load_lds_dwordx4 v174, s[42:43]
	s_mov_b32 m0, s87
	s_nop 0
	global_load_lds_dwordx4 v170, s[88:89]
	s_add_i32 m0, s87, 0x2000
	s_nop 0
	global_load_lds_dwordx4 v174, s[88:89]
	s_add_u32 s100, s44, s18
	s_addc_u32 s101, s45, s19
	s_mov_b32 m0, s39
	s_nop 0
	global_load_lds_dwordx4 v168, s[44:45]
	s_mov_b32 m0, s62
	s_nop 0
	global_load_lds_dwordx4 v172, s[44:45]
	s_waitcnt vmcnt(8)
	s_waitcnt lgkmcnt(0)
	v_mfma_f32_16x16x32_f16 v[56:59], v[136:139], v[160:163], v[56:59]
	v_mfma_f32_16x16x32_f16 v[60:63], v[128:131], v[160:163], v[60:63]
	v_mfma_f32_16x16x32_f16 v[40:43], v[136:139], v[184:187], v[40:43]
	v_mfma_f32_16x16x32_f16 v[44:47], v[128:131], v[184:187], v[44:47]
	s_barrier
	s_waitcnt lgkmcnt(0)
	v_mfma_f32_16x16x32_f16 v[24:27], v[136:139], v[192:195], v[24:27]
	v_mfma_f32_16x16x32_f16 v[28:31], v[128:131], v[192:195], v[28:31]
	v_mfma_f32_16x16x32_f16 v[8:11], v[136:139], v[200:203], v[8:11]
	v_mfma_f32_16x16x32_f16 v[12:15], v[128:131], v[200:203], v[12:15]
	v_mfma_f32_16x16x32_f16 v[56:59], v[140:143], v[164:167], v[56:59]
	v_mfma_f32_16x16x32_f16 v[60:63], v[132:135], v[164:167], v[60:63]
	v_mfma_f32_16x16x32_f16 v[40:43], v[140:143], v[188:191], v[40:43]
	v_mfma_f32_16x16x32_f16 v[44:47], v[132:135], v[188:191], v[44:47]
	v_mfma_f32_16x16x32_f16 v[24:27], v[140:143], v[196:199], v[24:27]
	v_mfma_f32_16x16x32_f16 v[28:31], v[132:135], v[196:199], v[28:31]
	v_mfma_f32_16x16x32_f16 v[8:11], v[140:143], v[214:217], v[8:11]
	v_mfma_f32_16x16x32_f16 v[12:15], v[132:135], v[214:217], v[12:15]
	v_mfma_f32_16x16x32_f16 v[48:51], v[152:155], v[160:163], v[48:51]
	v_mfma_f32_16x16x32_f16 v[52:55], v[144:147], v[160:163], v[52:55]
	v_mfma_f32_16x16x32_f16 v[32:35], v[152:155], v[184:187], v[32:35]
	v_mfma_f32_16x16x32_f16 v[36:39], v[144:147], v[184:187], v[36:39]
	v_mfma_f32_16x16x32_f16 v[16:19], v[152:155], v[192:195], v[16:19]
	v_mfma_f32_16x16x32_f16 v[20:23], v[144:147], v[192:195], v[20:23]
	v_mfma_f32_16x16x32_f16 v[0:3], v[152:155], v[200:203], v[0:3]
	v_mfma_f32_16x16x32_f16 v[4:7], v[144:147], v[200:203], v[4:7]
	v_mfma_f32_16x16x32_f16 v[48:51], v[156:159], v[164:167], v[48:51]
	v_mfma_f32_16x16x32_f16 v[52:55], v[148:151], v[164:167], v[52:55]
	v_mfma_f32_16x16x32_f16 v[32:35], v[156:159], v[188:191], v[32:35]
	v_mfma_f32_16x16x32_f16 v[36:39], v[148:151], v[188:191], v[36:39]
	v_mfma_f32_16x16x32_f16 v[16:19], v[156:159], v[196:199], v[16:19]
	v_mfma_f32_16x16x32_f16 v[20:23], v[148:151], v[196:199], v[20:23]
	v_mfma_f32_16x16x32_f16 v[0:3], v[156:159], v[214:217], v[0:3]
	v_mfma_f32_16x16x32_f16 v[4:7], v[148:151], v[214:217], v[4:7]
	s_barrier
; #define PG8_STAGE(bufoff, gbase, voff) do { _Pragma("unroll") for (int _i = 0; _i < 2; ++_i) \
;         __builtin_amdgcn_global_load_lds((const unsigned*)((const char*)(gbase) + (voff)[_i]), (PG8_LAS unsigned*)(lds + (bufoff) + ldsw + _i * 8192), 16, 0, 0); } while (0)
; #define PG8_LDA(dst, b, h) do { _Pragma("unroll") for (int m = 0; m < 4; ++m) _Pragma("unroll") for (int k = 0; k < 2; ++k) dst[m][k] = *(const PG8_LAS bf16x8*)(lds + PG8_SA(b, h) + aoff + m * 2048 + k * 1024); } while (0)
; #define PG8_LDB(dst, b, h) do { _Pragma("unroll") for (int n = 0; n < 2; ++n) _Pragma("unroll") for (int k = 0; k < 2; ++k) dst[n][k] = *(const PG8_LAS bf16x8*)(lds + PG8_SB(b, h) + boff + n * 2048 + k * 1024); } while (0)
; #define PG8_MMA(ai, bj, At, Bt) do { __builtin_amdgcn_s_setprio(1); _Pragma("unroll") for (int m = 0; m < 4; ++m) _Pragma("unroll") for (int n = 0; n < 2; ++n) _Pragma("unroll") for (int k = 0; k < 2; ++k) \
;         acc[ai][bj][m][n] = __builtin_amdgcn_mfma_f32_16x16x32_f16(Bt[n][k], At[m][k], acc[ai][bj][m][n], 0, 0, 0); __builtin_amdgcn_s_setprio(0); } while (0)
; #define PG8_WAIT_V(n) asm volatile("s_waitcnt vmcnt(" #n ")" ::: "memory")
; #define PG8_WAIT_L(n) asm volatile("s_waitcnt lgkmcnt(" #n ")" ::: "memory")
; #define PG8_BAR __builtin_amdgcn_s_barrier()
; #define PG8_SCHED __builtin_amdgcn_sched_barrier(0)
; template <class Epi, class Sched, bool ALIGN_EPI = false, bool SP2 = false>
; __device__ __forceinline__ void gemm_phase(PG8_LAS unsigned char* lds, const Gemm g, const Sched& S, const Epi& E) {
;     ...
;             PG8_LDB(B0, 1, 0); PG8_LDB(B1, 1, 1); PG8_SCHED; PG8_LDA(At, 1, 0); PG8_STAGE(PG8_SA(0, 1), a2 + hstep, voffA);
;             PG8_WAIT_V(8); PG8_WAIT_L(0); PG8_BAR; PG8_MMA(0, 0, At, B0); PG8_MMA(0, 1, At, B1); PG8_BAR; PG8_SCHED;
;             PG8_LDA(At, 1, 1); PG8_STAGE(PG8_SB(1, 0), b3, voffB); PG8_STAGE(PG8_SB(1, 1), b3 + hstep, voffB); PG8_STAGE(PG8_SA(1, 0), a3, voffA);
;             PG8_WAIT_V(8); PG8_WAIT_L(0); PG8_BAR; PG8_MMA(1, 0, At, B0); PG8_MMA(1, 1, At, B1); PG8_BAR; PG8_SCHED;
	s_add_i32 s87, 0, 0x18000
	s_add_i32 s88, 0, 0x1c000
	v_add_u32_e32 v140, s87, v209
	v_add_u32_e32 v156, s88, v209
	ds_read_b128 v[128:131], v140
	ds_read_b128 v[132:135], v140 offset:1024
	ds_read_b128 v[136:139], v140 offset:2048
	ds_read_b128 v[140:143], v140 offset:3072
	ds_read_b128 v[144:147], v156
	ds_read_b128 v[148:151], v156 offset:1024
	ds_read_b128 v[152:155], v156 offset:2048
	ds_read_b128 v[156:159], v156 offset:3072
	s_add_u32 s44, s44, 0x200000
	s_addc_u32 s45, s45, 0
	s_mov_b32 m0, s63
	ds_read_b128 v[160:163], v213 offset:32768
	ds_read_b128 v[164:167], v213 offset:33792
	ds_read_b128 v[184:187], v213 offset:34816
	ds_read_b128 v[188:191], v213 offset:35840
	ds_read_b128 v[192:195], v213 offset:36864
	ds_read_b128 v[196:199], v213 offset:37888
	ds_read_b128 v[200:203], v213 offset:38912
	ds_read_b128 v[214:217], v213 offset:39936
	global_load_lds_dwordx4 v168, s[44:45]
	s_mov_b32 m0, s64
	s_nop 0
	global_load_lds_dwordx4 v172, s[44:45]
	s_waitcnt vmcnt(8)
	s_waitcnt lgkmcnt(0)
	v_mfma_f32_16x16x32_f16 v[120:123], v[136:139], v[160:163], v[120:123]
	v_mfma_f32_16x16x32_f16 v[124:127], v[128:131], v[160:163], v[124:127]
	v_mfma_f32_16x16x32_f16 v[104:107], v[136:139], v[184:187], v[104:107]
	v_mfma_f32_16x16x32_f16 v[108:111], v[128:131], v[184:187], v[108:111]
	s_barrier
	s_waitcnt lgkmcnt(0)
	v_mfma_f32_16x16x32_f16 v[88:91], v[136:139], v[192:195], v[88:91]
	v_mfma_f32_16x16x32_f16 v[92:95], v[128:131], v[192:195], v[92:95]
	v_mfma_f32_16x16x32_f16 v[72:75], v[136:139], v[200:203], v[72:75]
	v_mfma_f32_16x16x32_f16 v[76:79], v[128:131], v[200:203], v[76:79]
	v_mfma_f32_16x16x32_f16 v[120:123], v[140:143], v[164:167], v[120:123]
	v_mfma_f32_16x16x32_f16 v[124:127], v[132:135], v[164:167], v[124:127]
	v_mfma_f32_16x16x32_f16 v[104:107], v[140:143], v[188:191], v[104:107]
	v_mfma_f32_16x16x32_f16 v[108:111], v[132:135], v[188:191], v[108:111]
	v_mfma_f32_16x16x32_f16 v[88:91], v[140:143], v[196:199], v[88:91]
	v_mfma_f32_16x16x32_f16 v[92:95], v[132:135], v[196:199], v[92:95]
	v_mfma_f32_16x16x32_f16 v[72:75], v[140:143], v[214:217], v[72:75]
	v_mfma_f32_16x16x32_f16 v[76:79], v[132:135], v[214:217], v[76:79]
	v_mfma_f32_16x16x32_f16 v[112:115], v[152:155], v[160:163], v[112:115]
	v_mfma_f32_16x16x32_f16 v[116:119], v[144:147], v[160:163], v[116:119]
	v_mfma_f32_16x16x32_f16 v[96:99], v[152:155], v[184:187], v[96:99]
	v_mfma_f32_16x16x32_f16 v[100:103], v[144:147], v[184:187], v[100:103]
	v_mfma_f32_16x16x32_f16 v[80:83], v[152:155], v[192:195], v[80:83]
	v_mfma_f32_16x16x32_f16 v[84:87], v[144:147], v[192:195], v[84:87]
	v_mfma_f32_16x16x32_f16 v[64:67], v[152:155], v[200:203], v[64:67]
	v_mfma_f32_16x16x32_f16 v[68:71], v[144:147], v[200:203], v[68:71]
	v_mfma_f32_16x16x32_f16 v[112:115], v[156:159], v[164:167], v[112:115]
	v_mfma_f32_16x16x32_f16 v[116:119], v[148:151], v[164:167], v[116:119]
	v_mfma_f32_16x16x32_f16 v[96:99], v[156:159], v[188:191], v[96:99]
	v_mfma_f32_16x16x32_f16 v[100:103], v[148:151], v[188:191], v[100:103]
	v_mfma_f32_16x16x32_f16 v[80:83], v[156:159], v[196:199], v[80:83]
	v_mfma_f32_16x16x32_f16 v[84:87], v[148:151], v[196:199], v[84:87]
	v_mfma_f32_16x16x32_f16 v[64:67], v[156:159], v[214:217], v[64:67]
	v_mfma_f32_16x16x32_f16 v[68:71], v[148:151], v[214:217], v[68:71]
	s_barrier
	s_add_i32 s44, s87, s61
	s_mov_b32 m0, s44
	ds_read_b128 v[160:163], v213 offset:49152
	ds_read_b128 v[164:167], v213 offset:50176
	ds_read_b128 v[184:187], v213 offset:51200
	ds_read_b128 v[188:191], v213 offset:52224
	ds_read_b128 v[192:195], v213 offset:53248
	ds_read_b128 v[196:199], v213 offset:54272
	ds_read_b128 v[200:203], v213 offset:55296
	ds_read_b128 v[214:217], v213 offset:56320
	global_load_lds_dwordx4 v170, s[98:99]
	s_add_i32 m0, s44, 0x2000
	s_add_u32 s42, s42, 0x200080
	s_addc_u32 s43, s43, 0
	s_add_i32 s44, s88, s61
	global_load_lds_dwordx4 v174, s[98:99]
	s_mov_b32 m0, s44
	s_nop 0
	global_load_lds_dwordx4 v170, s[42:43]
	s_add_i32 m0, s44, 0x2000
	s_nop 0
	global_load_lds_dwordx4 v174, s[42:43]
	s_mov_b32 m0, s66
	s_nop 0
	global_load_lds_dwordx4 v168, s[100:101]
	s_mov_b32 m0, s67
	s_nop 0
	global_load_lds_dwordx4 v172, s[100:101]
	s_waitcnt vmcnt(8)
	s_waitcnt lgkmcnt(0)
	v_mfma_f32_16x16x32_f16 v[56:59], v[136:139], v[160:163], v[56:59]
	v_mfma_f32_16x16x32_f16 v[60:63], v[128:131], v[160:163], v[60:63]
	v_mfma_f32_16x16x32_f16 v[40:43], v[136:139], v[184:187], v[40:43]
	v_mfma_f32_16x16x32_f16 v[44:47], v[128:131], v[184:187], v[44:47]
	s_barrier
	s_waitcnt lgkmcnt(0)
	v_mfma_f32_16x16x32_f16 v[24:27], v[136:139], v[192:195], v[24:27]
	v_mfma_f32_16x16x32_f16 v[28:31], v[128:131], v[192:195], v[28:31]
	v_mfma_f32_16x16x32_f16 v[8:11], v[136:139], v[200:203], v[8:11]
	v_mfma_f32_16x16x32_f16 v[12:15], v[128:131], v[200:203], v[12:15]
	v_mfma_f32_16x16x32_f16 v[56:59], v[140:143], v[164:167], v[56:59]
	v_mfma_f32_16x16x32_f16 v[60:63], v[132:135], v[164:167], v[60:63]
	v_mfma_f32_16x16x32_f16 v[40:43], v[140:143], v[188:191], v[40:43]
	v_mfma_f32_16x16x32_f16 v[44:47], v[132:135], v[188:191], v[44:47]
	v_mfma_f32_16x16x32_f16 v[24:27], v[140:143], v[196:199], v[24:27]
	v_mfma_f32_16x16x32_f16 v[28:31], v[132:135], v[196:199], v[28:31]
	v_mfma_f32_16x16x32_f16 v[8:11], v[140:143], v[214:217], v[8:11]
	v_mfma_f32_16x16x32_f16 v[12:15], v[132:135], v[214:217], v[12:15]
	v_mfma_f32_16x16x32_f16 v[48:51], v[152:155], v[160:163], v[48:51]
	v_mfma_f32_16x16x32_f16 v[52:55], v[144:147], v[160:163], v[52:55]
	v_mfma_f32_16x16x32_f16 v[32:35], v[152:155], v[184:187], v[32:35]
	v_mfma_f32_16x16x32_f16 v[36:39], v[144:147], v[184:187], v[36:39]
	v_mfma_f32_16x16x32_f16 v[16:19], v[152:155], v[192:195], v[16:19]
	v_mfma_f32_16x16x32_f16 v[20:23], v[144:147], v[192:195], v[20:23]
	v_mfma_f32_16x16x32_f16 v[0:3], v[152:155], v[200:203], v[0:3]
	v_mfma_f32_16x16x32_f16 v[4:7], v[144:147], v[200:203], v[4:7]
	v_mfma_f32_16x16x32_f16 v[48:51], v[156:159], v[164:167], v[48:51]
	v_mfma_f32_16x16x32_f16 v[52:55], v[148:151], v[164:167], v[52:55]
	v_mfma_f32_16x16x32_f16 v[32:35], v[156:159], v[188:191], v[32:35]
	v_mfma_f32_16x16x32_f16 v[36:39], v[148:151], v[188:191], v[36:39]
	v_mfma_f32_16x16x32_f16 v[16:19], v[156:159], v[196:199], v[16:19]
	v_mfma_f32_16x16x32_f16 v[20:23], v[148:151], v[196:199], v[20:23]
	v_mfma_f32_16x16x32_f16 v[0:3], v[156:159], v[214:217], v[0:3]
	v_mfma_f32_16x16x32_f16 v[4:7], v[148:151], v[214:217], v[4:7]
	s_barrier
	s_add_i32 s86, s86, 2
	s_add_u32 s82, s82, 0x100
	s_addc_u32 s83, s83, 0
	s_add_u32 s40, s40, 0x100
	s_addc_u32 s41, s41, 0
	s_cmpk_gt_u32 s86, 0x7d
	s_cbranch_scc0 .LBB0_655
	s_and_b64 vcc, exec, s[20:21]
	s_cbranch_vccz .LBB0_658
	s_barrier

; #define PG8_STAGE(bufoff, gbase, voff) do { _Pragma("unroll") for (int _i = 0; _i < 2; ++_i) \
;         __builtin_amdgcn_global_load_lds((const unsigned*)((const char*)(gbase) + (voff)[_i]), (PG8_LAS unsigned*)(lds + (bufoff) + ldsw + _i * 8192), 16, 0, 0); } while (0)
; #define PG8_LDA(dst, b, h) do { _Pragma("unroll") for (int m = 0; m < 4; ++m) _Pragma("unroll") for (int k = 0; k < 2; ++k) dst[m][k] = *(const PG8_LAS bf16x8*)(lds + PG8_SA(b, h) + aoff + m * 2048 + k * 1024); } while (0)
; #define PG8_LDB(dst, b, h) do { _Pragma("unroll") for (int n = 0; n < 2; ++n) _Pragma("unroll") for (int k = 0; k < 2; ++k) dst[n][k] = *(const PG8_LAS bf16x8*)(lds + PG8_SB(b, h) + boff + n * 2048 + k * 1024); } while (0)
; #define PG8_MMA(ai, bj, At, Bt) do { __builtin_amdgcn_s_setprio(1); _Pragma("unroll") for (int m = 0; m < 4; ++m) _Pragma("unroll") for (int n = 0; n < 2; ++n) _Pragma("unroll") for (int k = 0; k < 2; ++k) \
;         acc[ai][bj][m][n] = __builtin_amdgcn_mfma_f32_16x16x32_f16(Bt[n][k], At[m][k], acc[ai][bj][m][n], 0, 0, 0); __builtin_amdgcn_s_setprio(0); } while (0)
; #define PG8_WAIT_V(n) asm volatile("s_waitcnt vmcnt(" #n ")" ::: "memory")
; #define PG8_WAIT_L(n) asm volatile("s_waitcnt lgkmcnt(" #n ")" ::: "memory")
; template <class Epi, class Sched, bool ALIGN_EPI = false, bool SP2 = false>
; __device__ __forceinline__ void gemm_phase(PG8_LAS unsigned char* lds, const Gemm g, const Sched& S, const Epi& E) {
;     ...
;             const bool last = (t == nt - 2);
;             const char* a1 = cA + (size_t)(t + 1) * kstep;
;             const char* a2 = last ? nA : cA + (size_t)(t + 2) * kstep; const char* b2 = last ? nB : cB + (size_t)(t + 2) * kstep;
;             const char* a3 = a2 + kstep; const char* b3 = b2 + kstep;
;             if (last && has_next) S.a_ready(nxt);
;             if constexpr (SP2) {
;             PG8_LDB(B0, 0, 0); PG8_LDB(B1, 0, 1); PG8_SCHED; PG8_LDA(At, 0, 0); PG8_STAGE(PG8_SA(1, 1), a1 + hstep, voffA);
;             PG8_WAIT_V(8); PG8_WAIT_L(0); PG8_BAR; PG8_MMA(0, 0, At, B0); PG8_MMA(0, 1, At, B1); PG8_BAR; PG8_SCHED;
;             PG8_LDA(At, 0, 1); PG8_STAGE(PG8_SB(0, 0), b2, voffB); PG8_STAGE(PG8_SB(0, 1), b2 + hstep, voffB); PG8_STAGE(PG8_SA(0, 0), a2, voffA);
;             PG8_WAIT_V(8); PG8_WAIT_L(0); PG8_BAR; PG8_MMA(1, 0, At, B0); PG8_MMA(1, 1, At, B1); PG8_BAR; PG8_SCHED;
.LBB0_747:
	ds_read_b128 v[128:131], v191
	ds_read_b128 v[132:135], v191 offset:1024
	ds_read_b128 v[136:139], v191 offset:2048
	ds_read_b128 v[140:143], v191 offset:3072
	ds_read_b128 v[144:147], v192
	ds_read_b128 v[148:151], v192 offset:1024
	ds_read_b128 v[152:155], v192 offset:2048
	ds_read_b128 v[156:159], v192 offset:3072
	s_add_u32 s48, s44, 0xfff80080
	s_addc_u32 s49, s45, -1
	s_cmp_eq_u32 s90, 28
	s_cselect_b32 s51, s37, s49
	s_cselect_b32 s50, s86, s48
	s_cselect_b32 s49, s35, s89
	s_cselect_b32 s48, s87, s88
	s_add_i32 m0, s43, 0xc000
	ds_read_b128 v[176:179], v193
	ds_read_b128 v[180:183], v193 offset:1024
	ds_read_b128 v[184:187], v193 offset:2048
	ds_read_b128 v[194:197], v193 offset:3072
	ds_read_b128 v[198:201], v193 offset:4096
	ds_read_b128 v[208:211], v193 offset:5120
	ds_read_b128 v[212:215], v193 offset:6144
	ds_read_b128 v[216:219], v193 offset:7168
	global_load_lds_dwordx4 v170, s[44:45]
	s_add_i32 m0, s43, 0xe000
	s_nop 0
	global_load_lds_dwordx4 v168, s[44:45]
	s_waitcnt vmcnt(8)
	s_waitcnt lgkmcnt(0)
	v_mfma_f32_16x16x32_f16 v[120:123], v[136:139], v[176:179], v[120:123]
	v_mfma_f32_16x16x32_f16 v[124:127], v[128:131], v[176:179], v[124:127]
	v_mfma_f32_16x16x32_f16 v[104:107], v[136:139], v[184:187], v[104:107]
	v_mfma_f32_16x16x32_f16 v[112:115], v[128:131], v[184:187], v[112:115]
	s_barrier
	s_waitcnt lgkmcnt(0)
	v_mfma_f32_16x16x32_f16 v[88:91], v[136:139], v[198:201], v[88:91]
	v_mfma_f32_16x16x32_f16 v[96:99], v[128:131], v[198:201], v[96:99]
	v_mfma_f32_16x16x32_f16 v[72:75], v[136:139], v[212:215], v[72:75]
	v_mfma_f32_16x16x32_f16 v[80:83], v[128:131], v[212:215], v[80:83]
	v_mfma_f32_16x16x32_f16 v[120:123], v[140:143], v[180:183], v[120:123]
	v_mfma_f32_16x16x32_f16 v[124:127], v[132:135], v[180:183], v[124:127]
	v_mfma_f32_16x16x32_f16 v[104:107], v[140:143], v[194:197], v[104:107]
	v_mfma_f32_16x16x32_f16 v[112:115], v[132:135], v[194:197], v[112:115]
	v_mfma_f32_16x16x32_f16 v[88:91], v[140:143], v[208:211], v[88:91]
	v_mfma_f32_16x16x32_f16 v[96:99], v[132:135], v[208:211], v[96:99]
	v_mfma_f32_16x16x32_f16 v[72:75], v[140:143], v[216:219], v[72:75]
	v_mfma_f32_16x16x32_f16 v[80:83], v[132:135], v[216:219], v[80:83]
	v_mfma_f32_16x16x32_f16 v[108:111], v[152:155], v[176:179], v[108:111]
	v_mfma_f32_16x16x32_f16 v[116:119], v[144:147], v[176:179], v[116:119]
	v_mfma_f32_16x16x32_f16 v[92:95], v[152:155], v[184:187], v[92:95]
	v_mfma_f32_16x16x32_f16 v[100:103], v[144:147], v[184:187], v[100:103]
	v_mfma_f32_16x16x32_f16 v[76:79], v[152:155], v[198:201], v[76:79]
	v_mfma_f32_16x16x32_f16 v[84:87], v[144:147], v[198:201], v[84:87]
	v_mfma_f32_16x16x32_f16 v[64:67], v[152:155], v[212:215], v[64:67]
	v_mfma_f32_16x16x32_f16 v[68:71], v[144:147], v[212:215], v[68:71]
	v_mfma_f32_16x16x32_f16 v[108:111], v[156:159], v[180:183], v[108:111]
	v_mfma_f32_16x16x32_f16 v[116:119], v[148:151], v[180:183], v[116:119]
	v_mfma_f32_16x16x32_f16 v[92:95], v[156:159], v[194:197], v[92:95]
	v_mfma_f32_16x16x32_f16 v[100:103], v[148:151], v[194:197], v[100:103]
	v_mfma_f32_16x16x32_f16 v[76:79], v[156:159], v[208:211], v[76:79]
	v_mfma_f32_16x16x32_f16 v[84:87], v[148:151], v[208:211], v[84:87]
	v_mfma_f32_16x16x32_f16 v[64:67], v[156:159], v[216:219], v[64:67]
	v_mfma_f32_16x16x32_f16 v[68:71], v[148:151], v[216:219], v[68:71]
	s_barrier
	s_add_i32 s91, s68, s61
	s_add_u32 s98, s48, s18
	s_addc_u32 s99, s49, s19
	s_mov_b32 m0, s91
	ds_read_b128 v[176:179], v193 offset:16384
	ds_read_b128 v[180:183], v193 offset:17408
	ds_read_b128 v[184:187], v193 offset:18432
	ds_read_b128 v[194:197], v193 offset:19456
	ds_read_b128 v[198:201], v193 offset:20480
	ds_read_b128 v[208:211], v193 offset:21504
	ds_read_b128 v[212:215], v193 offset:22528
	ds_read_b128 v[216:219], v193 offset:23552
	global_load_lds_dwordx4 v162, s[48:49]
	s_add_i32 m0, s91, 0x2000
	s_add_u32 s92, s48, 0x80000
	s_addc_u32 s93, s49, 0
	s_add_i32 s91, s69, s61
	global_load_lds_dwordx4 v166, s[48:49]
	s_mov_b32 m0, s91
	s_nop 0
	global_load_lds_dwordx4 v162, s[92:93]
	s_add_i32 m0, s91, 0x2000
	s_nop 0
	global_load_lds_dwordx4 v166, s[92:93]
	s_add_u32 s100, s50, s18
	s_addc_u32 s101, s51, s19
	s_mov_b32 m0, s43
	s_nop 0
	global_load_lds_dwordx4 v160, s[50:51]
	s_mov_b32 m0, s62
	s_nop 0
	global_load_lds_dwordx4 v164, s[50:51]
	s_waitcnt vmcnt(8)
	s_waitcnt lgkmcnt(0)
	v_mfma_f32_16x16x32_f16 v[56:59], v[136:139], v[176:179], v[56:59]
	v_mfma_f32_16x16x32_f16 v[60:63], v[128:131], v[176:179], v[60:63]
	v_mfma_f32_16x16x32_f16 v[44:47], v[136:139], v[184:187], v[44:47]
	v_mfma_f32_16x16x32_f16 v[52:55], v[128:131], v[184:187], v[52:55]
	s_barrier
	s_waitcnt lgkmcnt(0)
	v_mfma_f32_16x16x32_f16 v[28:31], v[136:139], v[198:201], v[28:31]
	v_mfma_f32_16x16x32_f16 v[36:39], v[128:131], v[198:201], v[36:39]
	v_mfma_f32_16x16x32_f16 v[12:15], v[136:139], v[212:215], v[12:15]
	v_mfma_f32_16x16x32_f16 v[20:23], v[128:131], v[212:215], v[20:23]
	v_mfma_f32_16x16x32_f16 v[56:59], v[140:143], v[180:183], v[56:59]
	v_mfma_f32_16x16x32_f16 v[60:63], v[132:135], v[180:183], v[60:63]
	v_mfma_f32_16x16x32_f16 v[44:47], v[140:143], v[194:197], v[44:47]
	v_mfma_f32_16x16x32_f16 v[52:55], v[132:135], v[194:197], v[52:55]
	v_mfma_f32_16x16x32_f16 v[28:31], v[140:143], v[208:211], v[28:31]
	v_mfma_f32_16x16x32_f16 v[36:39], v[132:135], v[208:211], v[36:39]
	v_mfma_f32_16x16x32_f16 v[12:15], v[140:143], v[216:219], v[12:15]
	v_mfma_f32_16x16x32_f16 v[20:23], v[132:135], v[216:219], v[20:23]
	v_mfma_f32_16x16x32_f16 v[40:43], v[152:155], v[176:179], v[40:43]
	v_mfma_f32_16x16x32_f16 v[48:51], v[144:147], v[176:179], v[48:51]
	v_mfma_f32_16x16x32_f16 v[24:27], v[152:155], v[184:187], v[24:27]
	v_mfma_f32_16x16x32_f16 v[32:35], v[144:147], v[184:187], v[32:35]
	v_mfma_f32_16x16x32_f16 v[8:11], v[152:155], v[198:201], v[8:11]
	v_mfma_f32_16x16x32_f16 v[16:19], v[144:147], v[198:201], v[16:19]
	v_mfma_f32_16x16x32_f16 v[0:3], v[152:155], v[212:215], v[0:3]
	v_mfma_f32_16x16x32_f16 v[4:7], v[144:147], v[212:215], v[4:7]
	v_mfma_f32_16x16x32_f16 v[40:43], v[156:159], v[180:183], v[40:43]
	v_mfma_f32_16x16x32_f16 v[48:51], v[148:151], v[180:183], v[48:51]
	v_mfma_f32_16x16x32_f16 v[24:27], v[156:159], v[194:197], v[24:27]
	v_mfma_f32_16x16x32_f16 v[32:35], v[148:151], v[194:197], v[32:35]
	v_mfma_f32_16x16x32_f16 v[8:11], v[156:159], v[208:211], v[8:11]
	v_mfma_f32_16x16x32_f16 v[16:19], v[148:151], v[208:211], v[16:19]
	v_mfma_f32_16x16x32_f16 v[0:3], v[156:159], v[216:219], v[0:3]
	v_mfma_f32_16x16x32_f16 v[4:7], v[148:151], v[216:219], v[4:7]
	s_barrier
; #define PG8_STAGE(bufoff, gbase, voff) do { _Pragma("unroll") for (int _i = 0; _i < 2; ++_i) \
;         __builtin_amdgcn_global_load_lds((const unsigned*)((const char*)(gbase) + (voff)[_i]), (PG8_LAS unsigned*)(lds + (bufoff) + ldsw + _i * 8192), 16, 0, 0); } while (0)
; #define PG8_LDA(dst, b, h) do { _Pragma("unroll") for (int m = 0; m < 4; ++m) _Pragma("unroll") for (int k = 0; k < 2; ++k) dst[m][k] = *(const PG8_LAS bf16x8*)(lds + PG8_SA(b, h) + aoff + m * 2048 + k * 1024); } while (0)
; #define PG8_LDB(dst, b, h) do { _Pragma("unroll") for (int n = 0; n < 2; ++n) _Pragma("unroll") for (int k = 0; k < 2; ++k) dst[n][k] = *(const PG8_LAS bf16x8*)(lds + PG8_SB(b, h) + boff + n * 2048 + k * 1024); } while (0)
; #define PG8_MMA(ai, bj, At, Bt) do { __builtin_amdgcn_s_setprio(1); _Pragma("unroll") for (int m = 0; m < 4; ++m) _Pragma("unroll") for (int n = 0; n < 2; ++n) _Pragma("unroll") for (int k = 0; k < 2; ++k) \
;         acc[ai][bj][m][n] = __builtin_amdgcn_mfma_f32_16x16x32_f16(Bt[n][k], At[m][k], acc[ai][bj][m][n], 0, 0, 0); __builtin_amdgcn_s_setprio(0); } while (0)
; #define PG8_WAIT_V(n) asm volatile("s_waitcnt vmcnt(" #n ")" ::: "memory")
; #define PG8_WAIT_L(n) asm volatile("s_waitcnt lgkmcnt(" #n ")" ::: "memory")
; #define PG8_BAR __builtin_amdgcn_s_barrier()
; #define PG8_SCHED __builtin_amdgcn_sched_barrier(0)
; template <class Epi, class Sched, bool ALIGN_EPI = false, bool SP2 = false>
; __device__ __forceinline__ void gemm_phase(PG8_LAS unsigned char* lds, const Gemm g, const Sched& S, const Epi& E) {
;     ...
;             PG8_LDB(B0, 1, 0); PG8_LDB(B1, 1, 1); PG8_SCHED; PG8_LDA(At, 1, 0); PG8_STAGE(PG8_SA(0, 1), a2 + hstep, voffA);
;             PG8_WAIT_V(8); PG8_WAIT_L(0); PG8_BAR; PG8_MMA(0, 0, At, B0); PG8_MMA(0, 1, At, B1); PG8_BAR; PG8_SCHED;
;             PG8_LDA(At, 1, 1); PG8_STAGE(PG8_SB(1, 0), b3, voffB); PG8_STAGE(PG8_SB(1, 1), b3 + hstep, voffB); PG8_STAGE(PG8_SA(1, 0), a3, voffA);
;             PG8_WAIT_V(8); PG8_WAIT_L(0); PG8_BAR; PG8_MMA(1, 0, At, B0); PG8_MMA(1, 1, At, B1); PG8_BAR; PG8_SCHED;
	s_add_i32 s91, 0, 0x18000
	s_add_i32 s92, 0, 0x1c000
	v_add_u32_e32 v140, s91, v189
	v_add_u32_e32 v156, s92, v189
	ds_read_b128 v[128:131], v140
	ds_read_b128 v[132:135], v140 offset:1024
	ds_read_b128 v[136:139], v140 offset:2048
	ds_read_b128 v[140:143], v140 offset:3072
	ds_read_b128 v[144:147], v156
	ds_read_b128 v[148:151], v156 offset:1024
	ds_read_b128 v[152:155], v156 offset:2048
	ds_read_b128 v[156:159], v156 offset:3072
	s_add_u32 s50, s50, 0x80000
	s_addc_u32 s51, s51, 0
	s_mov_b32 m0, s63
	ds_read_b128 v[176:179], v193 offset:32768
	ds_read_b128 v[180:183], v193 offset:33792
	ds_read_b128 v[184:187], v193 offset:34816
	ds_read_b128 v[194:197], v193 offset:35840
	ds_read_b128 v[198:201], v193 offset:36864
	ds_read_b128 v[208:211], v193 offset:37888
	ds_read_b128 v[212:215], v193 offset:38912
	ds_read_b128 v[216:219], v193 offset:39936
	global_load_lds_dwordx4 v160, s[50:51]
	s_mov_b32 m0, s64
	s_nop 0
	global_load_lds_dwordx4 v164, s[50:51]
	s_waitcnt vmcnt(8)
	s_waitcnt lgkmcnt(0)
	v_mfma_f32_16x16x32_f16 v[120:123], v[136:139], v[176:179], v[120:123]
	v_mfma_f32_16x16x32_f16 v[124:127], v[128:131], v[176:179], v[124:127]
	v_mfma_f32_16x16x32_f16 v[104:107], v[136:139], v[184:187], v[104:107]
	v_mfma_f32_16x16x32_f16 v[112:115], v[128:131], v[184:187], v[112:115]
	s_barrier
	s_waitcnt lgkmcnt(0)
	v_mfma_f32_16x16x32_f16 v[88:91], v[136:139], v[198:201], v[88:91]
	v_mfma_f32_16x16x32_f16 v[96:99], v[128:131], v[198:201], v[96:99]
	v_mfma_f32_16x16x32_f16 v[72:75], v[136:139], v[212:215], v[72:75]
	v_mfma_f32_16x16x32_f16 v[80:83], v[128:131], v[212:215], v[80:83]
	v_mfma_f32_16x16x32_f16 v[120:123], v[140:143], v[180:183], v[120:123]
	v_mfma_f32_16x16x32_f16 v[124:127], v[132:135], v[180:183], v[124:127]
	v_mfma_f32_16x16x32_f16 v[104:107], v[140:143], v[194:197], v[104:107]
	v_mfma_f32_16x16x32_f16 v[112:115], v[132:135], v[194:197], v[112:115]
	v_mfma_f32_16x16x32_f16 v[88:91], v[140:143], v[208:211], v[88:91]
	v_mfma_f32_16x16x32_f16 v[96:99], v[132:135], v[208:211], v[96:99]
	v_mfma_f32_16x16x32_f16 v[72:75], v[140:143], v[216:219], v[72:75]
	v_mfma_f32_16x16x32_f16 v[80:83], v[132:135], v[216:219], v[80:83]
	v_mfma_f32_16x16x32_f16 v[108:111], v[152:155], v[176:179], v[108:111]
	v_mfma_f32_16x16x32_f16 v[116:119], v[144:147], v[176:179], v[116:119]
	v_mfma_f32_16x16x32_f16 v[92:95], v[152:155], v[184:187], v[92:95]
	v_mfma_f32_16x16x32_f16 v[100:103], v[144:147], v[184:187], v[100:103]
	v_mfma_f32_16x16x32_f16 v[76:79], v[152:155], v[198:201], v[76:79]
	v_mfma_f32_16x16x32_f16 v[84:87], v[144:147], v[198:201], v[84:87]
	v_mfma_f32_16x16x32_f16 v[64:67], v[152:155], v[212:215], v[64:67]
	v_mfma_f32_16x16x32_f16 v[68:71], v[144:147], v[212:215], v[68:71]
	v_mfma_f32_16x16x32_f16 v[108:111], v[156:159], v[180:183], v[108:111]
	v_mfma_f32_16x16x32_f16 v[116:119], v[148:151], v[180:183], v[116:119]
	v_mfma_f32_16x16x32_f16 v[92:95], v[156:159], v[194:197], v[92:95]
	v_mfma_f32_16x16x32_f16 v[100:103], v[148:151], v[194:197], v[100:103]
	v_mfma_f32_16x16x32_f16 v[76:79], v[156:159], v[208:211], v[76:79]
	v_mfma_f32_16x16x32_f16 v[84:87], v[148:151], v[208:211], v[84:87]
	v_mfma_f32_16x16x32_f16 v[64:67], v[156:159], v[216:219], v[64:67]
	v_mfma_f32_16x16x32_f16 v[68:71], v[148:151], v[216:219], v[68:71]
	s_barrier
	s_add_i32 s50, s91, s61
	s_mov_b32 m0, s50
	ds_read_b128 v[176:179], v193 offset:49152
	ds_read_b128 v[180:183], v193 offset:50176
	ds_read_b128 v[184:187], v193 offset:51200
	ds_read_b128 v[194:197], v193 offset:52224
	ds_read_b128 v[198:201], v193 offset:53248
	ds_read_b128 v[208:211], v193 offset:54272
	ds_read_b128 v[212:215], v193 offset:55296
	ds_read_b128 v[216:219], v193 offset:56320
	global_load_lds_dwordx4 v162, s[98:99]
	s_add_i32 m0, s50, 0x2000
	s_add_u32 s48, s48, 0x80080
	s_addc_u32 s49, s49, 0
	s_add_i32 s50, s92, s61
	global_load_lds_dwordx4 v166, s[98:99]
	s_mov_b32 m0, s50
	s_nop 0
	global_load_lds_dwordx4 v162, s[48:49]
	s_add_i32 m0, s50, 0x2000
	s_nop 0
	global_load_lds_dwordx4 v166, s[48:49]
	s_mov_b32 m0, s66
	s_nop 0
	global_load_lds_dwordx4 v160, s[100:101]
	s_mov_b32 m0, s67
	s_nop 0
	global_load_lds_dwordx4 v164, s[100:101]
	s_waitcnt vmcnt(8)
	s_waitcnt lgkmcnt(0)
	v_mfma_f32_16x16x32_f16 v[56:59], v[136:139], v[176:179], v[56:59]
	v_mfma_f32_16x16x32_f16 v[60:63], v[128:131], v[176:179], v[60:63]
	v_mfma_f32_16x16x32_f16 v[44:47], v[136:139], v[184:187], v[44:47]
	v_mfma_f32_16x16x32_f16 v[52:55], v[128:131], v[184:187], v[52:55]
	s_barrier
	s_waitcnt lgkmcnt(0)
	v_mfma_f32_16x16x32_f16 v[28:31], v[136:139], v[198:201], v[28:31]
	v_mfma_f32_16x16x32_f16 v[36:39], v[128:131], v[198:201], v[36:39]
	v_mfma_f32_16x16x32_f16 v[12:15], v[136:139], v[212:215], v[12:15]
	v_mfma_f32_16x16x32_f16 v[20:23], v[128:131], v[212:215], v[20:23]
	v_mfma_f32_16x16x32_f16 v[56:59], v[140:143], v[180:183], v[56:59]
	v_mfma_f32_16x16x32_f16 v[60:63], v[132:135], v[180:183], v[60:63]
	v_mfma_f32_16x16x32_f16 v[44:47], v[140:143], v[194:197], v[44:47]
	v_mfma_f32_16x16x32_f16 v[52:55], v[132:135], v[194:197], v[52:55]
	v_mfma_f32_16x16x32_f16 v[28:31], v[140:143], v[208:211], v[28:31]
	v_mfma_f32_16x16x32_f16 v[36:39], v[132:135], v[208:211], v[36:39]
	v_mfma_f32_16x16x32_f16 v[12:15], v[140:143], v[216:219], v[12:15]
	v_mfma_f32_16x16x32_f16 v[20:23], v[132:135], v[216:219], v[20:23]
	v_mfma_f32_16x16x32_f16 v[40:43], v[152:155], v[176:179], v[40:43]
	v_mfma_f32_16x16x32_f16 v[48:51], v[144:147], v[176:179], v[48:51]
	v_mfma_f32_16x16x32_f16 v[24:27], v[152:155], v[184:187], v[24:27]
	v_mfma_f32_16x16x32_f16 v[32:35], v[144:147], v[184:187], v[32:35]
	v_mfma_f32_16x16x32_f16 v[8:11], v[152:155], v[198:201], v[8:11]
	v_mfma_f32_16x16x32_f16 v[16:19], v[144:147], v[198:201], v[16:19]
	v_mfma_f32_16x16x32_f16 v[0:3], v[152:155], v[212:215], v[0:3]
	v_mfma_f32_16x16x32_f16 v[4:7], v[144:147], v[212:215], v[4:7]
	v_mfma_f32_16x16x32_f16 v[40:43], v[156:159], v[180:183], v[40:43]
	v_mfma_f32_16x16x32_f16 v[48:51], v[148:151], v[180:183], v[48:51]
	v_mfma_f32_16x16x32_f16 v[24:27], v[156:159], v[194:197], v[24:27]
	v_mfma_f32_16x16x32_f16 v[32:35], v[148:151], v[194:197], v[32:35]
	v_mfma_f32_16x16x32_f16 v[8:11], v[156:159], v[208:211], v[8:11]
	v_mfma_f32_16x16x32_f16 v[16:19], v[148:151], v[208:211], v[16:19]
	v_mfma_f32_16x16x32_f16 v[0:3], v[156:159], v[216:219], v[0:3]
	v_mfma_f32_16x16x32_f16 v[4:7], v[148:151], v[216:219], v[4:7]
	s_barrier
	s_add_i32 s90, s90, 2
	s_add_u32 s88, s88, 0x100
	s_addc_u32 s89, s89, 0
	s_add_u32 s44, s44, 0x100
	s_addc_u32 s45, s45, 0
	s_cmp_gt_u32 s90, 29
	s_cbranch_scc0 .LBB0_747
	s_and_b64 vcc, exec, s[20:21]
	s_cbranch_vccz .LBB0_750
	s_barrier

; #define PG8_STAGE(bufoff, gbase, voff) do { _Pragma("unroll") for (int _i = 0; _i < 2; ++_i) \
;         __builtin_amdgcn_global_load_lds((const unsigned*)((const char*)(gbase) + (voff)[_i]), (PG8_LAS unsigned*)(lds + (bufoff) + ldsw + _i * 8192), 16, 0, 0); } while (0)
; #define PG8_LDA(dst, b, h) do { _Pragma("unroll") for (int m = 0; m < 4; ++m) _Pragma("unroll") for (int k = 0; k < 2; ++k) dst[m][k] = *(const PG8_LAS bf16x8*)(lds + PG8_SA(b, h) + aoff + m * 2048 + k * 1024); } while (0)
; #define PG8_LDB(dst, b, h) do { _Pragma("unroll") for (int n = 0; n < 2; ++n) _Pragma("unroll") for (int k = 0; k < 2; ++k) dst[n][k] = *(const PG8_LAS bf16x8*)(lds + PG8_SB(b, h) + boff + n * 2048 + k * 1024); } while (0)
; #define PG8_MMA(ai, bj, At, Bt) do { __builtin_amdgcn_s_setprio(1); _Pragma("unroll") for (int m = 0; m < 4; ++m) _Pragma("unroll") for (int n = 0; n < 2; ++n) _Pragma("unroll") for (int k = 0; k < 2; ++k) \
;         acc[ai][bj][m][n] = __builtin_amdgcn_mfma_f32_16x16x32_f16(Bt[n][k], At[m][k], acc[ai][bj][m][n], 0, 0, 0); __builtin_amdgcn_s_setprio(0); } while (0)
; #define PG8_WAIT_V(n) asm volatile("s_waitcnt vmcnt(" #n ")" ::: "memory")
; #define PG8_WAIT_L(n) asm volatile("s_waitcnt lgkmcnt(" #n ")" ::: "memory")
; template <class Epi, class Sched, bool ALIGN_EPI = false, bool SP2 = false>
; __device__ __forceinline__ void gemm_phase(PG8_LAS unsigned char* lds, const Gemm g, const Sched& S, const Epi& E) {
;     ...
;             const bool last = (t == nt - 2);
;             const char* a1 = cA + (size_t)(t + 1) * kstep;
;             const char* a2 = last ? nA : cA + (size_t)(t + 2) * kstep; const char* b2 = last ? nB : cB + (size_t)(t + 2) * kstep;
;             const char* a3 = a2 + kstep; const char* b3 = b2 + kstep;
;             if (last && has_next) S.a_ready(nxt);
;             if constexpr (SP2) {
;             PG8_LDB(B0, 0, 0); PG8_LDB(B1, 0, 1); PG8_SCHED; PG8_LDA(At, 0, 0); PG8_STAGE(PG8_SA(1, 1), a1 + hstep, voffA);
;             PG8_WAIT_V(8); PG8_WAIT_L(0); PG8_BAR; PG8_MMA(0, 0, At, B0); PG8_MMA(0, 1, At, B1); PG8_BAR; PG8_SCHED;
;             PG8_LDA(At, 0, 1); PG8_STAGE(PG8_SB(0, 0), b2, voffB); PG8_STAGE(PG8_SB(0, 1), b2 + hstep, voffB); PG8_STAGE(PG8_SA(0, 0), a2, voffA);
;             PG8_WAIT_V(8); PG8_WAIT_L(0); PG8_BAR; PG8_MMA(1, 0, At, B0); PG8_MMA(1, 1, At, B1); PG8_BAR; PG8_SCHED;
.LBB0_872:
	ds_read_b128 v[128:131], v187
	ds_read_b128 v[132:135], v187 offset:1024
	ds_read_b128 v[136:139], v187 offset:2048
	ds_read_b128 v[140:143], v187 offset:3072
	ds_read_b128 v[144:147], v188
	ds_read_b128 v[148:151], v188 offset:1024
	ds_read_b128 v[152:155], v188 offset:2048
	ds_read_b128 v[156:159], v188 offset:3072
	s_add_u32 s28, s26, 0xfffe0080
	s_addc_u32 s29, s27, -1
	s_cmp_eq_u32 s65, 4
	s_cselect_b32 s31, s21, s29
	s_cselect_b32 s30, s61, s28
	s_cselect_b32 s29, s19, s64
	s_cselect_b32 s28, s62, s63
	s_add_i32 m0, s39, 0xc000
	ds_read_b128 v[160:163], v189
	ds_read_b128 v[164:167], v189 offset:1024
	ds_read_b128 v[192:195], v189 offset:2048
	ds_read_b128 v[196:199], v189 offset:3072
	ds_read_b128 v[200:203], v189 offset:4096
	ds_read_b128 v[208:211], v189 offset:5120
	ds_read_b128 v[212:215], v189 offset:6144
	ds_read_b128 v[216:219], v189 offset:7168
	global_load_lds_dwordx4 v178, s[26:27]
	s_add_i32 m0, s39, 0xe000
	s_nop 0
	global_load_lds_dwordx4 v176, s[26:27]
	s_waitcnt vmcnt(8)
	s_waitcnt lgkmcnt(0)
	v_mfma_f32_16x16x32_f16 v[120:123], v[136:139], v[160:163], v[120:123]
	v_mfma_f32_16x16x32_f16 v[124:127], v[128:131], v[160:163], v[124:127]
	v_mfma_f32_16x16x32_f16 v[104:107], v[136:139], v[192:195], v[104:107]
	v_mfma_f32_16x16x32_f16 v[108:111], v[128:131], v[192:195], v[108:111]
	s_barrier
	s_waitcnt lgkmcnt(0)
	v_mfma_f32_16x16x32_f16 v[88:91], v[136:139], v[200:203], v[88:91]
	v_mfma_f32_16x16x32_f16 v[92:95], v[128:131], v[200:203], v[92:95]
	v_mfma_f32_16x16x32_f16 v[72:75], v[136:139], v[212:215], v[72:75]
	v_mfma_f32_16x16x32_f16 v[76:79], v[128:131], v[212:215], v[76:79]
	v_mfma_f32_16x16x32_f16 v[120:123], v[140:143], v[164:167], v[120:123]
	v_mfma_f32_16x16x32_f16 v[124:127], v[132:135], v[164:167], v[124:127]
	v_mfma_f32_16x16x32_f16 v[104:107], v[140:143], v[196:199], v[104:107]
	v_mfma_f32_16x16x32_f16 v[108:111], v[132:135], v[196:199], v[108:111]
	v_mfma_f32_16x16x32_f16 v[88:91], v[140:143], v[208:211], v[88:91]
	v_mfma_f32_16x16x32_f16 v[92:95], v[132:135], v[208:211], v[92:95]
	v_mfma_f32_16x16x32_f16 v[72:75], v[140:143], v[216:219], v[72:75]
	v_mfma_f32_16x16x32_f16 v[76:79], v[132:135], v[216:219], v[76:79]
	v_mfma_f32_16x16x32_f16 v[112:115], v[152:155], v[160:163], v[112:115]
	v_mfma_f32_16x16x32_f16 v[116:119], v[144:147], v[160:163], v[116:119]
	v_mfma_f32_16x16x32_f16 v[96:99], v[152:155], v[192:195], v[96:99]
	v_mfma_f32_16x16x32_f16 v[100:103], v[144:147], v[192:195], v[100:103]
	v_mfma_f32_16x16x32_f16 v[80:83], v[152:155], v[200:203], v[80:83]
	v_mfma_f32_16x16x32_f16 v[84:87], v[144:147], v[200:203], v[84:87]
	v_mfma_f32_16x16x32_f16 v[64:67], v[152:155], v[212:215], v[64:67]
	v_mfma_f32_16x16x32_f16 v[68:71], v[144:147], v[212:215], v[68:71]
	v_mfma_f32_16x16x32_f16 v[112:115], v[156:159], v[164:167], v[112:115]
	v_mfma_f32_16x16x32_f16 v[116:119], v[148:151], v[164:167], v[116:119]
	v_mfma_f32_16x16x32_f16 v[96:99], v[156:159], v[196:199], v[96:99]
	v_mfma_f32_16x16x32_f16 v[100:103], v[148:151], v[196:199], v[100:103]
	v_mfma_f32_16x16x32_f16 v[80:83], v[156:159], v[208:211], v[80:83]
	v_mfma_f32_16x16x32_f16 v[84:87], v[148:151], v[208:211], v[84:87]
	v_mfma_f32_16x16x32_f16 v[64:67], v[156:159], v[216:219], v[64:67]
	v_mfma_f32_16x16x32_f16 v[68:71], v[148:151], v[216:219], v[68:71]
	s_barrier
	s_add_i32 s66, s49, s37
	s_add_u32 s98, s28, s14
	s_addc_u32 s99, s29, s15
	s_mov_b32 m0, s66
	ds_read_b128 v[160:163], v189 offset:16384
	ds_read_b128 v[164:167], v189 offset:17408
	ds_read_b128 v[192:195], v189 offset:18432
	ds_read_b128 v[196:199], v189 offset:19456
	ds_read_b128 v[200:203], v189 offset:20480
	ds_read_b128 v[208:211], v189 offset:21504
	ds_read_b128 v[212:215], v189 offset:22528
	ds_read_b128 v[216:219], v189 offset:23552
	global_load_lds_dwordx4 v170, s[28:29]
	s_add_i32 m0, s66, 0x2000
	s_add_u32 s66, s28, 0x20000
	s_addc_u32 s67, s29, 0
	s_add_i32 s68, s50, s37
	global_load_lds_dwordx4 v168, s[28:29]
	s_mov_b32 m0, s68
	s_nop 0
	global_load_lds_dwordx4 v170, s[66:67]
	s_add_i32 m0, s68, 0x2000
	s_nop 0
	global_load_lds_dwordx4 v168, s[66:67]
	s_add_u32 s100, s30, s14
	s_addc_u32 s101, s31, s15
	s_mov_b32 m0, s39
	s_nop 0
	global_load_lds_dwordx4 v170, s[30:31]
	s_mov_b32 m0, s40
	s_nop 0
	global_load_lds_dwordx4 v168, s[30:31]
	s_waitcnt vmcnt(8)
	s_waitcnt lgkmcnt(0)
	v_mfma_f32_16x16x32_f16 v[56:59], v[136:139], v[160:163], v[56:59]
	v_mfma_f32_16x16x32_f16 v[60:63], v[128:131], v[160:163], v[60:63]
	v_mfma_f32_16x16x32_f16 v[40:43], v[136:139], v[192:195], v[40:43]
	v_mfma_f32_16x16x32_f16 v[44:47], v[128:131], v[192:195], v[44:47]
	s_barrier
	s_waitcnt lgkmcnt(0)
	v_mfma_f32_16x16x32_f16 v[24:27], v[136:139], v[200:203], v[24:27]
	v_mfma_f32_16x16x32_f16 v[28:31], v[128:131], v[200:203], v[28:31]
	v_mfma_f32_16x16x32_f16 v[8:11], v[136:139], v[212:215], v[8:11]
	v_mfma_f32_16x16x32_f16 v[12:15], v[128:131], v[212:215], v[12:15]
	v_mfma_f32_16x16x32_f16 v[56:59], v[140:143], v[164:167], v[56:59]
	v_mfma_f32_16x16x32_f16 v[60:63], v[132:135], v[164:167], v[60:63]
	v_mfma_f32_16x16x32_f16 v[40:43], v[140:143], v[196:199], v[40:43]
	v_mfma_f32_16x16x32_f16 v[44:47], v[132:135], v[196:199], v[44:47]
	v_mfma_f32_16x16x32_f16 v[24:27], v[140:143], v[208:211], v[24:27]
	v_mfma_f32_16x16x32_f16 v[28:31], v[132:135], v[208:211], v[28:31]
	v_mfma_f32_16x16x32_f16 v[8:11], v[140:143], v[216:219], v[8:11]
	v_mfma_f32_16x16x32_f16 v[12:15], v[132:135], v[216:219], v[12:15]
	v_mfma_f32_16x16x32_f16 v[48:51], v[152:155], v[160:163], v[48:51]
	v_mfma_f32_16x16x32_f16 v[52:55], v[144:147], v[160:163], v[52:55]
	v_mfma_f32_16x16x32_f16 v[32:35], v[152:155], v[192:195], v[32:35]
	v_mfma_f32_16x16x32_f16 v[36:39], v[144:147], v[192:195], v[36:39]
	v_mfma_f32_16x16x32_f16 v[16:19], v[152:155], v[200:203], v[16:19]
	v_mfma_f32_16x16x32_f16 v[20:23], v[144:147], v[200:203], v[20:23]
	v_mfma_f32_16x16x32_f16 v[0:3], v[152:155], v[212:215], v[0:3]
	v_mfma_f32_16x16x32_f16 v[4:7], v[144:147], v[212:215], v[4:7]
	v_mfma_f32_16x16x32_f16 v[48:51], v[156:159], v[164:167], v[48:51]
	v_mfma_f32_16x16x32_f16 v[52:55], v[148:151], v[164:167], v[52:55]
	v_mfma_f32_16x16x32_f16 v[32:35], v[156:159], v[196:199], v[32:35]
	v_mfma_f32_16x16x32_f16 v[36:39], v[148:151], v[196:199], v[36:39]
	v_mfma_f32_16x16x32_f16 v[16:19], v[156:159], v[208:211], v[16:19]
	v_mfma_f32_16x16x32_f16 v[20:23], v[148:151], v[208:211], v[20:23]
	v_mfma_f32_16x16x32_f16 v[0:3], v[156:159], v[216:219], v[0:3]
	v_mfma_f32_16x16x32_f16 v[4:7], v[148:151], v[216:219], v[4:7]
	s_barrier
; #define PG8_STAGE(bufoff, gbase, voff) do { _Pragma("unroll") for (int _i = 0; _i < 2; ++_i) \
;         __builtin_amdgcn_global_load_lds((const unsigned*)((const char*)(gbase) + (voff)[_i]), (PG8_LAS unsigned*)(lds + (bufoff) + ldsw + _i * 8192), 16, 0, 0); } while (0)
; #define PG8_LDA(dst, b, h) do { _Pragma("unroll") for (int m = 0; m < 4; ++m) _Pragma("unroll") for (int k = 0; k < 2; ++k) dst[m][k] = *(const PG8_LAS bf16x8*)(lds + PG8_SA(b, h) + aoff + m * 2048 + k * 1024); } while (0)
; #define PG8_LDB(dst, b, h) do { _Pragma("unroll") for (int n = 0; n < 2; ++n) _Pragma("unroll") for (int k = 0; k < 2; ++k) dst[n][k] = *(const PG8_LAS bf16x8*)(lds + PG8_SB(b, h) + boff + n * 2048 + k * 1024); } while (0)
; #define PG8_MMA(ai, bj, At, Bt) do { __builtin_amdgcn_s_setprio(1); _Pragma("unroll") for (int m = 0; m < 4; ++m) _Pragma("unroll") for (int n = 0; n < 2; ++n) _Pragma("unroll") for (int k = 0; k < 2; ++k) \
;         acc[ai][bj][m][n] = __builtin_amdgcn_mfma_f32_16x16x32_f16(Bt[n][k], At[m][k], acc[ai][bj][m][n], 0, 0, 0); __builtin_amdgcn_s_setprio(0); } while (0)
; #define PG8_WAIT_V(n) asm volatile("s_waitcnt vmcnt(" #n ")" ::: "memory")
; #define PG8_WAIT_L(n) asm volatile("s_waitcnt lgkmcnt(" #n ")" ::: "memory")
; #define PG8_BAR __builtin_amdgcn_s_barrier()
; #define PG8_SCHED __builtin_amdgcn_sched_barrier(0)
; template <class Epi, class Sched, bool ALIGN_EPI = false, bool SP2 = false>
; __device__ __forceinline__ void gemm_phase(PG8_LAS unsigned char* lds, const Gemm g, const Sched& S, const Epi& E) {
;     ...
;             PG8_LDB(B0, 1, 0); PG8_LDB(B1, 1, 1); PG8_SCHED; PG8_LDA(At, 1, 0); PG8_STAGE(PG8_SA(0, 1), a2 + hstep, voffA);
;             PG8_WAIT_V(8); PG8_WAIT_L(0); PG8_BAR; PG8_MMA(0, 0, At, B0); PG8_MMA(0, 1, At, B1); PG8_BAR; PG8_SCHED;
;             PG8_LDA(At, 1, 1); PG8_STAGE(PG8_SB(1, 0), b3, voffB); PG8_STAGE(PG8_SB(1, 1), b3 + hstep, voffB); PG8_STAGE(PG8_SA(1, 0), a3, voffA);
;             PG8_WAIT_V(8); PG8_WAIT_L(0); PG8_BAR; PG8_MMA(1, 0, At, B0); PG8_MMA(1, 1, At, B1); PG8_BAR; PG8_SCHED;
	s_add_i32 s66, 0, 0x18000
	s_add_i32 s67, 0, 0x1c000
	v_add_u32_e32 v140, s66, v186
	v_add_u32_e32 v156, s67, v186
	ds_read_b128 v[128:131], v140
	ds_read_b128 v[132:135], v140 offset:1024
	ds_read_b128 v[136:139], v140 offset:2048
	ds_read_b128 v[140:143], v140 offset:3072
	ds_read_b128 v[144:147], v156
	ds_read_b128 v[148:151], v156 offset:1024
	ds_read_b128 v[152:155], v156 offset:2048
	ds_read_b128 v[156:159], v156 offset:3072
	s_add_u32 s30, s30, 0x20000
	s_addc_u32 s31, s31, 0
	s_mov_b32 m0, s41
	ds_read_b128 v[160:163], v189 offset:32768
	ds_read_b128 v[164:167], v189 offset:33792
	ds_read_b128 v[192:195], v189 offset:34816
	ds_read_b128 v[196:199], v189 offset:35840
	ds_read_b128 v[200:203], v189 offset:36864
	ds_read_b128 v[208:211], v189 offset:37888
	ds_read_b128 v[212:215], v189 offset:38912
	ds_read_b128 v[216:219], v189 offset:39936
	global_load_lds_dwordx4 v170, s[30:31]
	s_mov_b32 m0, s42
	s_nop 0
	global_load_lds_dwordx4 v168, s[30:31]
	s_waitcnt vmcnt(8)
	s_waitcnt lgkmcnt(0)
	v_mfma_f32_16x16x32_f16 v[120:123], v[136:139], v[160:163], v[120:123]
	v_mfma_f32_16x16x32_f16 v[124:127], v[128:131], v[160:163], v[124:127]
	v_mfma_f32_16x16x32_f16 v[104:107], v[136:139], v[192:195], v[104:107]
	v_mfma_f32_16x16x32_f16 v[108:111], v[128:131], v[192:195], v[108:111]
	s_barrier
	s_waitcnt lgkmcnt(0)
	v_mfma_f32_16x16x32_f16 v[88:91], v[136:139], v[200:203], v[88:91]
	v_mfma_f32_16x16x32_f16 v[92:95], v[128:131], v[200:203], v[92:95]
	v_mfma_f32_16x16x32_f16 v[72:75], v[136:139], v[212:215], v[72:75]
	v_mfma_f32_16x16x32_f16 v[76:79], v[128:131], v[212:215], v[76:79]
	v_mfma_f32_16x16x32_f16 v[120:123], v[140:143], v[164:167], v[120:123]
	v_mfma_f32_16x16x32_f16 v[124:127], v[132:135], v[164:167], v[124:127]
	v_mfma_f32_16x16x32_f16 v[104:107], v[140:143], v[196:199], v[104:107]
	v_mfma_f32_16x16x32_f16 v[108:111], v[132:135], v[196:199], v[108:111]
	v_mfma_f32_16x16x32_f16 v[88:91], v[140:143], v[208:211], v[88:91]
	v_mfma_f32_16x16x32_f16 v[92:95], v[132:135], v[208:211], v[92:95]
	v_mfma_f32_16x16x32_f16 v[72:75], v[140:143], v[216:219], v[72:75]
	v_mfma_f32_16x16x32_f16 v[76:79], v[132:135], v[216:219], v[76:79]
	v_mfma_f32_16x16x32_f16 v[112:115], v[152:155], v[160:163], v[112:115]
	v_mfma_f32_16x16x32_f16 v[116:119], v[144:147], v[160:163], v[116:119]
	v_mfma_f32_16x16x32_f16 v[96:99], v[152:155], v[192:195], v[96:99]
	v_mfma_f32_16x16x32_f16 v[100:103], v[144:147], v[192:195], v[100:103]
	v_mfma_f32_16x16x32_f16 v[80:83], v[152:155], v[200:203], v[80:83]
	v_mfma_f32_16x16x32_f16 v[84:87], v[144:147], v[200:203], v[84:87]
	v_mfma_f32_16x16x32_f16 v[64:67], v[152:155], v[212:215], v[64:67]
	v_mfma_f32_16x16x32_f16 v[68:71], v[144:147], v[212:215], v[68:71]
	v_mfma_f32_16x16x32_f16 v[112:115], v[156:159], v[164:167], v[112:115]
	v_mfma_f32_16x16x32_f16 v[116:119], v[148:151], v[164:167], v[116:119]
	v_mfma_f32_16x16x32_f16 v[96:99], v[156:159], v[196:199], v[96:99]
	v_mfma_f32_16x16x32_f16 v[100:103], v[148:151], v[196:199], v[100:103]
	v_mfma_f32_16x16x32_f16 v[80:83], v[156:159], v[208:211], v[80:83]
	v_mfma_f32_16x16x32_f16 v[84:87], v[148:151], v[208:211], v[84:87]
	v_mfma_f32_16x16x32_f16 v[64:67], v[156:159], v[216:219], v[64:67]
	v_mfma_f32_16x16x32_f16 v[68:71], v[148:151], v[216:219], v[68:71]
	s_barrier
	s_add_i32 s30, s66, s37
	s_mov_b32 m0, s30
	ds_read_b128 v[160:163], v189 offset:49152
	ds_read_b128 v[164:167], v189 offset:50176
	ds_read_b128 v[192:195], v189 offset:51200
	ds_read_b128 v[196:199], v189 offset:52224
	ds_read_b128 v[200:203], v189 offset:53248
	ds_read_b128 v[208:211], v189 offset:54272
	ds_read_b128 v[212:215], v189 offset:55296
	ds_read_b128 v[216:219], v189 offset:56320
	global_load_lds_dwordx4 v170, s[98:99]
	s_add_i32 m0, s30, 0x2000
	s_add_u32 s28, s28, 0x20080
	s_addc_u32 s29, s29, 0
	s_add_i32 s30, s67, s37
	global_load_lds_dwordx4 v168, s[98:99]
	s_mov_b32 m0, s30
	s_nop 0
	global_load_lds_dwordx4 v170, s[28:29]
	s_add_i32 m0, s30, 0x2000
	s_nop 0
	global_load_lds_dwordx4 v168, s[28:29]
	s_mov_b32 m0, s45
	s_nop 0
	global_load_lds_dwordx4 v170, s[100:101]
	s_mov_b32 m0, s48
	s_nop 0
	global_load_lds_dwordx4 v168, s[100:101]
	s_waitcnt vmcnt(8)
	s_waitcnt lgkmcnt(0)
	v_mfma_f32_16x16x32_f16 v[56:59], v[136:139], v[160:163], v[56:59]
	v_mfma_f32_16x16x32_f16 v[60:63], v[128:131], v[160:163], v[60:63]
	v_mfma_f32_16x16x32_f16 v[40:43], v[136:139], v[192:195], v[40:43]
	v_mfma_f32_16x16x32_f16 v[44:47], v[128:131], v[192:195], v[44:47]
	s_barrier
	s_waitcnt lgkmcnt(0)
	v_mfma_f32_16x16x32_f16 v[24:27], v[136:139], v[200:203], v[24:27]
	v_mfma_f32_16x16x32_f16 v[28:31], v[128:131], v[200:203], v[28:31]
	v_mfma_f32_16x16x32_f16 v[8:11], v[136:139], v[212:215], v[8:11]
	v_mfma_f32_16x16x32_f16 v[12:15], v[128:131], v[212:215], v[12:15]
	v_mfma_f32_16x16x32_f16 v[56:59], v[140:143], v[164:167], v[56:59]
	v_mfma_f32_16x16x32_f16 v[60:63], v[132:135], v[164:167], v[60:63]
	v_mfma_f32_16x16x32_f16 v[40:43], v[140:143], v[196:199], v[40:43]
	v_mfma_f32_16x16x32_f16 v[44:47], v[132:135], v[196:199], v[44:47]
	v_mfma_f32_16x16x32_f16 v[24:27], v[140:143], v[208:211], v[24:27]
	v_mfma_f32_16x16x32_f16 v[28:31], v[132:135], v[208:211], v[28:31]
	v_mfma_f32_16x16x32_f16 v[8:11], v[140:143], v[216:219], v[8:11]
	v_mfma_f32_16x16x32_f16 v[12:15], v[132:135], v[216:219], v[12:15]
	v_mfma_f32_16x16x32_f16 v[48:51], v[152:155], v[160:163], v[48:51]
	v_mfma_f32_16x16x32_f16 v[52:55], v[144:147], v[160:163], v[52:55]
	v_mfma_f32_16x16x32_f16 v[32:35], v[152:155], v[192:195], v[32:35]
	v_mfma_f32_16x16x32_f16 v[36:39], v[144:147], v[192:195], v[36:39]
	v_mfma_f32_16x16x32_f16 v[16:19], v[152:155], v[200:203], v[16:19]
	v_mfma_f32_16x16x32_f16 v[20:23], v[144:147], v[200:203], v[20:23]
	v_mfma_f32_16x16x32_f16 v[0:3], v[152:155], v[212:215], v[0:3]
	v_mfma_f32_16x16x32_f16 v[4:7], v[144:147], v[212:215], v[4:7]
	v_mfma_f32_16x16x32_f16 v[48:51], v[156:159], v[164:167], v[48:51]
	v_mfma_f32_16x16x32_f16 v[52:55], v[148:151], v[164:167], v[52:55]
	v_mfma_f32_16x16x32_f16 v[32:35], v[156:159], v[196:199], v[32:35]
	v_mfma_f32_16x16x32_f16 v[36:39], v[148:151], v[196:199], v[36:39]
	v_mfma_f32_16x16x32_f16 v[16:19], v[156:159], v[208:211], v[16:19]
	v_mfma_f32_16x16x32_f16 v[20:23], v[148:151], v[208:211], v[20:23]
	v_mfma_f32_16x16x32_f16 v[0:3], v[156:159], v[216:219], v[0:3]
	v_mfma_f32_16x16x32_f16 v[4:7], v[148:151], v[216:219], v[4:7]
	s_barrier
	s_add_i32 s65, s65, 2
	s_add_u32 s63, s63, 0x100
	s_addc_u32 s64, s64, 0
	s_add_u32 s26, s26, 0x100
	s_addc_u32 s27, s27, 0
	s_cmp_gt_u32 s65, 5
	s_cbranch_scc0 .LBB0_872
	s_and_b64 vcc, exec, s[16:17]
	s_cbranch_vccz .LBB0_875
	s_barrier

; #define PG8_STAGE(bufoff, gbase, voff) do { _Pragma("unroll") for (int _i = 0; _i < 2; ++_i) \
;         __builtin_amdgcn_global_load_lds((const unsigned*)((const char*)(gbase) + (voff)[_i]), (PG8_LAS unsigned*)(lds + (bufoff) + ldsw + _i * 8192), 16, 0, 0); } while (0)
; #define PG8_LDA(dst, b, h) do { _Pragma("unroll") for (int m = 0; m < 4; ++m) _Pragma("unroll") for (int k = 0; k < 2; ++k) dst[m][k] = *(const PG8_LAS bf16x8*)(lds + PG8_SA(b, h) + aoff + m * 2048 + k * 1024); } while (0)
; #define PG8_LDB(dst, b, h) do { _Pragma("unroll") for (int n = 0; n < 2; ++n) _Pragma("unroll") for (int k = 0; k < 2; ++k) dst[n][k] = *(const PG8_LAS bf16x8*)(lds + PG8_SB(b, h) + boff + n * 2048 + k * 1024); } while (0)
; #define PG8_MMA(ai, bj, At, Bt) do { __builtin_amdgcn_s_setprio(1); _Pragma("unroll") for (int m = 0; m < 4; ++m) _Pragma("unroll") for (int n = 0; n < 2; ++n) _Pragma("unroll") for (int k = 0; k < 2; ++k) \
;         acc[ai][bj][m][n] = __builtin_amdgcn_mfma_f32_16x16x32_f16(Bt[n][k], At[m][k], acc[ai][bj][m][n], 0, 0, 0); __builtin_amdgcn_s_setprio(0); } while (0)
; #define PG8_WAIT_V(n) asm volatile("s_waitcnt vmcnt(" #n ")" ::: "memory")
; #define PG8_WAIT_L(n) asm volatile("s_waitcnt lgkmcnt(" #n ")" ::: "memory")
; template <class Epi, class Sched, bool ALIGN_EPI = false, bool SP2 = false>
; __device__ __forceinline__ void gemm_phase(PG8_LAS unsigned char* lds, const Gemm g, const Sched& S, const Epi& E) {
;     ...
;             const bool last = (t == nt - 2);
;             const char* a1 = cA + (size_t)(t + 1) * kstep;
;             const char* a2 = last ? nA : cA + (size_t)(t + 2) * kstep; const char* b2 = last ? nB : cB + (size_t)(t + 2) * kstep;
;             const char* a3 = a2 + kstep; const char* b3 = b2 + kstep;
;             if (last && has_next) S.a_ready(nxt);
;             if constexpr (SP2) {
;             PG8_LDB(B0, 0, 0); PG8_LDB(B1, 0, 1); PG8_SCHED; PG8_LDA(At, 0, 0); PG8_STAGE(PG8_SA(1, 1), a1 + hstep, voffA);
;             PG8_WAIT_V(8); PG8_WAIT_L(0); PG8_BAR; PG8_MMA(0, 0, At, B0); PG8_MMA(0, 1, At, B1); PG8_BAR; PG8_SCHED;
;             PG8_LDA(At, 0, 1); PG8_STAGE(PG8_SB(0, 0), b2, voffB); PG8_STAGE(PG8_SB(0, 1), b2 + hstep, voffB); PG8_STAGE(PG8_SA(0, 0), a2, voffA);
;             PG8_WAIT_V(8); PG8_WAIT_L(0); PG8_BAR; PG8_MMA(1, 0, At, B0); PG8_MMA(1, 1, At, B1); PG8_BAR; PG8_SCHED;
.LBB0_1075:
	ds_read_b128 v[128:131], v211
	ds_read_b128 v[132:135], v211 offset:1024
	ds_read_b128 v[136:139], v211 offset:2048
	ds_read_b128 v[140:143], v211 offset:3072
	ds_read_b128 v[144:147], v212
	ds_read_b128 v[148:151], v212 offset:1024
	ds_read_b128 v[152:155], v212 offset:2048
	ds_read_b128 v[156:159], v212 offset:3072
	s_add_u32 s42, s40, 0xfff80080
	s_addc_u32 s43, s41, -1
	s_cmp_eq_u32 s70, 28
	s_cselect_b32 s45, s29, s43
	s_cselect_b32 s44, s37, s42
	s_cselect_b32 s43, s27, s69
	s_cselect_b32 s42, s67, s68
	s_add_i32 m0, s39, 0xc000
	ds_read_b128 v[160:163], v213
	ds_read_b128 v[164:167], v213 offset:1024
	ds_read_b128 v[184:187], v213 offset:2048
	ds_read_b128 v[188:191], v213 offset:3072
	ds_read_b128 v[192:195], v213 offset:4096
	ds_read_b128 v[196:199], v213 offset:5120
	ds_read_b128 v[200:203], v213 offset:6144
	ds_read_b128 v[214:217], v213 offset:7168
	global_load_lds_dwordx4 v178, s[40:41]
	s_add_i32 m0, s39, 0xe000
	s_nop 0
	global_load_lds_dwordx4 v176, s[40:41]
	s_waitcnt vmcnt(8)
	s_waitcnt lgkmcnt(0)
	v_mfma_f32_16x16x32_f16 v[120:123], v[136:139], v[160:163], v[120:123]
	v_mfma_f32_16x16x32_f16 v[124:127], v[128:131], v[160:163], v[124:127]
	v_mfma_f32_16x16x32_f16 v[104:107], v[136:139], v[184:187], v[104:107]
	v_mfma_f32_16x16x32_f16 v[108:111], v[128:131], v[184:187], v[108:111]
	s_barrier
	s_waitcnt lgkmcnt(0)
	v_mfma_f32_16x16x32_f16 v[88:91], v[136:139], v[192:195], v[88:91]
	v_mfma_f32_16x16x32_f16 v[92:95], v[128:131], v[192:195], v[92:95]
	v_mfma_f32_16x16x32_f16 v[72:75], v[136:139], v[200:203], v[72:75]
	v_mfma_f32_16x16x32_f16 v[76:79], v[128:131], v[200:203], v[76:79]
	v_mfma_f32_16x16x32_f16 v[120:123], v[140:143], v[164:167], v[120:123]
	v_mfma_f32_16x16x32_f16 v[124:127], v[132:135], v[164:167], v[124:127]
	v_mfma_f32_16x16x32_f16 v[104:107], v[140:143], v[188:191], v[104:107]
	v_mfma_f32_16x16x32_f16 v[108:111], v[132:135], v[188:191], v[108:111]
	v_mfma_f32_16x16x32_f16 v[88:91], v[140:143], v[196:199], v[88:91]
	v_mfma_f32_16x16x32_f16 v[92:95], v[132:135], v[196:199], v[92:95]
	v_mfma_f32_16x16x32_f16 v[72:75], v[140:143], v[214:217], v[72:75]
	v_mfma_f32_16x16x32_f16 v[76:79], v[132:135], v[214:217], v[76:79]
	v_mfma_f32_16x16x32_f16 v[112:115], v[152:155], v[160:163], v[112:115]
	v_mfma_f32_16x16x32_f16 v[116:119], v[144:147], v[160:163], v[116:119]
	v_mfma_f32_16x16x32_f16 v[96:99], v[152:155], v[184:187], v[96:99]
	v_mfma_f32_16x16x32_f16 v[100:103], v[144:147], v[184:187], v[100:103]
	v_mfma_f32_16x16x32_f16 v[80:83], v[152:155], v[192:195], v[80:83]
	v_mfma_f32_16x16x32_f16 v[84:87], v[144:147], v[192:195], v[84:87]
	v_mfma_f32_16x16x32_f16 v[64:67], v[152:155], v[200:203], v[64:67]
	v_mfma_f32_16x16x32_f16 v[68:71], v[144:147], v[200:203], v[68:71]
	v_mfma_f32_16x16x32_f16 v[112:115], v[156:159], v[164:167], v[112:115]
	v_mfma_f32_16x16x32_f16 v[116:119], v[148:151], v[164:167], v[116:119]
	v_mfma_f32_16x16x32_f16 v[96:99], v[156:159], v[188:191], v[96:99]
	v_mfma_f32_16x16x32_f16 v[100:103], v[148:151], v[188:191], v[100:103]
	v_mfma_f32_16x16x32_f16 v[80:83], v[156:159], v[196:199], v[80:83]
	v_mfma_f32_16x16x32_f16 v[84:87], v[148:151], v[196:199], v[84:87]
	v_mfma_f32_16x16x32_f16 v[64:67], v[156:159], v[214:217], v[64:67]
	v_mfma_f32_16x16x32_f16 v[68:71], v[148:151], v[214:217], v[68:71]
	s_barrier
	s_add_i32 s71, s64, s48
	s_add_u32 s98, s42, s18
	s_addc_u32 s99, s43, s19
	s_mov_b32 m0, s71
	ds_read_b128 v[160:163], v213 offset:16384
	ds_read_b128 v[164:167], v213 offset:17408
	ds_read_b128 v[184:187], v213 offset:18432
	ds_read_b128 v[188:191], v213 offset:19456
	ds_read_b128 v[192:195], v213 offset:20480
	ds_read_b128 v[196:199], v213 offset:21504
	ds_read_b128 v[200:203], v213 offset:22528
	ds_read_b128 v[214:217], v213 offset:23552
	global_load_lds_dwordx4 v170, s[42:43]
	s_add_i32 m0, s71, 0x2000
	s_add_u32 s72, s42, 0x80000
	s_addc_u32 s73, s43, 0
	s_add_i32 s71, s65, s48
	global_load_lds_dwordx4 v174, s[42:43]
	s_mov_b32 m0, s71
	s_nop 0
	global_load_lds_dwordx4 v170, s[72:73]
	s_add_i32 m0, s71, 0x2000
	s_nop 0
	global_load_lds_dwordx4 v174, s[72:73]
	s_add_u32 s100, s44, s18
	s_addc_u32 s101, s45, s19
	s_mov_b32 m0, s39
	s_nop 0
	global_load_lds_dwordx4 v168, s[44:45]
	s_mov_b32 m0, s49
	s_nop 0
	global_load_lds_dwordx4 v172, s[44:45]
	s_waitcnt vmcnt(8)
	s_waitcnt lgkmcnt(0)
	v_mfma_f32_16x16x32_f16 v[56:59], v[136:139], v[160:163], v[56:59]
	v_mfma_f32_16x16x32_f16 v[60:63], v[128:131], v[160:163], v[60:63]
	v_mfma_f32_16x16x32_f16 v[40:43], v[136:139], v[184:187], v[40:43]
	v_mfma_f32_16x16x32_f16 v[44:47], v[128:131], v[184:187], v[44:47]
	s_barrier
	s_waitcnt lgkmcnt(0)
	v_mfma_f32_16x16x32_f16 v[24:27], v[136:139], v[192:195], v[24:27]
	v_mfma_f32_16x16x32_f16 v[28:31], v[128:131], v[192:195], v[28:31]
	v_mfma_f32_16x16x32_f16 v[8:11], v[136:139], v[200:203], v[8:11]
	v_mfma_f32_16x16x32_f16 v[12:15], v[128:131], v[200:203], v[12:15]
	v_mfma_f32_16x16x32_f16 v[56:59], v[140:143], v[164:167], v[56:59]
	v_mfma_f32_16x16x32_f16 v[60:63], v[132:135], v[164:167], v[60:63]
	v_mfma_f32_16x16x32_f16 v[40:43], v[140:143], v[188:191], v[40:43]
	v_mfma_f32_16x16x32_f16 v[44:47], v[132:135], v[188:191], v[44:47]
	v_mfma_f32_16x16x32_f16 v[24:27], v[140:143], v[196:199], v[24:27]
	v_mfma_f32_16x16x32_f16 v[28:31], v[132:135], v[196:199], v[28:31]
	v_mfma_f32_16x16x32_f16 v[8:11], v[140:143], v[214:217], v[8:11]
	v_mfma_f32_16x16x32_f16 v[12:15], v[132:135], v[214:217], v[12:15]
	v_mfma_f32_16x16x32_f16 v[48:51], v[152:155], v[160:163], v[48:51]
	v_mfma_f32_16x16x32_f16 v[52:55], v[144:147], v[160:163], v[52:55]
	v_mfma_f32_16x16x32_f16 v[32:35], v[152:155], v[184:187], v[32:35]
	v_mfma_f32_16x16x32_f16 v[36:39], v[144:147], v[184:187], v[36:39]
	v_mfma_f32_16x16x32_f16 v[16:19], v[152:155], v[192:195], v[16:19]
	v_mfma_f32_16x16x32_f16 v[20:23], v[144:147], v[192:195], v[20:23]
	v_mfma_f32_16x16x32_f16 v[0:3], v[152:155], v[200:203], v[0:3]
	v_mfma_f32_16x16x32_f16 v[4:7], v[144:147], v[200:203], v[4:7]
	v_mfma_f32_16x16x32_f16 v[48:51], v[156:159], v[164:167], v[48:51]
	v_mfma_f32_16x16x32_f16 v[52:55], v[148:151], v[164:167], v[52:55]
	v_mfma_f32_16x16x32_f16 v[32:35], v[156:159], v[188:191], v[32:35]
	v_mfma_f32_16x16x32_f16 v[36:39], v[148:151], v[188:191], v[36:39]
	v_mfma_f32_16x16x32_f16 v[16:19], v[156:159], v[196:199], v[16:19]
	v_mfma_f32_16x16x32_f16 v[20:23], v[148:151], v[196:199], v[20:23]
	v_mfma_f32_16x16x32_f16 v[0:3], v[156:159], v[214:217], v[0:3]
	v_mfma_f32_16x16x32_f16 v[4:7], v[148:151], v[214:217], v[4:7]
	s_barrier
; #define PG8_STAGE(bufoff, gbase, voff) do { _Pragma("unroll") for (int _i = 0; _i < 2; ++_i) \
;         __builtin_amdgcn_global_load_lds((const unsigned*)((const char*)(gbase) + (voff)[_i]), (PG8_LAS unsigned*)(lds + (bufoff) + ldsw + _i * 8192), 16, 0, 0); } while (0)
; #define PG8_LDA(dst, b, h) do { _Pragma("unroll") for (int m = 0; m < 4; ++m) _Pragma("unroll") for (int k = 0; k < 2; ++k) dst[m][k] = *(const PG8_LAS bf16x8*)(lds + PG8_SA(b, h) + aoff + m * 2048 + k * 1024); } while (0)
; #define PG8_LDB(dst, b, h) do { _Pragma("unroll") for (int n = 0; n < 2; ++n) _Pragma("unroll") for (int k = 0; k < 2; ++k) dst[n][k] = *(const PG8_LAS bf16x8*)(lds + PG8_SB(b, h) + boff + n * 2048 + k * 1024); } while (0)
; #define PG8_MMA(ai, bj, At, Bt) do { __builtin_amdgcn_s_setprio(1); _Pragma("unroll") for (int m = 0; m < 4; ++m) _Pragma("unroll") for (int n = 0; n < 2; ++n) _Pragma("unroll") for (int k = 0; k < 2; ++k) \
;         acc[ai][bj][m][n] = __builtin_amdgcn_mfma_f32_16x16x32_f16(Bt[n][k], At[m][k], acc[ai][bj][m][n], 0, 0, 0); __builtin_amdgcn_s_setprio(0); } while (0)
; #define PG8_WAIT_V(n) asm volatile("s_waitcnt vmcnt(" #n ")" ::: "memory")
; #define PG8_WAIT_L(n) asm volatile("s_waitcnt lgkmcnt(" #n ")" ::: "memory")
; #define PG8_BAR __builtin_amdgcn_s_barrier()
; #define PG8_SCHED __builtin_amdgcn_sched_barrier(0)
; template <class Epi, class Sched, bool ALIGN_EPI = false, bool SP2 = false>
; __device__ __forceinline__ void gemm_phase(PG8_LAS unsigned char* lds, const Gemm g, const Sched& S, const Epi& E) {
;     ...
;             PG8_LDB(B0, 1, 0); PG8_LDB(B1, 1, 1); PG8_SCHED; PG8_LDA(At, 1, 0); PG8_STAGE(PG8_SA(0, 1), a2 + hstep, voffA);
;             PG8_WAIT_V(8); PG8_WAIT_L(0); PG8_BAR; PG8_MMA(0, 0, At, B0); PG8_MMA(0, 1, At, B1); PG8_BAR; PG8_SCHED;
;             PG8_LDA(At, 1, 1); PG8_STAGE(PG8_SB(1, 0), b3, voffB); PG8_STAGE(PG8_SB(1, 1), b3 + hstep, voffB); PG8_STAGE(PG8_SA(1, 0), a3, voffA);
;             PG8_WAIT_V(8); PG8_WAIT_L(0); PG8_BAR; PG8_MMA(1, 0, At, B0); PG8_MMA(1, 1, At, B1); PG8_BAR; PG8_SCHED;
	s_add_i32 s71, 0, 0x18000
	s_add_i32 s72, 0, 0x1c000
	v_add_u32_e32 v140, s71, v209
	v_add_u32_e32 v156, s72, v209
	ds_read_b128 v[128:131], v140
	ds_read_b128 v[132:135], v140 offset:1024
	ds_read_b128 v[136:139], v140 offset:2048
	ds_read_b128 v[140:143], v140 offset:3072
	ds_read_b128 v[144:147], v156
	ds_read_b128 v[148:151], v156 offset:1024
	ds_read_b128 v[152:155], v156 offset:2048
	ds_read_b128 v[156:159], v156 offset:3072
	s_add_u32 s44, s44, 0x80000
	s_addc_u32 s45, s45, 0
	s_mov_b32 m0, s50
	ds_read_b128 v[160:163], v213 offset:32768
	ds_read_b128 v[164:167], v213 offset:33792
	ds_read_b128 v[184:187], v213 offset:34816
	ds_read_b128 v[188:191], v213 offset:35840
	ds_read_b128 v[192:195], v213 offset:36864
	ds_read_b128 v[196:199], v213 offset:37888
	ds_read_b128 v[200:203], v213 offset:38912
	ds_read_b128 v[214:217], v213 offset:39936
	global_load_lds_dwordx4 v168, s[44:45]
	s_mov_b32 m0, s51
	s_nop 0
	global_load_lds_dwordx4 v172, s[44:45]
	s_waitcnt vmcnt(8)
	s_waitcnt lgkmcnt(0)
	v_mfma_f32_16x16x32_f16 v[120:123], v[136:139], v[160:163], v[120:123]
	v_mfma_f32_16x16x32_f16 v[124:127], v[128:131], v[160:163], v[124:127]
	v_mfma_f32_16x16x32_f16 v[104:107], v[136:139], v[184:187], v[104:107]
	v_mfma_f32_16x16x32_f16 v[108:111], v[128:131], v[184:187], v[108:111]
	s_barrier
	s_waitcnt lgkmcnt(0)
	v_mfma_f32_16x16x32_f16 v[88:91], v[136:139], v[192:195], v[88:91]
	v_mfma_f32_16x16x32_f16 v[92:95], v[128:131], v[192:195], v[92:95]
	v_mfma_f32_16x16x32_f16 v[72:75], v[136:139], v[200:203], v[72:75]
	v_mfma_f32_16x16x32_f16 v[76:79], v[128:131], v[200:203], v[76:79]
	v_mfma_f32_16x16x32_f16 v[120:123], v[140:143], v[164:167], v[120:123]
	v_mfma_f32_16x16x32_f16 v[124:127], v[132:135], v[164:167], v[124:127]
	v_mfma_f32_16x16x32_f16 v[104:107], v[140:143], v[188:191], v[104:107]
	v_mfma_f32_16x16x32_f16 v[108:111], v[132:135], v[188:191], v[108:111]
	v_mfma_f32_16x16x32_f16 v[88:91], v[140:143], v[196:199], v[88:91]
	v_mfma_f32_16x16x32_f16 v[92:95], v[132:135], v[196:199], v[92:95]
	v_mfma_f32_16x16x32_f16 v[72:75], v[140:143], v[214:217], v[72:75]
	v_mfma_f32_16x16x32_f16 v[76:79], v[132:135], v[214:217], v[76:79]
	v_mfma_f32_16x16x32_f16 v[112:115], v[152:155], v[160:163], v[112:115]
	v_mfma_f32_16x16x32_f16 v[116:119], v[144:147], v[160:163], v[116:119]
	v_mfma_f32_16x16x32_f16 v[96:99], v[152:155], v[184:187], v[96:99]
	v_mfma_f32_16x16x32_f16 v[100:103], v[144:147], v[184:187], v[100:103]
	v_mfma_f32_16x16x32_f16 v[80:83], v[152:155], v[192:195], v[80:83]
	v_mfma_f32_16x16x32_f16 v[84:87], v[144:147], v[192:195], v[84:87]
	v_mfma_f32_16x16x32_f16 v[64:67], v[152:155], v[200:203], v[64:67]
	v_mfma_f32_16x16x32_f16 v[68:71], v[144:147], v[200:203], v[68:71]
	v_mfma_f32_16x16x32_f16 v[112:115], v[156:159], v[164:167], v[112:115]
	v_mfma_f32_16x16x32_f16 v[116:119], v[148:151], v[164:167], v[116:119]
	v_mfma_f32_16x16x32_f16 v[96:99], v[156:159], v[188:191], v[96:99]
	v_mfma_f32_16x16x32_f16 v[100:103], v[148:151], v[188:191], v[100:103]
	v_mfma_f32_16x16x32_f16 v[80:83], v[156:159], v[196:199], v[80:83]
	v_mfma_f32_16x16x32_f16 v[84:87], v[148:151], v[196:199], v[84:87]
	v_mfma_f32_16x16x32_f16 v[64:67], v[156:159], v[214:217], v[64:67]
	v_mfma_f32_16x16x32_f16 v[68:71], v[148:151], v[214:217], v[68:71]
	s_barrier
	s_add_i32 s44, s71, s48
	s_mov_b32 m0, s44
	ds_read_b128 v[160:163], v213 offset:49152
	ds_read_b128 v[164:167], v213 offset:50176
	ds_read_b128 v[184:187], v213 offset:51200
	ds_read_b128 v[188:191], v213 offset:52224
	ds_read_b128 v[192:195], v213 offset:53248
	ds_read_b128 v[196:199], v213 offset:54272
	ds_read_b128 v[200:203], v213 offset:55296
	ds_read_b128 v[214:217], v213 offset:56320
	global_load_lds_dwordx4 v170, s[98:99]
	s_add_i32 m0, s44, 0x2000
	s_add_u32 s42, s42, 0x80080
	s_addc_u32 s43, s43, 0
	s_add_i32 s44, s72, s48
	global_load_lds_dwordx4 v174, s[98:99]
	s_mov_b32 m0, s44
	s_nop 0
	global_load_lds_dwordx4 v170, s[42:43]
	s_add_i32 m0, s44, 0x2000
	s_nop 0
	global_load_lds_dwordx4 v174, s[42:43]
	s_mov_b32 m0, s61
	s_nop 0
	global_load_lds_dwordx4 v168, s[100:101]
	s_mov_b32 m0, s62
	s_nop 0
	global_load_lds_dwordx4 v172, s[100:101]
	s_waitcnt vmcnt(8)
	s_waitcnt lgkmcnt(0)
	v_mfma_f32_16x16x32_f16 v[56:59], v[136:139], v[160:163], v[56:59]
	v_mfma_f32_16x16x32_f16 v[60:63], v[128:131], v[160:163], v[60:63]
	v_mfma_f32_16x16x32_f16 v[40:43], v[136:139], v[184:187], v[40:43]
	v_mfma_f32_16x16x32_f16 v[44:47], v[128:131], v[184:187], v[44:47]
	s_barrier
	s_waitcnt lgkmcnt(0)
	v_mfma_f32_16x16x32_f16 v[24:27], v[136:139], v[192:195], v[24:27]
	v_mfma_f32_16x16x32_f16 v[28:31], v[128:131], v[192:195], v[28:31]
	v_mfma_f32_16x16x32_f16 v[8:11], v[136:139], v[200:203], v[8:11]
	v_mfma_f32_16x16x32_f16 v[12:15], v[128:131], v[200:203], v[12:15]
	v_mfma_f32_16x16x32_f16 v[56:59], v[140:143], v[164:167], v[56:59]
	v_mfma_f32_16x16x32_f16 v[60:63], v[132:135], v[164:167], v[60:63]
	v_mfma_f32_16x16x32_f16 v[40:43], v[140:143], v[188:191], v[40:43]
	v_mfma_f32_16x16x32_f16 v[44:47], v[132:135], v[188:191], v[44:47]
	v_mfma_f32_16x16x32_f16 v[24:27], v[140:143], v[196:199], v[24:27]
	v_mfma_f32_16x16x32_f16 v[28:31], v[132:135], v[196:199], v[28:31]
	v_mfma_f32_16x16x32_f16 v[8:11], v[140:143], v[214:217], v[8:11]
	v_mfma_f32_16x16x32_f16 v[12:15], v[132:135], v[214:217], v[12:15]
	v_mfma_f32_16x16x32_f16 v[48:51], v[152:155], v[160:163], v[48:51]
	v_mfma_f32_16x16x32_f16 v[52:55], v[144:147], v[160:163], v[52:55]
	v_mfma_f32_16x16x32_f16 v[32:35], v[152:155], v[184:187], v[32:35]
	v_mfma_f32_16x16x32_f16 v[36:39], v[144:147], v[184:187], v[36:39]
	v_mfma_f32_16x16x32_f16 v[16:19], v[152:155], v[192:195], v[16:19]
	v_mfma_f32_16x16x32_f16 v[20:23], v[144:147], v[192:195], v[20:23]
	v_mfma_f32_16x16x32_f16 v[0:3], v[152:155], v[200:203], v[0:3]
	v_mfma_f32_16x16x32_f16 v[4:7], v[144:147], v[200:203], v[4:7]
	v_mfma_f32_16x16x32_f16 v[48:51], v[156:159], v[164:167], v[48:51]
	v_mfma_f32_16x16x32_f16 v[52:55], v[148:151], v[164:167], v[52:55]
	v_mfma_f32_16x16x32_f16 v[32:35], v[156:159], v[188:191], v[32:35]
	v_mfma_f32_16x16x32_f16 v[36:39], v[148:151], v[188:191], v[36:39]
	v_mfma_f32_16x16x32_f16 v[16:19], v[156:159], v[196:199], v[16:19]
	v_mfma_f32_16x16x32_f16 v[20:23], v[148:151], v[196:199], v[20:23]
	v_mfma_f32_16x16x32_f16 v[0:3], v[156:159], v[214:217], v[0:3]
	v_mfma_f32_16x16x32_f16 v[4:7], v[148:151], v[214:217], v[4:7]
	s_barrier
	s_add_i32 s70, s70, 2
	s_add_u32 s68, s68, 0x100
	s_addc_u32 s69, s69, 0
	s_add_u32 s40, s40, 0x100
	s_addc_u32 s41, s41, 0
	s_cmp_gt_u32 s70, 29
	s_cbranch_scc0 .LBB0_1075
	s_and_b64 vcc, exec, s[20:21]
	s_cbranch_vccz .LBB0_1078
	s_barrier

; #define PG8_STAGE(bufoff, gbase, voff) do { _Pragma("unroll") for (int _i = 0; _i < 2; ++_i) \
;         __builtin_amdgcn_global_load_lds((const unsigned*)((const char*)(gbase) + (voff)[_i]), (PG8_LAS unsigned*)(lds + (bufoff) + ldsw + _i * 8192), 16, 0, 0); } while (0)
; #define PG8_LDA(dst, b, h) do { _Pragma("unroll") for (int m = 0; m < 4; ++m) _Pragma("unroll") for (int k = 0; k < 2; ++k) dst[m][k] = *(const PG8_LAS bf16x8*)(lds + PG8_SA(b, h) + aoff + m * 2048 + k * 1024); } while (0)
; #define PG8_LDB(dst, b, h) do { _Pragma("unroll") for (int n = 0; n < 2; ++n) _Pragma("unroll") for (int k = 0; k < 2; ++k) dst[n][k] = *(const PG8_LAS bf16x8*)(lds + PG8_SB(b, h) + boff + n * 2048 + k * 1024); } while (0)
; #define PG8_MMA(ai, bj, At, Bt) do { __builtin_amdgcn_s_setprio(1); _Pragma("unroll") for (int m = 0; m < 4; ++m) _Pragma("unroll") for (int n = 0; n < 2; ++n) _Pragma("unroll") for (int k = 0; k < 2; ++k) \
;         acc[ai][bj][m][n] = __builtin_amdgcn_mfma_f32_16x16x32_f16(Bt[n][k], At[m][k], acc[ai][bj][m][n], 0, 0, 0); __builtin_amdgcn_s_setprio(0); } while (0)
; #define PG8_WAIT_V(n) asm volatile("s_waitcnt vmcnt(" #n ")" ::: "memory")
; #define PG8_WAIT_L(n) asm volatile("s_waitcnt lgkmcnt(" #n ")" ::: "memory")
; template <class Epi, class Sched, bool ALIGN_EPI = false, bool SP2 = false>
; __device__ __forceinline__ void gemm_phase(PG8_LAS unsigned char* lds, const Gemm g, const Sched& S, const Epi& E) {
;     ...
;             const bool last = (t == nt - 2);
;             const char* a1 = cA + (size_t)(t + 1) * kstep;
;             const char* a2 = last ? nA : cA + (size_t)(t + 2) * kstep; const char* b2 = last ? nB : cB + (size_t)(t + 2) * kstep;
;             const char* a3 = a2 + kstep; const char* b3 = b2 + kstep;
;             if (last && has_next) S.a_ready(nxt);
;             if constexpr (SP2) {
;             PG8_LDB(B0, 0, 0); PG8_LDB(B1, 0, 1); PG8_SCHED; PG8_LDA(At, 0, 0); PG8_STAGE(PG8_SA(1, 1), a1 + hstep, voffA);
;             PG8_WAIT_V(8); PG8_WAIT_L(0); PG8_BAR; PG8_MMA(0, 0, At, B0); PG8_MMA(0, 1, At, B1); PG8_BAR; PG8_SCHED;
;             PG8_LDA(At, 0, 1); PG8_STAGE(PG8_SB(0, 0), b2, voffB); PG8_STAGE(PG8_SB(0, 1), b2 + hstep, voffB); PG8_STAGE(PG8_SA(0, 0), a2, voffA);
;             PG8_WAIT_V(8); PG8_WAIT_L(0); PG8_BAR; PG8_MMA(1, 0, At, B0); PG8_MMA(1, 1, At, B1); PG8_BAR; PG8_SCHED;
.LBB0_1167:
	ds_read_b128 v[128:131], v198
	ds_read_b128 v[132:135], v198 offset:1024
	ds_read_b128 v[136:139], v198 offset:2048
	ds_read_b128 v[140:143], v198 offset:3072
	ds_read_b128 v[144:147], v199
	ds_read_b128 v[148:151], v199 offset:1024
	ds_read_b128 v[152:155], v199 offset:2048
	ds_read_b128 v[156:159], v199 offset:3072
	s_add_u32 s44, s42, 0xfff80080
	s_addc_u32 s45, s43, -1
	s_cmp_eq_u32 s81, 28
	s_cselect_b32 s49, s35, s45
	s_cselect_b32 s48, s72, s44
	s_cselect_b32 s45, s31, s75
	s_cselect_b32 s44, s73, s74
	s_add_i32 m0, s41, 0xc000
	ds_read_b128 v[176:179], v200
	ds_read_b128 v[180:183], v200 offset:1024
	ds_read_b128 v[184:187], v200 offset:2048
	ds_read_b128 v[188:191], v200 offset:3072
	ds_read_b128 v[208:211], v200 offset:4096
	ds_read_b128 v[212:215], v200 offset:5120
	ds_read_b128 v[216:219], v200 offset:6144
	ds_read_b128 v[220:223], v200 offset:7168
	global_load_lds_dwordx4 v170, s[42:43]
	s_add_i32 m0, s41, 0xe000
	s_nop 0
	global_load_lds_dwordx4 v168, s[42:43]
	s_waitcnt vmcnt(8)
	s_waitcnt lgkmcnt(0)
	v_mfma_f32_16x16x32_f16 v[120:123], v[136:139], v[176:179], v[120:123]
	v_mfma_f32_16x16x32_f16 v[124:127], v[128:131], v[176:179], v[124:127]
	v_mfma_f32_16x16x32_f16 v[104:107], v[136:139], v[184:187], v[104:107]
	v_mfma_f32_16x16x32_f16 v[108:111], v[128:131], v[184:187], v[108:111]
	s_barrier
	s_waitcnt lgkmcnt(0)
	v_mfma_f32_16x16x32_f16 v[88:91], v[136:139], v[208:211], v[88:91]
	v_mfma_f32_16x16x32_f16 v[92:95], v[128:131], v[208:211], v[92:95]
	v_mfma_f32_16x16x32_f16 v[72:75], v[136:139], v[216:219], v[72:75]
	v_mfma_f32_16x16x32_f16 v[76:79], v[128:131], v[216:219], v[76:79]
	v_mfma_f32_16x16x32_f16 v[120:123], v[140:143], v[180:183], v[120:123]
	v_mfma_f32_16x16x32_f16 v[124:127], v[132:135], v[180:183], v[124:127]
	v_mfma_f32_16x16x32_f16 v[104:107], v[140:143], v[188:191], v[104:107]
	v_mfma_f32_16x16x32_f16 v[108:111], v[132:135], v[188:191], v[108:111]
	v_mfma_f32_16x16x32_f16 v[88:91], v[140:143], v[212:215], v[88:91]
	v_mfma_f32_16x16x32_f16 v[92:95], v[132:135], v[212:215], v[92:95]
	v_mfma_f32_16x16x32_f16 v[72:75], v[140:143], v[220:223], v[72:75]
	v_mfma_f32_16x16x32_f16 v[76:79], v[132:135], v[220:223], v[76:79]
	v_mfma_f32_16x16x32_f16 v[112:115], v[152:155], v[176:179], v[112:115]
	v_mfma_f32_16x16x32_f16 v[116:119], v[144:147], v[176:179], v[116:119]
	v_mfma_f32_16x16x32_f16 v[96:99], v[152:155], v[184:187], v[96:99]
	v_mfma_f32_16x16x32_f16 v[100:103], v[144:147], v[184:187], v[100:103]
	v_mfma_f32_16x16x32_f16 v[80:83], v[152:155], v[208:211], v[80:83]
	v_mfma_f32_16x16x32_f16 v[84:87], v[144:147], v[208:211], v[84:87]
	v_mfma_f32_16x16x32_f16 v[64:67], v[152:155], v[216:219], v[64:67]
	v_mfma_f32_16x16x32_f16 v[68:71], v[144:147], v[216:219], v[68:71]
	v_mfma_f32_16x16x32_f16 v[112:115], v[156:159], v[180:183], v[112:115]
	v_mfma_f32_16x16x32_f16 v[116:119], v[148:151], v[180:183], v[116:119]
	v_mfma_f32_16x16x32_f16 v[96:99], v[156:159], v[188:191], v[96:99]
	v_mfma_f32_16x16x32_f16 v[100:103], v[148:151], v[188:191], v[100:103]
	v_mfma_f32_16x16x32_f16 v[80:83], v[156:159], v[212:215], v[80:83]
	v_mfma_f32_16x16x32_f16 v[84:87], v[148:151], v[212:215], v[84:87]
	v_mfma_f32_16x16x32_f16 v[64:67], v[156:159], v[220:223], v[64:67]
	v_mfma_f32_16x16x32_f16 v[68:71], v[148:151], v[220:223], v[68:71]
	s_barrier
	s_add_i32 s82, s65, s52
	s_add_u32 s98, s44, s16
	s_addc_u32 s99, s45, s17
	s_mov_b32 m0, s82
	ds_read_b128 v[176:179], v200 offset:16384
	ds_read_b128 v[180:183], v200 offset:17408
	ds_read_b128 v[184:187], v200 offset:18432
	ds_read_b128 v[188:191], v200 offset:19456
	ds_read_b128 v[208:211], v200 offset:20480
	ds_read_b128 v[212:215], v200 offset:21504
	ds_read_b128 v[216:219], v200 offset:22528
	ds_read_b128 v[220:223], v200 offset:23552
	global_load_lds_dwordx4 v162, s[44:45]
	s_add_i32 m0, s82, 0x2000
	s_add_u32 s82, s44, 0x80000
	s_addc_u32 s83, s45, 0
	s_add_i32 s86, s66, s52
	global_load_lds_dwordx4 v166, s[44:45]
	s_mov_b32 m0, s86
	s_nop 0
	global_load_lds_dwordx4 v162, s[82:83]
	s_add_i32 m0, s86, 0x2000
	s_nop 0
	global_load_lds_dwordx4 v166, s[82:83]
	s_add_u32 s100, s48, s16
	s_addc_u32 s101, s49, s17
	s_mov_b32 m0, s41
	s_nop 0
	global_load_lds_dwordx4 v160, s[48:49]
	s_mov_b32 m0, s53
	s_nop 0
	global_load_lds_dwordx4 v164, s[48:49]
	s_waitcnt vmcnt(8)
	s_waitcnt lgkmcnt(0)
	v_mfma_f32_16x16x32_f16 v[56:59], v[136:139], v[176:179], v[56:59]
	v_mfma_f32_16x16x32_f16 v[60:63], v[128:131], v[176:179], v[60:63]
	v_mfma_f32_16x16x32_f16 v[40:43], v[136:139], v[184:187], v[40:43]
	v_mfma_f32_16x16x32_f16 v[44:47], v[128:131], v[184:187], v[44:47]
	s_barrier
	s_waitcnt lgkmcnt(0)
	v_mfma_f32_16x16x32_f16 v[24:27], v[136:139], v[208:211], v[24:27]
	v_mfma_f32_16x16x32_f16 v[28:31], v[128:131], v[208:211], v[28:31]
	v_mfma_f32_16x16x32_f16 v[8:11], v[136:139], v[216:219], v[8:11]
	v_mfma_f32_16x16x32_f16 v[12:15], v[128:131], v[216:219], v[12:15]
	v_mfma_f32_16x16x32_f16 v[56:59], v[140:143], v[180:183], v[56:59]
	v_mfma_f32_16x16x32_f16 v[60:63], v[132:135], v[180:183], v[60:63]
	v_mfma_f32_16x16x32_f16 v[40:43], v[140:143], v[188:191], v[40:43]
	v_mfma_f32_16x16x32_f16 v[44:47], v[132:135], v[188:191], v[44:47]
	v_mfma_f32_16x16x32_f16 v[24:27], v[140:143], v[212:215], v[24:27]
	v_mfma_f32_16x16x32_f16 v[28:31], v[132:135], v[212:215], v[28:31]
	v_mfma_f32_16x16x32_f16 v[8:11], v[140:143], v[220:223], v[8:11]
	v_mfma_f32_16x16x32_f16 v[12:15], v[132:135], v[220:223], v[12:15]
	v_mfma_f32_16x16x32_f16 v[48:51], v[152:155], v[176:179], v[48:51]
	v_mfma_f32_16x16x32_f16 v[52:55], v[144:147], v[176:179], v[52:55]
	v_mfma_f32_16x16x32_f16 v[32:35], v[152:155], v[184:187], v[32:35]
	v_mfma_f32_16x16x32_f16 v[36:39], v[144:147], v[184:187], v[36:39]
	v_mfma_f32_16x16x32_f16 v[16:19], v[152:155], v[208:211], v[16:19]
	v_mfma_f32_16x16x32_f16 v[20:23], v[144:147], v[208:211], v[20:23]
	v_mfma_f32_16x16x32_f16 v[0:3], v[152:155], v[216:219], v[0:3]
	v_mfma_f32_16x16x32_f16 v[4:7], v[144:147], v[216:219], v[4:7]
	v_mfma_f32_16x16x32_f16 v[48:51], v[156:159], v[180:183], v[48:51]
	v_mfma_f32_16x16x32_f16 v[52:55], v[148:151], v[180:183], v[52:55]
	v_mfma_f32_16x16x32_f16 v[32:35], v[156:159], v[188:191], v[32:35]
	v_mfma_f32_16x16x32_f16 v[36:39], v[148:151], v[188:191], v[36:39]
	v_mfma_f32_16x16x32_f16 v[16:19], v[156:159], v[212:215], v[16:19]
	v_mfma_f32_16x16x32_f16 v[20:23], v[148:151], v[212:215], v[20:23]
	v_mfma_f32_16x16x32_f16 v[0:3], v[156:159], v[220:223], v[0:3]
	v_mfma_f32_16x16x32_f16 v[4:7], v[148:151], v[220:223], v[4:7]
	s_barrier
; #define PG8_STAGE(bufoff, gbase, voff) do { _Pragma("unroll") for (int _i = 0; _i < 2; ++_i) \
;         __builtin_amdgcn_global_load_lds((const unsigned*)((const char*)(gbase) + (voff)[_i]), (PG8_LAS unsigned*)(lds + (bufoff) + ldsw + _i * 8192), 16, 0, 0); } while (0)
; #define PG8_LDA(dst, b, h) do { _Pragma("unroll") for (int m = 0; m < 4; ++m) _Pragma("unroll") for (int k = 0; k < 2; ++k) dst[m][k] = *(const PG8_LAS bf16x8*)(lds + PG8_SA(b, h) + aoff + m * 2048 + k * 1024); } while (0)
; #define PG8_LDB(dst, b, h) do { _Pragma("unroll") for (int n = 0; n < 2; ++n) _Pragma("unroll") for (int k = 0; k < 2; ++k) dst[n][k] = *(const PG8_LAS bf16x8*)(lds + PG8_SB(b, h) + boff + n * 2048 + k * 1024); } while (0)
; #define PG8_MMA(ai, bj, At, Bt) do { __builtin_amdgcn_s_setprio(1); _Pragma("unroll") for (int m = 0; m < 4; ++m) _Pragma("unroll") for (int n = 0; n < 2; ++n) _Pragma("unroll") for (int k = 0; k < 2; ++k) \
;         acc[ai][bj][m][n] = __builtin_amdgcn_mfma_f32_16x16x32_f16(Bt[n][k], At[m][k], acc[ai][bj][m][n], 0, 0, 0); __builtin_amdgcn_s_setprio(0); } while (0)
; #define PG8_WAIT_V(n) asm volatile("s_waitcnt vmcnt(" #n ")" ::: "memory")
; #define PG8_WAIT_L(n) asm volatile("s_waitcnt lgkmcnt(" #n ")" ::: "memory")
; #define PG8_BAR __builtin_amdgcn_s_barrier()
; #define PG8_SCHED __builtin_amdgcn_sched_barrier(0)
; template <class Epi, class Sched, bool ALIGN_EPI = false, bool SP2 = false>
; __device__ __forceinline__ void gemm_phase(PG8_LAS unsigned char* lds, const Gemm g, const Sched& S, const Epi& E) {
;     ...
;             PG8_LDB(B0, 1, 0); PG8_LDB(B1, 1, 1); PG8_SCHED; PG8_LDA(At, 1, 0); PG8_STAGE(PG8_SA(0, 1), a2 + hstep, voffA);
;             PG8_WAIT_V(8); PG8_WAIT_L(0); PG8_BAR; PG8_MMA(0, 0, At, B0); PG8_MMA(0, 1, At, B1); PG8_BAR; PG8_SCHED;
;             PG8_LDA(At, 1, 1); PG8_STAGE(PG8_SB(1, 0), b3, voffB); PG8_STAGE(PG8_SB(1, 1), b3 + hstep, voffB); PG8_STAGE(PG8_SA(1, 0), a3, voffA);
;             PG8_WAIT_V(8); PG8_WAIT_L(0); PG8_BAR; PG8_MMA(1, 0, At, B0); PG8_MMA(1, 1, At, B1); PG8_BAR; PG8_SCHED;
	s_add_i32 s82, 0, 0x18000
	s_add_i32 s83, 0, 0x1c000
	v_add_u32_e32 v140, s82, v196
	v_add_u32_e32 v156, s83, v196
	ds_read_b128 v[128:131], v140
	ds_read_b128 v[132:135], v140 offset:1024
	ds_read_b128 v[136:139], v140 offset:2048
	ds_read_b128 v[140:143], v140 offset:3072
	ds_read_b128 v[144:147], v156
	ds_read_b128 v[148:151], v156 offset:1024
	ds_read_b128 v[152:155], v156 offset:2048
	ds_read_b128 v[156:159], v156 offset:3072
	s_add_u32 s48, s48, 0x80000
	s_addc_u32 s49, s49, 0
	s_mov_b32 m0, s60
	ds_read_b128 v[176:179], v200 offset:32768
	ds_read_b128 v[180:183], v200 offset:33792
	ds_read_b128 v[184:187], v200 offset:34816
	ds_read_b128 v[188:191], v200 offset:35840
	ds_read_b128 v[208:211], v200 offset:36864
	ds_read_b128 v[212:215], v200 offset:37888
	ds_read_b128 v[216:219], v200 offset:38912
	ds_read_b128 v[220:223], v200 offset:39936
	global_load_lds_dwordx4 v160, s[48:49]
	s_mov_b32 m0, s61
	s_nop 0
	global_load_lds_dwordx4 v164, s[48:49]
	s_waitcnt vmcnt(8)
	s_waitcnt lgkmcnt(0)
	v_mfma_f32_16x16x32_f16 v[120:123], v[136:139], v[176:179], v[120:123]
	v_mfma_f32_16x16x32_f16 v[124:127], v[128:131], v[176:179], v[124:127]
	v_mfma_f32_16x16x32_f16 v[104:107], v[136:139], v[184:187], v[104:107]
	v_mfma_f32_16x16x32_f16 v[108:111], v[128:131], v[184:187], v[108:111]
	s_barrier
	s_waitcnt lgkmcnt(0)
	v_mfma_f32_16x16x32_f16 v[88:91], v[136:139], v[208:211], v[88:91]
	v_mfma_f32_16x16x32_f16 v[92:95], v[128:131], v[208:211], v[92:95]
	v_mfma_f32_16x16x32_f16 v[72:75], v[136:139], v[216:219], v[72:75]
	v_mfma_f32_16x16x32_f16 v[76:79], v[128:131], v[216:219], v[76:79]
	v_mfma_f32_16x16x32_f16 v[120:123], v[140:143], v[180:183], v[120:123]
	v_mfma_f32_16x16x32_f16 v[124:127], v[132:135], v[180:183], v[124:127]
	v_mfma_f32_16x16x32_f16 v[104:107], v[140:143], v[188:191], v[104:107]
	v_mfma_f32_16x16x32_f16 v[108:111], v[132:135], v[188:191], v[108:111]
	v_mfma_f32_16x16x32_f16 v[88:91], v[140:143], v[212:215], v[88:91]
	v_mfma_f32_16x16x32_f16 v[92:95], v[132:135], v[212:215], v[92:95]
	v_mfma_f32_16x16x32_f16 v[72:75], v[140:143], v[220:223], v[72:75]
	v_mfma_f32_16x16x32_f16 v[76:79], v[132:135], v[220:223], v[76:79]
	v_mfma_f32_16x16x32_f16 v[112:115], v[152:155], v[176:179], v[112:115]
	v_mfma_f32_16x16x32_f16 v[116:119], v[144:147], v[176:179], v[116:119]
	v_mfma_f32_16x16x32_f16 v[96:99], v[152:155], v[184:187], v[96:99]
	v_mfma_f32_16x16x32_f16 v[100:103], v[144:147], v[184:187], v[100:103]
	v_mfma_f32_16x16x32_f16 v[80:83], v[152:155], v[208:211], v[80:83]
	v_mfma_f32_16x16x32_f16 v[84:87], v[144:147], v[208:211], v[84:87]
	v_mfma_f32_16x16x32_f16 v[64:67], v[152:155], v[216:219], v[64:67]
	v_mfma_f32_16x16x32_f16 v[68:71], v[144:147], v[216:219], v[68:71]
	v_mfma_f32_16x16x32_f16 v[112:115], v[156:159], v[180:183], v[112:115]
	v_mfma_f32_16x16x32_f16 v[116:119], v[148:151], v[180:183], v[116:119]
	v_mfma_f32_16x16x32_f16 v[96:99], v[156:159], v[188:191], v[96:99]
	v_mfma_f32_16x16x32_f16 v[100:103], v[148:151], v[188:191], v[100:103]
	v_mfma_f32_16x16x32_f16 v[80:83], v[156:159], v[212:215], v[80:83]
	v_mfma_f32_16x16x32_f16 v[84:87], v[148:151], v[212:215], v[84:87]
	v_mfma_f32_16x16x32_f16 v[64:67], v[156:159], v[220:223], v[64:67]
	v_mfma_f32_16x16x32_f16 v[68:71], v[148:151], v[220:223], v[68:71]
	s_barrier
	s_add_i32 s48, s82, s52
	s_mov_b32 m0, s48
	ds_read_b128 v[176:179], v200 offset:49152
	ds_read_b128 v[180:183], v200 offset:50176
	ds_read_b128 v[184:187], v200 offset:51200
	ds_read_b128 v[188:191], v200 offset:52224
	ds_read_b128 v[208:211], v200 offset:53248
	ds_read_b128 v[212:215], v200 offset:54272
	ds_read_b128 v[216:219], v200 offset:55296
	ds_read_b128 v[220:223], v200 offset:56320
	global_load_lds_dwordx4 v162, s[98:99]
	s_add_i32 m0, s48, 0x2000
	s_add_u32 s44, s44, 0x80080
	s_addc_u32 s45, s45, 0
	s_add_i32 s48, s83, s52
	global_load_lds_dwordx4 v166, s[98:99]
	s_mov_b32 m0, s48
	s_nop 0
	global_load_lds_dwordx4 v162, s[44:45]
	s_add_i32 m0, s48, 0x2000
	s_nop 0
	global_load_lds_dwordx4 v166, s[44:45]
	s_mov_b32 m0, s63
	s_nop 0
	global_load_lds_dwordx4 v160, s[100:101]
	s_mov_b32 m0, s64
	s_nop 0
	global_load_lds_dwordx4 v164, s[100:101]
	s_waitcnt vmcnt(8)
	s_waitcnt lgkmcnt(0)
	v_mfma_f32_16x16x32_f16 v[56:59], v[136:139], v[176:179], v[56:59]
	v_mfma_f32_16x16x32_f16 v[60:63], v[128:131], v[176:179], v[60:63]
	v_mfma_f32_16x16x32_f16 v[40:43], v[136:139], v[184:187], v[40:43]
	v_mfma_f32_16x16x32_f16 v[44:47], v[128:131], v[184:187], v[44:47]
	s_barrier
	s_waitcnt lgkmcnt(0)
	v_mfma_f32_16x16x32_f16 v[24:27], v[136:139], v[208:211], v[24:27]
	v_mfma_f32_16x16x32_f16 v[28:31], v[128:131], v[208:211], v[28:31]
	v_mfma_f32_16x16x32_f16 v[8:11], v[136:139], v[216:219], v[8:11]
	v_mfma_f32_16x16x32_f16 v[12:15], v[128:131], v[216:219], v[12:15]
	v_mfma_f32_16x16x32_f16 v[56:59], v[140:143], v[180:183], v[56:59]
	v_mfma_f32_16x16x32_f16 v[60:63], v[132:135], v[180:183], v[60:63]
	v_mfma_f32_16x16x32_f16 v[40:43], v[140:143], v[188:191], v[40:43]
	v_mfma_f32_16x16x32_f16 v[44:47], v[132:135], v[188:191], v[44:47]
	v_mfma_f32_16x16x32_f16 v[24:27], v[140:143], v[212:215], v[24:27]
	v_mfma_f32_16x16x32_f16 v[28:31], v[132:135], v[212:215], v[28:31]
	v_mfma_f32_16x16x32_f16 v[8:11], v[140:143], v[220:223], v[8:11]
	v_mfma_f32_16x16x32_f16 v[12:15], v[132:135], v[220:223], v[12:15]
	v_mfma_f32_16x16x32_f16 v[48:51], v[152:155], v[176:179], v[48:51]
	v_mfma_f32_16x16x32_f16 v[52:55], v[144:147], v[176:179], v[52:55]
	v_mfma_f32_16x16x32_f16 v[32:35], v[152:155], v[184:187], v[32:35]
	v_mfma_f32_16x16x32_f16 v[36:39], v[144:147], v[184:187], v[36:39]
	v_mfma_f32_16x16x32_f16 v[16:19], v[152:155], v[208:211], v[16:19]
	v_mfma_f32_16x16x32_f16 v[20:23], v[144:147], v[208:211], v[20:23]
	v_mfma_f32_16x16x32_f16 v[0:3], v[152:155], v[216:219], v[0:3]
	v_mfma_f32_16x16x32_f16 v[4:7], v[144:147], v[216:219], v[4:7]
	v_mfma_f32_16x16x32_f16 v[48:51], v[156:159], v[180:183], v[48:51]
	v_mfma_f32_16x16x32_f16 v[52:55], v[148:151], v[180:183], v[52:55]
	v_mfma_f32_16x16x32_f16 v[32:35], v[156:159], v[188:191], v[32:35]
	v_mfma_f32_16x16x32_f16 v[36:39], v[148:151], v[188:191], v[36:39]
	v_mfma_f32_16x16x32_f16 v[16:19], v[156:159], v[212:215], v[16:19]
	v_mfma_f32_16x16x32_f16 v[20:23], v[148:151], v[212:215], v[20:23]
	v_mfma_f32_16x16x32_f16 v[0:3], v[156:159], v[220:223], v[0:3]
	v_mfma_f32_16x16x32_f16 v[4:7], v[148:151], v[220:223], v[4:7]
	s_barrier
	s_add_i32 s81, s81, 2
	s_add_u32 s74, s74, 0x100
	s_addc_u32 s75, s75, 0
	s_add_u32 s42, s42, 0x100
	s_addc_u32 s43, s43, 0
	s_cmp_gt_u32 s81, 29
	s_cbranch_scc0 .LBB0_1167
	s_and_b64 vcc, exec, s[18:19]
	s_cbranch_vccz .LBB0_1170
	s_barrier

; #define PG8_STAGE(bufoff, gbase, voff) do { _Pragma("unroll") for (int _i = 0; _i < 2; ++_i) \
;         __builtin_amdgcn_global_load_lds((const unsigned*)((const char*)(gbase) + (voff)[_i]), (PG8_LAS unsigned*)(lds + (bufoff) + ldsw + _i * 8192), 16, 0, 0); } while (0)
; #define PG8_LDA(dst, b, h) do { _Pragma("unroll") for (int m = 0; m < 4; ++m) _Pragma("unroll") for (int k = 0; k < 2; ++k) dst[m][k] = *(const PG8_LAS bf16x8*)(lds + PG8_SA(b, h) + aoff + m * 2048 + k * 1024); } while (0)
; #define PG8_LDB(dst, b, h) do { _Pragma("unroll") for (int n = 0; n < 2; ++n) _Pragma("unroll") for (int k = 0; k < 2; ++k) dst[n][k] = *(const PG8_LAS bf16x8*)(lds + PG8_SB(b, h) + boff + n * 2048 + k * 1024); } while (0)
; #define PG8_MMA(ai, bj, At, Bt) do { __builtin_amdgcn_s_setprio(1); _Pragma("unroll") for (int m = 0; m < 4; ++m) _Pragma("unroll") for (int n = 0; n < 2; ++n) _Pragma("unroll") for (int k = 0; k < 2; ++k) \
;         acc[ai][bj][m][n] = __builtin_amdgcn_mfma_f32_16x16x32_f16(Bt[n][k], At[m][k], acc[ai][bj][m][n], 0, 0, 0); __builtin_amdgcn_s_setprio(0); } while (0)
; #define PG8_WAIT_V(n) asm volatile("s_waitcnt vmcnt(" #n ")" ::: "memory")
; #define PG8_WAIT_L(n) asm volatile("s_waitcnt lgkmcnt(" #n ")" ::: "memory")
; template <class Epi, class Sched, bool ALIGN_EPI = false, bool SP2 = false>
; __device__ __forceinline__ void gemm_phase(PG8_LAS unsigned char* lds, const Gemm g, const Sched& S, const Epi& E) {
;     ...
;             const bool last = (t == nt - 2);
;             const char* a1 = cA + (size_t)(t + 1) * kstep;
;             const char* a2 = last ? nA : cA + (size_t)(t + 2) * kstep; const char* b2 = last ? nB : cB + (size_t)(t + 2) * kstep;
;             const char* a3 = a2 + kstep; const char* b3 = b2 + kstep;
;             if (last && has_next) S.a_ready(nxt);
;             if constexpr (SP2) {
;             PG8_LDB(B0, 0, 0); PG8_LDB(B1, 0, 1); PG8_SCHED; PG8_LDA(At, 0, 0); PG8_STAGE(PG8_SA(1, 1), a1 + hstep, voffA);
;             PG8_WAIT_V(8); PG8_WAIT_L(0); PG8_BAR; PG8_MMA(0, 0, At, B0); PG8_MMA(0, 1, At, B1); PG8_BAR; PG8_SCHED;
;             PG8_LDA(At, 0, 1); PG8_STAGE(PG8_SB(0, 0), b2, voffB); PG8_STAGE(PG8_SB(0, 1), b2 + hstep, voffB); PG8_STAGE(PG8_SA(0, 0), a2, voffA);
;             PG8_WAIT_V(8); PG8_WAIT_L(0); PG8_BAR; PG8_MMA(1, 0, At, B0); PG8_MMA(1, 1, At, B1); PG8_BAR; PG8_SCHED;
.LBB0_1243:
	ds_read_b128 v[128:131], v189
	ds_read_b128 v[132:135], v189 offset:1024
	ds_read_b128 v[136:139], v189 offset:2048
	ds_read_b128 v[140:143], v189 offset:3072
	ds_read_b128 v[144:147], v190
	ds_read_b128 v[148:151], v190 offset:1024
	ds_read_b128 v[152:155], v190 offset:2048
	ds_read_b128 v[156:159], v190 offset:3072
	s_add_u32 s34, s30, 0xffe00080
	s_addc_u32 s35, s31, -1
	s_cmpk_eq_i32 s61, 0x7c
	s_cselect_b32 s37, s23, s35
	s_cselect_b32 s36, s51, s34
	s_cselect_b32 s35, s21, s60
	s_cselect_b32 s34, s52, s53
	s_add_i32 m0, s29, 0xc000
	ds_read_b128 v[176:179], v191
	ds_read_b128 v[180:183], v191 offset:1024
	ds_read_b128 v[192:195], v191 offset:2048
	ds_read_b128 v[196:199], v191 offset:3072
	ds_read_b128 v[200:203], v191 offset:4096
	ds_read_b128 v[208:211], v191 offset:5120
	ds_read_b128 v[212:215], v191 offset:6144
	ds_read_b128 v[216:219], v191 offset:7168
	global_load_lds_dwordx4 v170, s[30:31]
	s_add_i32 m0, s29, 0xe000
	s_nop 0
	global_load_lds_dwordx4 v168, s[30:31]
	s_waitcnt vmcnt(8)
	s_waitcnt lgkmcnt(0)
	v_mfma_f32_16x16x32_f16 v[120:123], v[136:139], v[176:179], v[120:123]
	v_mfma_f32_16x16x32_f16 v[124:127], v[128:131], v[176:179], v[124:127]
	v_mfma_f32_16x16x32_f16 v[104:107], v[136:139], v[192:195], v[104:107]
	v_mfma_f32_16x16x32_f16 v[108:111], v[128:131], v[192:195], v[108:111]
	s_barrier
	s_waitcnt lgkmcnt(0)
	v_mfma_f32_16x16x32_f16 v[88:91], v[136:139], v[200:203], v[88:91]
	v_mfma_f32_16x16x32_f16 v[92:95], v[128:131], v[200:203], v[92:95]
	v_mfma_f32_16x16x32_f16 v[72:75], v[136:139], v[212:215], v[72:75]
	v_mfma_f32_16x16x32_f16 v[76:79], v[128:131], v[212:215], v[76:79]
	v_mfma_f32_16x16x32_f16 v[120:123], v[140:143], v[180:183], v[120:123]
	v_mfma_f32_16x16x32_f16 v[124:127], v[132:135], v[180:183], v[124:127]
	v_mfma_f32_16x16x32_f16 v[104:107], v[140:143], v[196:199], v[104:107]
	v_mfma_f32_16x16x32_f16 v[108:111], v[132:135], v[196:199], v[108:111]
	v_mfma_f32_16x16x32_f16 v[88:91], v[140:143], v[208:211], v[88:91]
	v_mfma_f32_16x16x32_f16 v[92:95], v[132:135], v[208:211], v[92:95]
	v_mfma_f32_16x16x32_f16 v[72:75], v[140:143], v[216:219], v[72:75]
	v_mfma_f32_16x16x32_f16 v[76:79], v[132:135], v[216:219], v[76:79]
	v_mfma_f32_16x16x32_f16 v[112:115], v[152:155], v[176:179], v[112:115]
	v_mfma_f32_16x16x32_f16 v[116:119], v[144:147], v[176:179], v[116:119]
	v_mfma_f32_16x16x32_f16 v[96:99], v[152:155], v[192:195], v[96:99]
	v_mfma_f32_16x16x32_f16 v[100:103], v[144:147], v[192:195], v[100:103]
	v_mfma_f32_16x16x32_f16 v[80:83], v[152:155], v[200:203], v[80:83]
	v_mfma_f32_16x16x32_f16 v[84:87], v[144:147], v[200:203], v[84:87]
	v_mfma_f32_16x16x32_f16 v[64:67], v[152:155], v[212:215], v[64:67]
	v_mfma_f32_16x16x32_f16 v[68:71], v[144:147], v[212:215], v[68:71]
	v_mfma_f32_16x16x32_f16 v[112:115], v[156:159], v[180:183], v[112:115]
	v_mfma_f32_16x16x32_f16 v[116:119], v[148:151], v[180:183], v[116:119]
	v_mfma_f32_16x16x32_f16 v[96:99], v[156:159], v[196:199], v[96:99]
	v_mfma_f32_16x16x32_f16 v[100:103], v[148:151], v[196:199], v[100:103]
	v_mfma_f32_16x16x32_f16 v[80:83], v[156:159], v[208:211], v[80:83]
	v_mfma_f32_16x16x32_f16 v[84:87], v[148:151], v[208:211], v[84:87]
	v_mfma_f32_16x16x32_f16 v[64:67], v[156:159], v[216:219], v[64:67]
	v_mfma_f32_16x16x32_f16 v[68:71], v[148:151], v[216:219], v[68:71]
	s_barrier
	s_add_i32 s62, s48, s39
	s_add_u32 s98, s34, s12
	s_addc_u32 s99, s35, s13
	s_mov_b32 m0, s62
	ds_read_b128 v[176:179], v191 offset:16384
	ds_read_b128 v[180:183], v191 offset:17408
	ds_read_b128 v[192:195], v191 offset:18432
	ds_read_b128 v[196:199], v191 offset:19456
	ds_read_b128 v[200:203], v191 offset:20480
	ds_read_b128 v[208:211], v191 offset:21504
	ds_read_b128 v[212:215], v191 offset:22528
	ds_read_b128 v[216:219], v191 offset:23552
	global_load_lds_dwordx4 v162, s[34:35]
	s_add_i32 m0, s62, 0x2000
	s_add_u32 s62, s34, 0x200000
	s_addc_u32 s63, s35, 0
	s_add_i32 s64, s49, s39
	global_load_lds_dwordx4 v166, s[34:35]
	s_mov_b32 m0, s64
	s_nop 0
	global_load_lds_dwordx4 v162, s[62:63]
	s_add_i32 m0, s64, 0x2000
	s_nop 0
	global_load_lds_dwordx4 v166, s[62:63]
	s_add_u32 s100, s36, s12
	s_addc_u32 s101, s37, s13
	s_mov_b32 m0, s29
	s_nop 0
	global_load_lds_dwordx4 v160, s[36:37]
	s_mov_b32 m0, s40
	s_nop 0
	global_load_lds_dwordx4 v164, s[36:37]
	s_waitcnt vmcnt(8)
	s_waitcnt lgkmcnt(0)
	v_mfma_f32_16x16x32_f16 v[56:59], v[136:139], v[176:179], v[56:59]
	v_mfma_f32_16x16x32_f16 v[60:63], v[128:131], v[176:179], v[60:63]
	v_mfma_f32_16x16x32_f16 v[40:43], v[136:139], v[192:195], v[40:43]
	v_mfma_f32_16x16x32_f16 v[44:47], v[128:131], v[192:195], v[44:47]
	s_barrier
	s_waitcnt lgkmcnt(0)
	v_mfma_f32_16x16x32_f16 v[24:27], v[136:139], v[200:203], v[24:27]
	v_mfma_f32_16x16x32_f16 v[28:31], v[128:131], v[200:203], v[28:31]
	v_mfma_f32_16x16x32_f16 v[8:11], v[136:139], v[212:215], v[8:11]
	v_mfma_f32_16x16x32_f16 v[12:15], v[128:131], v[212:215], v[12:15]
	v_mfma_f32_16x16x32_f16 v[56:59], v[140:143], v[180:183], v[56:59]
	v_mfma_f32_16x16x32_f16 v[60:63], v[132:135], v[180:183], v[60:63]
	v_mfma_f32_16x16x32_f16 v[40:43], v[140:143], v[196:199], v[40:43]
	v_mfma_f32_16x16x32_f16 v[44:47], v[132:135], v[196:199], v[44:47]
	v_mfma_f32_16x16x32_f16 v[24:27], v[140:143], v[208:211], v[24:27]
	v_mfma_f32_16x16x32_f16 v[28:31], v[132:135], v[208:211], v[28:31]
	v_mfma_f32_16x16x32_f16 v[8:11], v[140:143], v[216:219], v[8:11]
	v_mfma_f32_16x16x32_f16 v[12:15], v[132:135], v[216:219], v[12:15]
	v_mfma_f32_16x16x32_f16 v[48:51], v[152:155], v[176:179], v[48:51]
	v_mfma_f32_16x16x32_f16 v[52:55], v[144:147], v[176:179], v[52:55]
	v_mfma_f32_16x16x32_f16 v[32:35], v[152:155], v[192:195], v[32:35]
	v_mfma_f32_16x16x32_f16 v[36:39], v[144:147], v[192:195], v[36:39]
	v_mfma_f32_16x16x32_f16 v[16:19], v[152:155], v[200:203], v[16:19]
	v_mfma_f32_16x16x32_f16 v[20:23], v[144:147], v[200:203], v[20:23]
	v_mfma_f32_16x16x32_f16 v[0:3], v[152:155], v[212:215], v[0:3]
	v_mfma_f32_16x16x32_f16 v[4:7], v[144:147], v[212:215], v[4:7]
	v_mfma_f32_16x16x32_f16 v[48:51], v[156:159], v[180:183], v[48:51]
	v_mfma_f32_16x16x32_f16 v[52:55], v[148:151], v[180:183], v[52:55]
	v_mfma_f32_16x16x32_f16 v[32:35], v[156:159], v[196:199], v[32:35]
	v_mfma_f32_16x16x32_f16 v[36:39], v[148:151], v[196:199], v[36:39]
	v_mfma_f32_16x16x32_f16 v[16:19], v[156:159], v[208:211], v[16:19]
	v_mfma_f32_16x16x32_f16 v[20:23], v[148:151], v[208:211], v[20:23]
	v_mfma_f32_16x16x32_f16 v[0:3], v[156:159], v[216:219], v[0:3]
	v_mfma_f32_16x16x32_f16 v[4:7], v[148:151], v[216:219], v[4:7]
	s_barrier
; #define PG8_STAGE(bufoff, gbase, voff) do { _Pragma("unroll") for (int _i = 0; _i < 2; ++_i) \
;         __builtin_amdgcn_global_load_lds((const unsigned*)((const char*)(gbase) + (voff)[_i]), (PG8_LAS unsigned*)(lds + (bufoff) + ldsw + _i * 8192), 16, 0, 0); } while (0)
; #define PG8_LDA(dst, b, h) do { _Pragma("unroll") for (int m = 0; m < 4; ++m) _Pragma("unroll") for (int k = 0; k < 2; ++k) dst[m][k] = *(const PG8_LAS bf16x8*)(lds + PG8_SA(b, h) + aoff + m * 2048 + k * 1024); } while (0)
; #define PG8_LDB(dst, b, h) do { _Pragma("unroll") for (int n = 0; n < 2; ++n) _Pragma("unroll") for (int k = 0; k < 2; ++k) dst[n][k] = *(const PG8_LAS bf16x8*)(lds + PG8_SB(b, h) + boff + n * 2048 + k * 1024); } while (0)
; #define PG8_MMA(ai, bj, At, Bt) do { __builtin_amdgcn_s_setprio(1); _Pragma("unroll") for (int m = 0; m < 4; ++m) _Pragma("unroll") for (int n = 0; n < 2; ++n) _Pragma("unroll") for (int k = 0; k < 2; ++k) \
;         acc[ai][bj][m][n] = __builtin_amdgcn_mfma_f32_16x16x32_f16(Bt[n][k], At[m][k], acc[ai][bj][m][n], 0, 0, 0); __builtin_amdgcn_s_setprio(0); } while (0)
; #define PG8_WAIT_V(n) asm volatile("s_waitcnt vmcnt(" #n ")" ::: "memory")
; #define PG8_WAIT_L(n) asm volatile("s_waitcnt lgkmcnt(" #n ")" ::: "memory")
; #define PG8_BAR __builtin_amdgcn_s_barrier()
; #define PG8_SCHED __builtin_amdgcn_sched_barrier(0)
; template <class Epi, class Sched, bool ALIGN_EPI = false, bool SP2 = false>
; __device__ __forceinline__ void gemm_phase(PG8_LAS unsigned char* lds, const Gemm g, const Sched& S, const Epi& E) {
;     ...
;             PG8_LDB(B0, 1, 0); PG8_LDB(B1, 1, 1); PG8_SCHED; PG8_LDA(At, 1, 0); PG8_STAGE(PG8_SA(0, 1), a2 + hstep, voffA);
;             PG8_WAIT_V(8); PG8_WAIT_L(0); PG8_BAR; PG8_MMA(0, 0, At, B0); PG8_MMA(0, 1, At, B1); PG8_BAR; PG8_SCHED;
;             PG8_LDA(At, 1, 1); PG8_STAGE(PG8_SB(1, 0), b3, voffB); PG8_STAGE(PG8_SB(1, 1), b3 + hstep, voffB); PG8_STAGE(PG8_SA(1, 0), a3, voffA);
;             PG8_WAIT_V(8); PG8_WAIT_L(0); PG8_BAR; PG8_MMA(1, 0, At, B0); PG8_MMA(1, 1, At, B1); PG8_BAR; PG8_SCHED;
	s_add_i32 s62, 0, 0x18000
	s_add_i32 s63, 0, 0x1c000
	v_add_u32_e32 v140, s62, v187
	v_add_u32_e32 v156, s63, v187
	ds_read_b128 v[128:131], v140
	ds_read_b128 v[132:135], v140 offset:1024
	ds_read_b128 v[136:139], v140 offset:2048
	ds_read_b128 v[140:143], v140 offset:3072
	ds_read_b128 v[144:147], v156
	ds_read_b128 v[148:151], v156 offset:1024
	ds_read_b128 v[152:155], v156 offset:2048
	ds_read_b128 v[156:159], v156 offset:3072
	s_add_u32 s36, s36, 0x200000
	s_addc_u32 s37, s37, 0
	s_mov_b32 m0, s41
	ds_read_b128 v[176:179], v191 offset:32768
	ds_read_b128 v[180:183], v191 offset:33792
	ds_read_b128 v[192:195], v191 offset:34816
	ds_read_b128 v[196:199], v191 offset:35840
	ds_read_b128 v[200:203], v191 offset:36864
	ds_read_b128 v[208:211], v191 offset:37888
	ds_read_b128 v[212:215], v191 offset:38912
	ds_read_b128 v[216:219], v191 offset:39936
	global_load_lds_dwordx4 v160, s[36:37]
	s_mov_b32 m0, s42
	s_nop 0
	global_load_lds_dwordx4 v164, s[36:37]
	s_waitcnt vmcnt(8)
	s_waitcnt lgkmcnt(0)
	v_mfma_f32_16x16x32_f16 v[120:123], v[136:139], v[176:179], v[120:123]
	v_mfma_f32_16x16x32_f16 v[124:127], v[128:131], v[176:179], v[124:127]
	v_mfma_f32_16x16x32_f16 v[104:107], v[136:139], v[192:195], v[104:107]
	v_mfma_f32_16x16x32_f16 v[108:111], v[128:131], v[192:195], v[108:111]
	s_barrier
	s_waitcnt lgkmcnt(0)
	v_mfma_f32_16x16x32_f16 v[88:91], v[136:139], v[200:203], v[88:91]
	v_mfma_f32_16x16x32_f16 v[92:95], v[128:131], v[200:203], v[92:95]
	v_mfma_f32_16x16x32_f16 v[72:75], v[136:139], v[212:215], v[72:75]
	v_mfma_f32_16x16x32_f16 v[76:79], v[128:131], v[212:215], v[76:79]
	v_mfma_f32_16x16x32_f16 v[120:123], v[140:143], v[180:183], v[120:123]
	v_mfma_f32_16x16x32_f16 v[124:127], v[132:135], v[180:183], v[124:127]
	v_mfma_f32_16x16x32_f16 v[104:107], v[140:143], v[196:199], v[104:107]
	v_mfma_f32_16x16x32_f16 v[108:111], v[132:135], v[196:199], v[108:111]
	v_mfma_f32_16x16x32_f16 v[88:91], v[140:143], v[208:211], v[88:91]
	v_mfma_f32_16x16x32_f16 v[92:95], v[132:135], v[208:211], v[92:95]
	v_mfma_f32_16x16x32_f16 v[72:75], v[140:143], v[216:219], v[72:75]
	v_mfma_f32_16x16x32_f16 v[76:79], v[132:135], v[216:219], v[76:79]
	v_mfma_f32_16x16x32_f16 v[112:115], v[152:155], v[176:179], v[112:115]
	v_mfma_f32_16x16x32_f16 v[116:119], v[144:147], v[176:179], v[116:119]
	v_mfma_f32_16x16x32_f16 v[96:99], v[152:155], v[192:195], v[96:99]
	v_mfma_f32_16x16x32_f16 v[100:103], v[144:147], v[192:195], v[100:103]
	v_mfma_f32_16x16x32_f16 v[80:83], v[152:155], v[200:203], v[80:83]
	v_mfma_f32_16x16x32_f16 v[84:87], v[144:147], v[200:203], v[84:87]
	v_mfma_f32_16x16x32_f16 v[64:67], v[152:155], v[212:215], v[64:67]
	v_mfma_f32_16x16x32_f16 v[68:71], v[144:147], v[212:215], v[68:71]
	v_mfma_f32_16x16x32_f16 v[112:115], v[156:159], v[180:183], v[112:115]
	v_mfma_f32_16x16x32_f16 v[116:119], v[148:151], v[180:183], v[116:119]
	v_mfma_f32_16x16x32_f16 v[96:99], v[156:159], v[196:199], v[96:99]
	v_mfma_f32_16x16x32_f16 v[100:103], v[148:151], v[196:199], v[100:103]
	v_mfma_f32_16x16x32_f16 v[80:83], v[156:159], v[208:211], v[80:83]
	v_mfma_f32_16x16x32_f16 v[84:87], v[148:151], v[208:211], v[84:87]
	v_mfma_f32_16x16x32_f16 v[64:67], v[156:159], v[216:219], v[64:67]
	v_mfma_f32_16x16x32_f16 v[68:71], v[148:151], v[216:219], v[68:71]
	s_barrier
	s_add_i32 s36, s62, s39
	s_mov_b32 m0, s36
	ds_read_b128 v[176:179], v191 offset:49152
	ds_read_b128 v[180:183], v191 offset:50176
	ds_read_b128 v[192:195], v191 offset:51200
	ds_read_b128 v[196:199], v191 offset:52224
	ds_read_b128 v[200:203], v191 offset:53248
	ds_read_b128 v[208:211], v191 offset:54272
	ds_read_b128 v[212:215], v191 offset:55296
	ds_read_b128 v[216:219], v191 offset:56320
	global_load_lds_dwordx4 v162, s[98:99]
	s_add_i32 m0, s36, 0x2000
	s_add_u32 s34, s34, 0x200080
	s_addc_u32 s35, s35, 0
	s_add_i32 s36, s63, s39
	global_load_lds_dwordx4 v166, s[98:99]
	s_mov_b32 m0, s36
	s_nop 0
	global_load_lds_dwordx4 v162, s[34:35]
	s_add_i32 m0, s36, 0x2000
	s_nop 0
	global_load_lds_dwordx4 v166, s[34:35]
	s_mov_b32 m0, s44
	s_nop 0
	global_load_lds_dwordx4 v160, s[100:101]
	s_mov_b32 m0, s45
	s_nop 0
	global_load_lds_dwordx4 v164, s[100:101]
	s_waitcnt vmcnt(8)
	s_waitcnt lgkmcnt(0)
	v_mfma_f32_16x16x32_f16 v[56:59], v[136:139], v[176:179], v[56:59]
	v_mfma_f32_16x16x32_f16 v[60:63], v[128:131], v[176:179], v[60:63]
	v_mfma_f32_16x16x32_f16 v[40:43], v[136:139], v[192:195], v[40:43]
	v_mfma_f32_16x16x32_f16 v[44:47], v[128:131], v[192:195], v[44:47]
	s_barrier
	s_waitcnt lgkmcnt(0)
	v_mfma_f32_16x16x32_f16 v[24:27], v[136:139], v[200:203], v[24:27]
	v_mfma_f32_16x16x32_f16 v[28:31], v[128:131], v[200:203], v[28:31]
	v_mfma_f32_16x16x32_f16 v[8:11], v[136:139], v[212:215], v[8:11]
	v_mfma_f32_16x16x32_f16 v[12:15], v[128:131], v[212:215], v[12:15]
	v_mfma_f32_16x16x32_f16 v[56:59], v[140:143], v[180:183], v[56:59]
	v_mfma_f32_16x16x32_f16 v[60:63], v[132:135], v[180:183], v[60:63]
	v_mfma_f32_16x16x32_f16 v[40:43], v[140:143], v[196:199], v[40:43]
	v_mfma_f32_16x16x32_f16 v[44:47], v[132:135], v[196:199], v[44:47]
	v_mfma_f32_16x16x32_f16 v[24:27], v[140:143], v[208:211], v[24:27]
	v_mfma_f32_16x16x32_f16 v[28:31], v[132:135], v[208:211], v[28:31]
	v_mfma_f32_16x16x32_f16 v[8:11], v[140:143], v[216:219], v[8:11]
	v_mfma_f32_16x16x32_f16 v[12:15], v[132:135], v[216:219], v[12:15]
	v_mfma_f32_16x16x32_f16 v[48:51], v[152:155], v[176:179], v[48:51]
	v_mfma_f32_16x16x32_f16 v[52:55], v[144:147], v[176:179], v[52:55]
	v_mfma_f32_16x16x32_f16 v[32:35], v[152:155], v[192:195], v[32:35]
	v_mfma_f32_16x16x32_f16 v[36:39], v[144:147], v[192:195], v[36:39]
	v_mfma_f32_16x16x32_f16 v[16:19], v[152:155], v[200:203], v[16:19]
	v_mfma_f32_16x16x32_f16 v[20:23], v[144:147], v[200:203], v[20:23]
	v_mfma_f32_16x16x32_f16 v[0:3], v[152:155], v[212:215], v[0:3]
	v_mfma_f32_16x16x32_f16 v[4:7], v[144:147], v[212:215], v[4:7]
	v_mfma_f32_16x16x32_f16 v[48:51], v[156:159], v[180:183], v[48:51]
	v_mfma_f32_16x16x32_f16 v[52:55], v[148:151], v[180:183], v[52:55]
	v_mfma_f32_16x16x32_f16 v[32:35], v[156:159], v[196:199], v[32:35]
	v_mfma_f32_16x16x32_f16 v[36:39], v[148:151], v[196:199], v[36:39]
	v_mfma_f32_16x16x32_f16 v[16:19], v[156:159], v[208:211], v[16:19]
	v_mfma_f32_16x16x32_f16 v[20:23], v[148:151], v[208:211], v[20:23]
	v_mfma_f32_16x16x32_f16 v[0:3], v[156:159], v[216:219], v[0:3]
	v_mfma_f32_16x16x32_f16 v[4:7], v[148:151], v[216:219], v[4:7]
	s_barrier
	s_add_i32 s61, s61, 2
	s_add_u32 s53, s53, 0x100
	s_addc_u32 s60, s60, 0
	s_add_u32 s30, s30, 0x100
	s_addc_u32 s31, s31, 0
	s_cmpk_gt_u32 s61, 0x7d
	s_cbranch_scc0 .LBB0_1243
	s_and_b64 vcc, exec, s[14:15]
	s_cbranch_vccz .LBB0_1246
	s_barrier
